# final: baseline device code + compute-dtype comment line (no ISA change kept; explored epilogue load hoisting, XCD stagger, setprio edits - none gave robust gain)
# speedup vs baseline: 1.0047x; 1.0047x over previous
.LBB0_284:
	ds_read_b128 v[58:61], v171
	ds_read_b128 v[62:65], v171 offset:1024
	ds_read_b128 v[74:77], v171 offset:2048
	ds_read_b128 v[78:81], v171 offset:3072
	ds_read_b128 v[176:179], v172
	ds_read_b128 v[180:183], v172 offset:1024
	ds_read_b128 v[184:187], v172 offset:2048
	ds_read_b128 v[188:191], v172 offset:3072
	s_add_u32 s4, s42, 0xfff80080
	s_addc_u32 s5, s43, -1
	s_cmp_eq_u32 s77, 28
	s_cselect_b32 s51, s11, s5
	s_cselect_b32 s50, s31, s4
	s_cselect_b32 s5, s29, s76
	s_cselect_b32 s4, s39, s75
	v_lshl_add_u64 v[164:165], s[42:43], 0, v[156:157]
	s_add_i32 m0, s33, 0xc000
	ds_read_b128 v[192:195], v173
	ds_read_b128 v[196:199], v173 offset:1024
	ds_read_b128 v[200:203], v173 offset:2048
	ds_read_b128 v[204:207], v173 offset:3072
	ds_read_b128 v[208:211], v173 offset:4096
	ds_read_b128 v[212:215], v173 offset:5120
	ds_read_b128 v[216:219], v173 offset:6144
	ds_read_b128 v[220:223], v173 offset:7168
	global_load_lds_dwordx4 v[164:165], off
	v_lshl_add_u64 v[164:165], s[42:43], 0, v[158:159]
	s_add_i32 m0, s33, 0xe000
	s_nop 0
	global_load_lds_dwordx4 v[164:165], off
	s_waitcnt vmcnt(8)
	s_waitcnt lgkmcnt(0)
	s_barrier
	s_setprio 1
	s_waitcnt lgkmcnt(0)
	v_mfma_f32_16x16x32_bf16 v[142:145], v[58:61], v[192:195], v[142:145]
	v_mfma_f32_16x16x32_bf16 v[138:141], v[74:77], v[192:195], v[138:141]
	v_mfma_f32_16x16x32_bf16 v[126:129], v[58:61], v[200:203], v[126:129]
	v_mfma_f32_16x16x32_bf16 v[122:125], v[74:77], v[200:203], v[122:125]
	v_mfma_f32_16x16x32_bf16 v[110:113], v[58:61], v[208:211], v[110:113]
	v_mfma_f32_16x16x32_bf16 v[106:109], v[74:77], v[208:211], v[106:109]
	v_mfma_f32_16x16x32_bf16 v[94:97], v[58:61], v[216:219], v[94:97]
	v_mfma_f32_16x16x32_bf16 v[90:93], v[74:77], v[216:219], v[90:93]
	v_mfma_f32_16x16x32_bf16 v[142:145], v[62:65], v[196:199], v[142:145]
	v_mfma_f32_16x16x32_bf16 v[138:141], v[78:81], v[196:199], v[138:141]
	v_mfma_f32_16x16x32_bf16 v[126:129], v[62:65], v[204:207], v[126:129]
	v_mfma_f32_16x16x32_bf16 v[122:125], v[78:81], v[204:207], v[122:125]
	v_mfma_f32_16x16x32_bf16 v[110:113], v[62:65], v[212:215], v[110:113]
	v_mfma_f32_16x16x32_bf16 v[106:109], v[78:81], v[212:215], v[106:109]
	v_mfma_f32_16x16x32_bf16 v[94:97], v[62:65], v[220:223], v[94:97]
	v_mfma_f32_16x16x32_bf16 v[90:93], v[78:81], v[220:223], v[90:93]
	s_setprio 0
	s_setprio 1
	v_mfma_f32_16x16x32_bf16 v[134:137], v[176:179], v[192:195], v[134:137]
	v_mfma_f32_16x16x32_bf16 v[130:133], v[184:187], v[192:195], v[130:133]
	v_mfma_f32_16x16x32_bf16 v[118:121], v[176:179], v[200:203], v[118:121]
	v_mfma_f32_16x16x32_bf16 v[114:117], v[184:187], v[200:203], v[114:117]
	v_mfma_f32_16x16x32_bf16 v[102:105], v[176:179], v[208:211], v[102:105]
	v_mfma_f32_16x16x32_bf16 v[98:101], v[184:187], v[208:211], v[98:101]
	v_mfma_f32_16x16x32_bf16 v[86:89], v[176:179], v[216:219], v[86:89]
	v_mfma_f32_16x16x32_bf16 v[82:85], v[184:187], v[216:219], v[82:85]
	v_mfma_f32_16x16x32_bf16 v[134:137], v[180:183], v[196:199], v[134:137]
	v_mfma_f32_16x16x32_bf16 v[130:133], v[188:191], v[196:199], v[130:133]
	v_mfma_f32_16x16x32_bf16 v[118:121], v[180:183], v[204:207], v[118:121]
	v_mfma_f32_16x16x32_bf16 v[114:117], v[188:191], v[204:207], v[114:117]
	v_mfma_f32_16x16x32_bf16 v[102:105], v[180:183], v[212:215], v[102:105]
	v_mfma_f32_16x16x32_bf16 v[98:101], v[188:191], v[212:215], v[98:101]
	v_mfma_f32_16x16x32_bf16 v[86:89], v[180:183], v[220:223], v[86:89]
	v_mfma_f32_16x16x32_bf16 v[82:85], v[188:191], v[220:223], v[82:85]
	s_setprio 0
	s_barrier
	s_add_i32 s78, s72, s27
	v_lshl_add_u64 v[164:165], s[4:5], 0, v[148:149]
	s_mov_b32 m0, s78
	ds_read_b128 v[192:195], v173 offset:16384
	ds_read_b128 v[196:199], v173 offset:17408
	ds_read_b128 v[200:203], v173 offset:18432
	ds_read_b128 v[204:207], v173 offset:19456
	ds_read_b128 v[208:211], v173 offset:20480
	ds_read_b128 v[212:215], v173 offset:21504
	ds_read_b128 v[216:219], v173 offset:22528
	ds_read_b128 v[220:223], v173 offset:23552
	global_load_lds_dwordx4 v[164:165], off
	s_add_i32 m0, s78, 0x2000
	s_add_u32 s78, s4, 0x80000
	v_lshl_add_u64 v[168:169], s[4:5], 0, v[152:153]
	s_addc_u32 s79, s5, 0
	s_add_i32 s80, s73, s27
	global_load_lds_dwordx4 v[168:169], off
	v_lshl_add_u64 v[224:225], s[78:79], 0, v[148:149]
	s_mov_b32 m0, s80
	v_lshl_add_u64 v[226:227], s[50:51], 0, v[150:151]
	global_load_lds_dwordx4 v[224:225], off
	v_lshl_add_u64 v[224:225], s[78:79], 0, v[152:153]
	s_add_i32 m0, s80, 0x2000
	s_nop 0
	global_load_lds_dwordx4 v[224:225], off
	v_lshl_add_u64 v[224:225], s[50:51], 0, v[146:147]
	s_mov_b32 m0, s33
	s_nop 0
	global_load_lds_dwordx4 v[224:225], off
	s_mov_b32 m0, s52
	s_nop 0
	global_load_lds_dwordx4 v[226:227], off
	s_waitcnt vmcnt(8)
	s_waitcnt lgkmcnt(0)
	s_barrier
	s_setprio 1
	s_waitcnt lgkmcnt(0)
	v_mfma_f32_16x16x32_bf16 v[70:73], v[58:61], v[192:195], v[70:73]
	v_mfma_f32_16x16x32_bf16 v[66:69], v[74:77], v[192:195], v[66:69]
	v_mfma_f32_16x16x32_bf16 v[46:49], v[58:61], v[200:203], v[46:49]
	v_mfma_f32_16x16x32_bf16 v[42:45], v[74:77], v[200:203], v[42:45]
	v_mfma_f32_16x16x32_bf16 v[30:33], v[58:61], v[208:211], v[30:33]
	v_mfma_f32_16x16x32_bf16 v[26:29], v[74:77], v[208:211], v[26:29]
	v_mfma_f32_16x16x32_bf16 v[14:17], v[58:61], v[216:219], v[14:17]
	v_mfma_f32_16x16x32_bf16 v[10:13], v[74:77], v[216:219], v[10:13]
	v_mfma_f32_16x16x32_bf16 v[70:73], v[62:65], v[196:199], v[70:73]
	v_mfma_f32_16x16x32_bf16 v[66:69], v[78:81], v[196:199], v[66:69]
	v_mfma_f32_16x16x32_bf16 v[46:49], v[62:65], v[204:207], v[46:49]
	v_mfma_f32_16x16x32_bf16 v[42:45], v[78:81], v[204:207], v[42:45]
	v_mfma_f32_16x16x32_bf16 v[30:33], v[62:65], v[212:215], v[30:33]
	v_mfma_f32_16x16x32_bf16 v[26:29], v[78:81], v[212:215], v[26:29]
	v_mfma_f32_16x16x32_bf16 v[14:17], v[62:65], v[220:223], v[14:17]
	v_mfma_f32_16x16x32_bf16 v[10:13], v[78:81], v[220:223], v[10:13]
	s_setprio 0
	s_setprio 1
	v_mfma_f32_16x16x32_bf16 v[54:57], v[176:179], v[192:195], v[54:57]
	v_mfma_f32_16x16x32_bf16 v[50:53], v[184:187], v[192:195], v[50:53]
	v_mfma_f32_16x16x32_bf16 v[38:41], v[176:179], v[200:203], v[38:41]
	v_mfma_f32_16x16x32_bf16 v[34:37], v[184:187], v[200:203], v[34:37]
	v_mfma_f32_16x16x32_bf16 v[22:25], v[176:179], v[208:211], v[22:25]
	v_mfma_f32_16x16x32_bf16 v[18:21], v[184:187], v[208:211], v[18:21]
	v_mfma_f32_16x16x32_bf16 v[6:9], v[176:179], v[216:219], v[6:9]
	v_mfma_f32_16x16x32_bf16 v[2:5], v[184:187], v[216:219], v[2:5]
	v_mfma_f32_16x16x32_bf16 v[54:57], v[180:183], v[196:199], v[54:57]
	v_mfma_f32_16x16x32_bf16 v[50:53], v[188:191], v[196:199], v[50:53]
	v_mfma_f32_16x16x32_bf16 v[38:41], v[180:183], v[204:207], v[38:41]
	v_mfma_f32_16x16x32_bf16 v[34:37], v[188:191], v[204:207], v[34:37]
	v_mfma_f32_16x16x32_bf16 v[22:25], v[180:183], v[212:215], v[22:25]
	v_mfma_f32_16x16x32_bf16 v[18:21], v[188:191], v[212:215], v[18:21]
	v_mfma_f32_16x16x32_bf16 v[6:9], v[180:183], v[220:223], v[6:9]
	v_mfma_f32_16x16x32_bf16 v[2:5], v[188:191], v[220:223], v[2:5]
	s_setprio 0
	s_barrier
	s_add_i32 s78, 0, 0x18000
	s_add_i32 s79, 0, 0x1c000
	v_add_u32_e32 v78, s78, v167
	v_add_u32_e32 v155, s79, v167
	ds_read_b128 v[58:61], v78
	ds_read_b128 v[62:65], v78 offset:1024
	ds_read_b128 v[74:77], v78 offset:2048
	ds_read_b128 v[78:81], v78 offset:3072
	ds_read_b128 v[176:179], v155
	ds_read_b128 v[180:183], v155 offset:1024
	ds_read_b128 v[184:187], v155 offset:2048
	ds_read_b128 v[188:191], v155 offset:3072
	s_add_u32 s50, s50, 0x80000
	s_addc_u32 s51, s51, 0
	s_mov_b32 m0, s53
	v_lshl_add_u64 v[228:229], s[50:51], 0, v[146:147]
	ds_read_b128 v[192:195], v173 offset:32768
	ds_read_b128 v[196:199], v173 offset:33792
	ds_read_b128 v[200:203], v173 offset:34816
	ds_read_b128 v[204:207], v173 offset:35840
	ds_read_b128 v[208:211], v173 offset:36864
	ds_read_b128 v[212:215], v173 offset:37888
	ds_read_b128 v[216:219], v173 offset:38912
	ds_read_b128 v[220:223], v173 offset:39936
	global_load_lds_dwordx4 v[228:229], off
	v_lshl_add_u64 v[228:229], s[50:51], 0, v[150:151]
	s_mov_b32 m0, s54
	s_nop 0
	global_load_lds_dwordx4 v[228:229], off
	s_waitcnt vmcnt(8)
	s_waitcnt lgkmcnt(0)
	s_barrier
	s_setprio 1
	s_waitcnt lgkmcnt(0)
	v_mfma_f32_16x16x32_bf16 v[142:145], v[58:61], v[192:195], v[142:145]
	v_mfma_f32_16x16x32_bf16 v[138:141], v[74:77], v[192:195], v[138:141]
	v_mfma_f32_16x16x32_bf16 v[126:129], v[58:61], v[200:203], v[126:129]
	v_mfma_f32_16x16x32_bf16 v[122:125], v[74:77], v[200:203], v[122:125]
	v_mfma_f32_16x16x32_bf16 v[110:113], v[58:61], v[208:211], v[110:113]
	v_mfma_f32_16x16x32_bf16 v[106:109], v[74:77], v[208:211], v[106:109]
	v_mfma_f32_16x16x32_bf16 v[94:97], v[58:61], v[216:219], v[94:97]
	v_mfma_f32_16x16x32_bf16 v[90:93], v[74:77], v[216:219], v[90:93]
	v_mfma_f32_16x16x32_bf16 v[142:145], v[62:65], v[196:199], v[142:145]
	v_mfma_f32_16x16x32_bf16 v[138:141], v[78:81], v[196:199], v[138:141]
	v_mfma_f32_16x16x32_bf16 v[126:129], v[62:65], v[204:207], v[126:129]
	v_mfma_f32_16x16x32_bf16 v[122:125], v[78:81], v[204:207], v[122:125]
	v_mfma_f32_16x16x32_bf16 v[110:113], v[62:65], v[212:215], v[110:113]
	v_mfma_f32_16x16x32_bf16 v[106:109], v[78:81], v[212:215], v[106:109]
	v_mfma_f32_16x16x32_bf16 v[94:97], v[62:65], v[220:223], v[94:97]
	v_mfma_f32_16x16x32_bf16 v[90:93], v[78:81], v[220:223], v[90:93]
	s_setprio 0
	s_setprio 1
	v_mfma_f32_16x16x32_bf16 v[134:137], v[176:179], v[192:195], v[134:137]
	v_mfma_f32_16x16x32_bf16 v[130:133], v[184:187], v[192:195], v[130:133]
	v_mfma_f32_16x16x32_bf16 v[118:121], v[176:179], v[200:203], v[118:121]
	v_mfma_f32_16x16x32_bf16 v[114:117], v[184:187], v[200:203], v[114:117]
	v_mfma_f32_16x16x32_bf16 v[102:105], v[176:179], v[208:211], v[102:105]
	v_mfma_f32_16x16x32_bf16 v[98:101], v[184:187], v[208:211], v[98:101]
	v_mfma_f32_16x16x32_bf16 v[86:89], v[176:179], v[216:219], v[86:89]
	v_mfma_f32_16x16x32_bf16 v[82:85], v[184:187], v[216:219], v[82:85]
	v_mfma_f32_16x16x32_bf16 v[134:137], v[180:183], v[196:199], v[134:137]
	v_mfma_f32_16x16x32_bf16 v[130:133], v[188:191], v[196:199], v[130:133]
	v_mfma_f32_16x16x32_bf16 v[118:121], v[180:183], v[204:207], v[118:121]
	v_mfma_f32_16x16x32_bf16 v[114:117], v[188:191], v[204:207], v[114:117]
	v_mfma_f32_16x16x32_bf16 v[102:105], v[180:183], v[212:215], v[102:105]
	v_mfma_f32_16x16x32_bf16 v[98:101], v[188:191], v[212:215], v[98:101]
	v_mfma_f32_16x16x32_bf16 v[86:89], v[180:183], v[220:223], v[86:89]
	v_mfma_f32_16x16x32_bf16 v[82:85], v[188:191], v[220:223], v[82:85]
	s_setprio 0
	s_barrier
	s_add_i32 s50, s78, s27
	v_lshl_add_u64 v[164:165], v[164:165], 0, s[20:21]
	s_mov_b32 m0, s50
	ds_read_b128 v[192:195], v173 offset:49152
	ds_read_b128 v[196:199], v173 offset:50176
	ds_read_b128 v[200:203], v173 offset:51200
	ds_read_b128 v[204:207], v173 offset:52224
	ds_read_b128 v[208:211], v173 offset:53248
	ds_read_b128 v[212:215], v173 offset:54272
	ds_read_b128 v[216:219], v173 offset:55296
	ds_read_b128 v[220:223], v173 offset:56320
	global_load_lds_dwordx4 v[164:165], off
	s_add_i32 m0, s50, 0x2000
	s_add_u32 s4, s4, 0x80080
	v_lshl_add_u64 v[164:165], v[168:169], 0, s[20:21]
	s_addc_u32 s5, s5, 0
	s_add_i32 s50, s79, s27
	global_load_lds_dwordx4 v[164:165], off
	v_lshl_add_u64 v[164:165], s[4:5], 0, v[148:149]
	s_mov_b32 m0, s50
	s_nop 0
	global_load_lds_dwordx4 v[164:165], off
	v_lshl_add_u64 v[164:165], s[4:5], 0, v[152:153]
	s_add_i32 m0, s50, 0x2000
	s_nop 0
	global_load_lds_dwordx4 v[164:165], off
	v_lshl_add_u64 v[164:165], v[224:225], 0, s[20:21]
	s_mov_b32 m0, s63
	s_nop 0
	global_load_lds_dwordx4 v[164:165], off
	v_lshl_add_u64 v[164:165], v[226:227], 0, s[20:21]
	s_mov_b32 m0, s66
	s_nop 0
	global_load_lds_dwordx4 v[164:165], off
	s_waitcnt vmcnt(8)
	s_waitcnt lgkmcnt(0)
	s_barrier
	s_setprio 1
	s_waitcnt lgkmcnt(0)
	v_mfma_f32_16x16x32_bf16 v[70:73], v[58:61], v[192:195], v[70:73]
	v_mfma_f32_16x16x32_bf16 v[66:69], v[74:77], v[192:195], v[66:69]
	v_mfma_f32_16x16x32_bf16 v[46:49], v[58:61], v[200:203], v[46:49]
	v_mfma_f32_16x16x32_bf16 v[42:45], v[74:77], v[200:203], v[42:45]
	v_mfma_f32_16x16x32_bf16 v[30:33], v[58:61], v[208:211], v[30:33]
	v_mfma_f32_16x16x32_bf16 v[26:29], v[74:77], v[208:211], v[26:29]
	v_mfma_f32_16x16x32_bf16 v[14:17], v[58:61], v[216:219], v[14:17]
	v_mfma_f32_16x16x32_bf16 v[10:13], v[74:77], v[216:219], v[10:13]
	v_mfma_f32_16x16x32_bf16 v[70:73], v[62:65], v[196:199], v[70:73]
	v_mfma_f32_16x16x32_bf16 v[66:69], v[78:81], v[196:199], v[66:69]
	v_mfma_f32_16x16x32_bf16 v[46:49], v[62:65], v[204:207], v[46:49]
	v_mfma_f32_16x16x32_bf16 v[42:45], v[78:81], v[204:207], v[42:45]
	v_mfma_f32_16x16x32_bf16 v[30:33], v[62:65], v[212:215], v[30:33]
	v_mfma_f32_16x16x32_bf16 v[26:29], v[78:81], v[212:215], v[26:29]
	v_mfma_f32_16x16x32_bf16 v[14:17], v[62:65], v[220:223], v[14:17]
	v_mfma_f32_16x16x32_bf16 v[10:13], v[78:81], v[220:223], v[10:13]
	s_setprio 0
	s_setprio 1
	v_mfma_f32_16x16x32_bf16 v[54:57], v[176:179], v[192:195], v[54:57]
	v_mfma_f32_16x16x32_bf16 v[50:53], v[184:187], v[192:195], v[50:53]
	v_mfma_f32_16x16x32_bf16 v[38:41], v[176:179], v[200:203], v[38:41]
	v_mfma_f32_16x16x32_bf16 v[34:37], v[184:187], v[200:203], v[34:37]
	v_mfma_f32_16x16x32_bf16 v[22:25], v[176:179], v[208:211], v[22:25]
	v_mfma_f32_16x16x32_bf16 v[18:21], v[184:187], v[208:211], v[18:21]
	v_mfma_f32_16x16x32_bf16 v[6:9], v[176:179], v[216:219], v[6:9]
	v_mfma_f32_16x16x32_bf16 v[2:5], v[184:187], v[216:219], v[2:5]
	v_mfma_f32_16x16x32_bf16 v[54:57], v[180:183], v[196:199], v[54:57]
	v_mfma_f32_16x16x32_bf16 v[50:53], v[188:191], v[196:199], v[50:53]
	v_mfma_f32_16x16x32_bf16 v[38:41], v[180:183], v[204:207], v[38:41]
	v_mfma_f32_16x16x32_bf16 v[34:37], v[188:191], v[204:207], v[34:37]
	v_mfma_f32_16x16x32_bf16 v[22:25], v[180:183], v[212:215], v[22:25]
	v_mfma_f32_16x16x32_bf16 v[18:21], v[188:191], v[212:215], v[18:21]
	v_mfma_f32_16x16x32_bf16 v[6:9], v[180:183], v[220:223], v[6:9]
	v_mfma_f32_16x16x32_bf16 v[2:5], v[188:191], v[220:223], v[2:5]
	s_setprio 0
	s_barrier
	s_add_i32 s77, s77, 2
	s_add_u32 s42, s42, 0x100
	s_addc_u32 s43, s43, 0
	s_add_u32 s75, s75, 0x100
	s_addc_u32 s76, s76, 0
	s_cmp_gt_u32 s77, 29
	s_cbranch_scc0 .LBB0_284
	s_and_b64 vcc, exec, s[22:23]
	s_cbranch_vccz .LBB0_287
	s_barrier

.LBB0_459:
	ds_read_b128 v[130:133], v233
	ds_read_b128 v[134:137], v233 offset:1024
	ds_read_b128 v[138:141], v233 offset:2048
	ds_read_b128 v[142:145], v233 offset:3072
	ds_read_b128 v[146:149], v234
	ds_read_b128 v[150:153], v234 offset:1024
	ds_read_b128 v[172:175], v234 offset:2048
	ds_read_b128 v[176:179], v234 offset:3072
	s_add_u32 s4, s52, 0xffe00080
	s_addc_u32 s5, s53, -1
	s_cmp_eq_u32 s79, 60
	s_cselect_b32 s55, s11, s5
	s_cselect_b32 s54, s37, s4
	s_cselect_b32 s5, s35, s78
	s_cselect_b32 s4, s76, s77
	v_lshl_add_u64 v[212:213], s[52:53], 0, v[162:163]
	s_add_i32 m0, s51, 0xc000
	ds_read_b128 v[180:183], v235
	ds_read_b128 v[184:187], v235 offset:1024
	ds_read_b128 v[188:191], v235 offset:2048
	ds_read_b128 v[192:195], v235 offset:3072
	ds_read_b128 v[196:199], v235 offset:4096
	ds_read_b128 v[200:203], v235 offset:5120
	ds_read_b128 v[204:207], v235 offset:6144
	ds_read_b128 v[208:211], v235 offset:7168
	global_load_lds_dwordx4 v[212:213], off
	v_lshl_add_u64 v[212:213], s[52:53], 0, v[164:165]
	s_add_i32 m0, s51, 0xe000
	s_nop 0
	global_load_lds_dwordx4 v[212:213], off
	s_waitcnt vmcnt(8)
	s_waitcnt lgkmcnt(0)
	s_barrier
	s_setprio 1
	s_waitcnt lgkmcnt(0)
	v_mfma_f32_16x16x32_bf16 v[118:121], v[130:133], v[180:183], v[118:121]
	v_mfma_f32_16x16x32_bf16 v[114:117], v[138:141], v[180:183], v[114:117]
	v_mfma_f32_16x16x32_bf16 v[106:109], v[130:133], v[188:191], v[106:109]
	v_mfma_f32_16x16x32_bf16 v[102:105], v[138:141], v[188:191], v[102:105]
	v_mfma_f32_16x16x32_bf16 v[126:129], v[130:133], v[196:199], v[126:129]
	v_mfma_f32_16x16x32_bf16 v[122:125], v[138:141], v[196:199], v[122:125]
	v_mfma_f32_16x16x32_bf16 v[110:113], v[130:133], v[204:207], v[110:113]
	v_mfma_f32_16x16x32_bf16 v[98:101], v[138:141], v[204:207], v[98:101]
	v_mfma_f32_16x16x32_bf16 v[118:121], v[134:137], v[184:187], v[118:121]
	v_mfma_f32_16x16x32_bf16 v[114:117], v[142:145], v[184:187], v[114:117]
	v_mfma_f32_16x16x32_bf16 v[106:109], v[134:137], v[192:195], v[106:109]
	v_mfma_f32_16x16x32_bf16 v[102:105], v[142:145], v[192:195], v[102:105]
	v_mfma_f32_16x16x32_bf16 v[126:129], v[134:137], v[200:203], v[126:129]
	v_mfma_f32_16x16x32_bf16 v[122:125], v[142:145], v[200:203], v[122:125]
	v_mfma_f32_16x16x32_bf16 v[110:113], v[134:137], v[208:211], v[110:113]
	v_mfma_f32_16x16x32_bf16 v[98:101], v[142:145], v[208:211], v[98:101]
	s_setprio 0
	s_setprio 1
	v_mfma_f32_16x16x32_bf16 v[62:65], v[146:149], v[180:183], v[62:65]
	v_mfma_f32_16x16x32_bf16 v[58:61], v[172:175], v[180:183], v[58:61]
	v_mfma_f32_16x16x32_bf16 v[54:57], v[146:149], v[188:191], v[54:57]
	v_mfma_f32_16x16x32_bf16 v[50:53], v[172:175], v[188:191], v[50:53]
	v_mfma_f32_16x16x32_bf16 v[46:49], v[146:149], v[196:199], v[46:49]
	v_mfma_f32_16x16x32_bf16 v[42:45], v[172:175], v[196:199], v[42:45]
	v_mfma_f32_16x16x32_bf16 v[38:41], v[146:149], v[204:207], v[38:41]
	v_mfma_f32_16x16x32_bf16 v[34:37], v[172:175], v[204:207], v[34:37]
	v_mfma_f32_16x16x32_bf16 v[62:65], v[150:153], v[184:187], v[62:65]
	v_mfma_f32_16x16x32_bf16 v[58:61], v[176:179], v[184:187], v[58:61]
	v_mfma_f32_16x16x32_bf16 v[54:57], v[150:153], v[192:195], v[54:57]
	v_mfma_f32_16x16x32_bf16 v[50:53], v[176:179], v[192:195], v[50:53]
	v_mfma_f32_16x16x32_bf16 v[46:49], v[150:153], v[200:203], v[46:49]
	v_mfma_f32_16x16x32_bf16 v[42:45], v[176:179], v[200:203], v[42:45]
	v_mfma_f32_16x16x32_bf16 v[38:41], v[150:153], v[208:211], v[38:41]
	v_mfma_f32_16x16x32_bf16 v[34:37], v[176:179], v[208:211], v[34:37]
	s_setprio 0
	s_barrier
	s_add_i32 s80, s74, s56
	v_lshl_add_u64 v[212:213], s[4:5], 0, v[156:157]
	s_mov_b32 m0, s80
	ds_read_b128 v[180:183], v235 offset:16384
	ds_read_b128 v[184:187], v235 offset:17408
	ds_read_b128 v[188:191], v235 offset:18432
	ds_read_b128 v[192:195], v235 offset:19456
	ds_read_b128 v[196:199], v235 offset:20480
	ds_read_b128 v[200:203], v235 offset:21504
	ds_read_b128 v[204:207], v235 offset:22528
	ds_read_b128 v[208:211], v235 offset:23552
	global_load_lds_dwordx4 v[212:213], off
	s_add_i32 m0, s80, 0x2000
	s_add_u32 s80, s4, 0x100000
	v_lshl_add_u64 v[214:215], s[4:5], 0, v[160:161]
	s_addc_u32 s81, s5, 0
	s_add_i32 s82, s75, s56
	global_load_lds_dwordx4 v[214:215], off
	v_lshl_add_u64 v[216:217], s[80:81], 0, v[156:157]
	s_mov_b32 m0, s82
	v_lshl_add_u64 v[218:219], s[54:55], 0, v[158:159]
	global_load_lds_dwordx4 v[216:217], off
	v_lshl_add_u64 v[216:217], s[80:81], 0, v[160:161]
	s_add_i32 m0, s82, 0x2000
	s_nop 0
	global_load_lds_dwordx4 v[216:217], off
	v_lshl_add_u64 v[216:217], s[54:55], 0, v[154:155]
	s_mov_b32 m0, s51
	s_nop 0
	global_load_lds_dwordx4 v[216:217], off
	s_mov_b32 m0, s57
	s_nop 0
	global_load_lds_dwordx4 v[218:219], off
	s_waitcnt vmcnt(8)
	s_waitcnt lgkmcnt(0)
	s_barrier
	s_setprio 1
	s_waitcnt lgkmcnt(0)
	v_mfma_f32_16x16x32_bf16 v[94:97], v[130:133], v[180:183], v[94:97]
	v_mfma_f32_16x16x32_bf16 v[90:93], v[138:141], v[180:183], v[90:93]
	v_mfma_f32_16x16x32_bf16 v[86:89], v[130:133], v[188:191], v[86:89]
	v_mfma_f32_16x16x32_bf16 v[82:85], v[138:141], v[188:191], v[82:85]
	v_mfma_f32_16x16x32_bf16 v[78:81], v[130:133], v[196:199], v[78:81]
	v_mfma_f32_16x16x32_bf16 v[74:77], v[138:141], v[196:199], v[74:77]
	v_mfma_f32_16x16x32_bf16 v[70:73], v[130:133], v[204:207], v[70:73]
	v_mfma_f32_16x16x32_bf16 v[66:69], v[138:141], v[204:207], v[66:69]
	v_mfma_f32_16x16x32_bf16 v[94:97], v[134:137], v[184:187], v[94:97]
	v_mfma_f32_16x16x32_bf16 v[90:93], v[142:145], v[184:187], v[90:93]
	v_mfma_f32_16x16x32_bf16 v[86:89], v[134:137], v[192:195], v[86:89]
	v_mfma_f32_16x16x32_bf16 v[82:85], v[142:145], v[192:195], v[82:85]
	v_mfma_f32_16x16x32_bf16 v[78:81], v[134:137], v[200:203], v[78:81]
	v_mfma_f32_16x16x32_bf16 v[74:77], v[142:145], v[200:203], v[74:77]
	v_mfma_f32_16x16x32_bf16 v[70:73], v[134:137], v[208:211], v[70:73]
	v_mfma_f32_16x16x32_bf16 v[66:69], v[142:145], v[208:211], v[66:69]
	s_setprio 0
	s_setprio 1
	v_mfma_f32_16x16x32_bf16 v[30:33], v[146:149], v[180:183], v[30:33]
	v_mfma_f32_16x16x32_bf16 v[26:29], v[172:175], v[180:183], v[26:29]
	v_mfma_f32_16x16x32_bf16 v[22:25], v[146:149], v[188:191], v[22:25]
	v_mfma_f32_16x16x32_bf16 v[18:21], v[172:175], v[188:191], v[18:21]
	v_mfma_f32_16x16x32_bf16 v[14:17], v[146:149], v[196:199], v[14:17]
	v_mfma_f32_16x16x32_bf16 v[10:13], v[172:175], v[196:199], v[10:13]
	v_mfma_f32_16x16x32_bf16 v[6:9], v[146:149], v[204:207], v[6:9]
	v_mfma_f32_16x16x32_bf16 v[2:5], v[172:175], v[204:207], v[2:5]
	v_mfma_f32_16x16x32_bf16 v[30:33], v[150:153], v[184:187], v[30:33]
	v_mfma_f32_16x16x32_bf16 v[26:29], v[176:179], v[184:187], v[26:29]
	v_mfma_f32_16x16x32_bf16 v[22:25], v[150:153], v[192:195], v[22:25]
	v_mfma_f32_16x16x32_bf16 v[18:21], v[176:179], v[192:195], v[18:21]
	v_mfma_f32_16x16x32_bf16 v[14:17], v[150:153], v[200:203], v[14:17]
	v_mfma_f32_16x16x32_bf16 v[10:13], v[176:179], v[200:203], v[10:13]
	v_mfma_f32_16x16x32_bf16 v[6:9], v[150:153], v[208:211], v[6:9]
	v_mfma_f32_16x16x32_bf16 v[2:5], v[176:179], v[208:211], v[2:5]
	s_setprio 0
	s_barrier
	s_add_i32 s80, 0, 0x18000
	s_add_i32 s81, 0, 0x1c000
	v_add_u32_e32 v142, s80, v167
	v_add_u32_e32 v176, s81, v167
	ds_read_b128 v[130:133], v142
	ds_read_b128 v[134:137], v142 offset:1024
	ds_read_b128 v[138:141], v142 offset:2048
	ds_read_b128 v[142:145], v142 offset:3072
	ds_read_b128 v[146:149], v176
	ds_read_b128 v[150:153], v176 offset:1024
	ds_read_b128 v[172:175], v176 offset:2048
	ds_read_b128 v[176:179], v176 offset:3072
	s_add_u32 s54, s54, 0x200000
	s_addc_u32 s55, s55, 0
	s_mov_b32 m0, s58
	v_lshl_add_u64 v[220:221], s[54:55], 0, v[154:155]
	ds_read_b128 v[180:183], v235 offset:32768
	ds_read_b128 v[184:187], v235 offset:33792
	ds_read_b128 v[188:191], v235 offset:34816
	ds_read_b128 v[192:195], v235 offset:35840
	ds_read_b128 v[196:199], v235 offset:36864
	ds_read_b128 v[200:203], v235 offset:37888
	ds_read_b128 v[204:207], v235 offset:38912
	ds_read_b128 v[208:211], v235 offset:39936
	global_load_lds_dwordx4 v[220:221], off
	v_lshl_add_u64 v[220:221], s[54:55], 0, v[158:159]
	s_mov_b32 m0, s59
	s_nop 0
	global_load_lds_dwordx4 v[220:221], off
	s_waitcnt vmcnt(8)
	s_waitcnt lgkmcnt(0)
	s_barrier
	s_setprio 1
	s_waitcnt lgkmcnt(0)
	v_mfma_f32_16x16x32_bf16 v[118:121], v[130:133], v[180:183], v[118:121]
	v_mfma_f32_16x16x32_bf16 v[114:117], v[138:141], v[180:183], v[114:117]
	v_mfma_f32_16x16x32_bf16 v[106:109], v[130:133], v[188:191], v[106:109]
	v_mfma_f32_16x16x32_bf16 v[102:105], v[138:141], v[188:191], v[102:105]
	v_mfma_f32_16x16x32_bf16 v[126:129], v[130:133], v[196:199], v[126:129]
	v_mfma_f32_16x16x32_bf16 v[122:125], v[138:141], v[196:199], v[122:125]
	v_mfma_f32_16x16x32_bf16 v[110:113], v[130:133], v[204:207], v[110:113]
	v_mfma_f32_16x16x32_bf16 v[98:101], v[138:141], v[204:207], v[98:101]
	v_mfma_f32_16x16x32_bf16 v[118:121], v[134:137], v[184:187], v[118:121]
	v_mfma_f32_16x16x32_bf16 v[114:117], v[142:145], v[184:187], v[114:117]
	v_mfma_f32_16x16x32_bf16 v[106:109], v[134:137], v[192:195], v[106:109]
	v_mfma_f32_16x16x32_bf16 v[102:105], v[142:145], v[192:195], v[102:105]
	v_mfma_f32_16x16x32_bf16 v[126:129], v[134:137], v[200:203], v[126:129]
	v_mfma_f32_16x16x32_bf16 v[122:125], v[142:145], v[200:203], v[122:125]
	v_mfma_f32_16x16x32_bf16 v[110:113], v[134:137], v[208:211], v[110:113]
	v_mfma_f32_16x16x32_bf16 v[98:101], v[142:145], v[208:211], v[98:101]
	s_setprio 0
	s_setprio 1
	v_mfma_f32_16x16x32_bf16 v[62:65], v[146:149], v[180:183], v[62:65]
	v_mfma_f32_16x16x32_bf16 v[58:61], v[172:175], v[180:183], v[58:61]
	v_mfma_f32_16x16x32_bf16 v[54:57], v[146:149], v[188:191], v[54:57]
	v_mfma_f32_16x16x32_bf16 v[50:53], v[172:175], v[188:191], v[50:53]
	v_mfma_f32_16x16x32_bf16 v[46:49], v[146:149], v[196:199], v[46:49]
	v_mfma_f32_16x16x32_bf16 v[42:45], v[172:175], v[196:199], v[42:45]
	v_mfma_f32_16x16x32_bf16 v[38:41], v[146:149], v[204:207], v[38:41]
	v_mfma_f32_16x16x32_bf16 v[34:37], v[172:175], v[204:207], v[34:37]
	v_mfma_f32_16x16x32_bf16 v[62:65], v[150:153], v[184:187], v[62:65]
	v_mfma_f32_16x16x32_bf16 v[58:61], v[176:179], v[184:187], v[58:61]
	v_mfma_f32_16x16x32_bf16 v[54:57], v[150:153], v[192:195], v[54:57]
	v_mfma_f32_16x16x32_bf16 v[50:53], v[176:179], v[192:195], v[50:53]
	v_mfma_f32_16x16x32_bf16 v[46:49], v[150:153], v[200:203], v[46:49]
	v_mfma_f32_16x16x32_bf16 v[42:45], v[176:179], v[200:203], v[42:45]
	v_mfma_f32_16x16x32_bf16 v[38:41], v[150:153], v[208:211], v[38:41]
	v_mfma_f32_16x16x32_bf16 v[34:37], v[176:179], v[208:211], v[34:37]
	s_setprio 0
	s_barrier
	s_add_i32 s54, s80, s56
	v_lshl_add_u64 v[212:213], v[212:213], 0, s[22:23]
	s_mov_b32 m0, s54
	ds_read_b128 v[180:183], v235 offset:49152
	ds_read_b128 v[184:187], v235 offset:50176
	ds_read_b128 v[188:191], v235 offset:51200
	ds_read_b128 v[192:195], v235 offset:52224
	ds_read_b128 v[196:199], v235 offset:53248
	ds_read_b128 v[200:203], v235 offset:54272
	ds_read_b128 v[204:207], v235 offset:55296
	ds_read_b128 v[208:211], v235 offset:56320
	global_load_lds_dwordx4 v[212:213], off
	s_add_i32 m0, s54, 0x2000
	s_add_u32 s4, s4, 0x100080
	v_lshl_add_u64 v[212:213], v[214:215], 0, s[22:23]
	s_addc_u32 s5, s5, 0
	s_add_i32 s54, s81, s56
	global_load_lds_dwordx4 v[212:213], off
	v_lshl_add_u64 v[212:213], s[4:5], 0, v[156:157]
	s_mov_b32 m0, s54
	s_nop 0
	global_load_lds_dwordx4 v[212:213], off
	v_lshl_add_u64 v[212:213], s[4:5], 0, v[160:161]
	s_add_i32 m0, s54, 0x2000
	s_nop 0
	global_load_lds_dwordx4 v[212:213], off
	v_lshl_add_u64 v[212:213], v[216:217], 0, s[22:23]
	s_mov_b32 m0, s67
	s_nop 0
	global_load_lds_dwordx4 v[212:213], off
	v_lshl_add_u64 v[212:213], v[218:219], 0, s[22:23]
	s_mov_b32 m0, s72
	s_nop 0
	global_load_lds_dwordx4 v[212:213], off
	s_waitcnt vmcnt(8)
	s_waitcnt lgkmcnt(0)
	s_barrier
	s_setprio 1
	s_waitcnt lgkmcnt(0)
	v_mfma_f32_16x16x32_bf16 v[94:97], v[130:133], v[180:183], v[94:97]
	v_mfma_f32_16x16x32_bf16 v[90:93], v[138:141], v[180:183], v[90:93]
	v_mfma_f32_16x16x32_bf16 v[86:89], v[130:133], v[188:191], v[86:89]
	v_mfma_f32_16x16x32_bf16 v[82:85], v[138:141], v[188:191], v[82:85]
	v_mfma_f32_16x16x32_bf16 v[78:81], v[130:133], v[196:199], v[78:81]
	v_mfma_f32_16x16x32_bf16 v[74:77], v[138:141], v[196:199], v[74:77]
	v_mfma_f32_16x16x32_bf16 v[70:73], v[130:133], v[204:207], v[70:73]
	v_mfma_f32_16x16x32_bf16 v[66:69], v[138:141], v[204:207], v[66:69]
	v_mfma_f32_16x16x32_bf16 v[94:97], v[134:137], v[184:187], v[94:97]
	v_mfma_f32_16x16x32_bf16 v[90:93], v[142:145], v[184:187], v[90:93]
	v_mfma_f32_16x16x32_bf16 v[86:89], v[134:137], v[192:195], v[86:89]
	v_mfma_f32_16x16x32_bf16 v[82:85], v[142:145], v[192:195], v[82:85]
	v_mfma_f32_16x16x32_bf16 v[78:81], v[134:137], v[200:203], v[78:81]
	v_mfma_f32_16x16x32_bf16 v[74:77], v[142:145], v[200:203], v[74:77]
	v_mfma_f32_16x16x32_bf16 v[70:73], v[134:137], v[208:211], v[70:73]
	v_mfma_f32_16x16x32_bf16 v[66:69], v[142:145], v[208:211], v[66:69]
	s_setprio 0
	s_setprio 1
	v_mfma_f32_16x16x32_bf16 v[30:33], v[146:149], v[180:183], v[30:33]
	v_mfma_f32_16x16x32_bf16 v[26:29], v[172:175], v[180:183], v[26:29]
	v_mfma_f32_16x16x32_bf16 v[22:25], v[146:149], v[188:191], v[22:25]
	v_mfma_f32_16x16x32_bf16 v[18:21], v[172:175], v[188:191], v[18:21]
	v_mfma_f32_16x16x32_bf16 v[14:17], v[146:149], v[196:199], v[14:17]
	v_mfma_f32_16x16x32_bf16 v[10:13], v[172:175], v[196:199], v[10:13]
	v_mfma_f32_16x16x32_bf16 v[6:9], v[146:149], v[204:207], v[6:9]
	v_mfma_f32_16x16x32_bf16 v[2:5], v[172:175], v[204:207], v[2:5]
	v_mfma_f32_16x16x32_bf16 v[30:33], v[150:153], v[184:187], v[30:33]
	v_mfma_f32_16x16x32_bf16 v[26:29], v[176:179], v[184:187], v[26:29]
	v_mfma_f32_16x16x32_bf16 v[22:25], v[150:153], v[192:195], v[22:25]
	v_mfma_f32_16x16x32_bf16 v[18:21], v[176:179], v[192:195], v[18:21]
	v_mfma_f32_16x16x32_bf16 v[14:17], v[150:153], v[200:203], v[14:17]
	v_mfma_f32_16x16x32_bf16 v[10:13], v[176:179], v[200:203], v[10:13]
	v_mfma_f32_16x16x32_bf16 v[6:9], v[150:153], v[208:211], v[6:9]
	v_mfma_f32_16x16x32_bf16 v[2:5], v[176:179], v[208:211], v[2:5]
	s_setprio 0
	s_barrier
	s_add_i32 s79, s79, 2
	s_add_u32 s52, s52, 0x100
	s_addc_u32 s53, s53, 0
	s_add_u32 s77, s77, 0x100
	s_addc_u32 s78, s78, 0
	s_cmp_gt_u32 s79, 61
	s_cbranch_scc0 .LBB0_459
	s_and_b64 vcc, exec, s[24:25]
	s_cbranch_vccz .LBB0_462
	s_barrier

.LBB0_559:
	ds_read_b128 v[98:101], v173
	ds_read_b128 v[102:105], v173 offset:1024
	ds_read_b128 v[106:109], v173 offset:2048
	ds_read_b128 v[110:113], v173 offset:3072
	ds_read_b128 v[162:165], v174
	ds_read_b128 v[168:171], v174 offset:1024
	ds_read_b128 v[178:181], v174 offset:2048
	ds_read_b128 v[182:185], v174 offset:3072
	s_add_u32 s4, s38, 0xfff80080
	s_addc_u32 s5, s39, -1
	s_cmp_eq_u32 s72, 28
	s_cselect_b32 s41, s31, s5
	s_cselect_b32 s40, s66, s4
	s_cselect_b32 s5, s29, s69
	s_cselect_b32 s4, s67, s68
	v_lshl_add_u64 v[218:219], s[38:39], 0, v[154:155]
	s_add_i32 m0, s50, 0xc000
	ds_read_b128 v[186:189], v175
	ds_read_b128 v[190:193], v175 offset:1024
	ds_read_b128 v[194:197], v175 offset:2048
	ds_read_b128 v[198:201], v175 offset:3072
	ds_read_b128 v[202:205], v175 offset:4096
	ds_read_b128 v[206:209], v175 offset:5120
	ds_read_b128 v[210:213], v175 offset:6144
	ds_read_b128 v[214:217], v175 offset:7168
	global_load_lds_dwordx4 v[218:219], off
	v_lshl_add_u64 v[218:219], s[38:39], 0, v[156:157]
	s_add_i32 m0, s50, 0xe000
	s_nop 0
	global_load_lds_dwordx4 v[218:219], off
	s_waitcnt vmcnt(8)
	s_waitcnt lgkmcnt(0)
	s_barrier
	s_setprio 1
	s_waitcnt lgkmcnt(0)
	v_mfma_f32_16x16x32_bf16 v[142:145], v[98:101], v[186:189], v[142:145]
	v_mfma_f32_16x16x32_bf16 v[138:141], v[106:109], v[186:189], v[138:141]
	v_mfma_f32_16x16x32_bf16 v[126:129], v[98:101], v[194:197], v[126:129]
	v_mfma_f32_16x16x32_bf16 v[122:125], v[106:109], v[194:197], v[122:125]
	v_mfma_f32_16x16x32_bf16 v[94:97], v[98:101], v[202:205], v[94:97]
	v_mfma_f32_16x16x32_bf16 v[90:93], v[106:109], v[202:205], v[90:93]
	v_mfma_f32_16x16x32_bf16 v[78:81], v[98:101], v[210:213], v[78:81]
	v_mfma_f32_16x16x32_bf16 v[74:77], v[106:109], v[210:213], v[74:77]
	v_mfma_f32_16x16x32_bf16 v[142:145], v[102:105], v[190:193], v[142:145]
	v_mfma_f32_16x16x32_bf16 v[138:141], v[110:113], v[190:193], v[138:141]
	v_mfma_f32_16x16x32_bf16 v[126:129], v[102:105], v[198:201], v[126:129]
	v_mfma_f32_16x16x32_bf16 v[122:125], v[110:113], v[198:201], v[122:125]
	v_mfma_f32_16x16x32_bf16 v[94:97], v[102:105], v[206:209], v[94:97]
	v_mfma_f32_16x16x32_bf16 v[90:93], v[110:113], v[206:209], v[90:93]
	v_mfma_f32_16x16x32_bf16 v[78:81], v[102:105], v[214:217], v[78:81]
	v_mfma_f32_16x16x32_bf16 v[74:77], v[110:113], v[214:217], v[74:77]
	s_setprio 0
	s_setprio 1
	v_mfma_f32_16x16x32_bf16 v[134:137], v[162:165], v[186:189], v[134:137]
	v_mfma_f32_16x16x32_bf16 v[130:133], v[178:181], v[186:189], v[130:133]
	v_mfma_f32_16x16x32_bf16 v[118:121], v[162:165], v[194:197], v[118:121]
	v_mfma_f32_16x16x32_bf16 v[114:117], v[178:181], v[194:197], v[114:117]
	v_mfma_f32_16x16x32_bf16 v[86:89], v[162:165], v[202:205], v[86:89]
	v_mfma_f32_16x16x32_bf16 v[82:85], v[178:181], v[202:205], v[82:85]
	v_mfma_f32_16x16x32_bf16 v[70:73], v[162:165], v[210:213], v[70:73]
	v_mfma_f32_16x16x32_bf16 v[66:69], v[178:181], v[210:213], v[66:69]
	v_mfma_f32_16x16x32_bf16 v[134:137], v[168:171], v[190:193], v[134:137]
	v_mfma_f32_16x16x32_bf16 v[130:133], v[182:185], v[190:193], v[130:133]
	v_mfma_f32_16x16x32_bf16 v[118:121], v[168:171], v[198:201], v[118:121]
	v_mfma_f32_16x16x32_bf16 v[114:117], v[182:185], v[198:201], v[114:117]
	v_mfma_f32_16x16x32_bf16 v[86:89], v[168:171], v[206:209], v[86:89]
	v_mfma_f32_16x16x32_bf16 v[82:85], v[182:185], v[206:209], v[82:85]
	v_mfma_f32_16x16x32_bf16 v[70:73], v[168:171], v[214:217], v[70:73]
	v_mfma_f32_16x16x32_bf16 v[66:69], v[182:185], v[214:217], v[66:69]
	s_setprio 0
	s_barrier
	s_add_i32 s73, s59, s42
	v_lshl_add_u64 v[218:219], s[4:5], 0, v[148:149]
	s_mov_b32 m0, s73
	ds_read_b128 v[186:189], v175 offset:16384
	ds_read_b128 v[190:193], v175 offset:17408
	ds_read_b128 v[194:197], v175 offset:18432
	ds_read_b128 v[198:201], v175 offset:19456
	ds_read_b128 v[202:205], v175 offset:20480
	ds_read_b128 v[206:209], v175 offset:21504
	ds_read_b128 v[210:213], v175 offset:22528
	ds_read_b128 v[214:217], v175 offset:23552
	global_load_lds_dwordx4 v[218:219], off
	s_add_i32 m0, s73, 0x2000
	s_add_u32 s74, s4, 0x80000
	v_lshl_add_u64 v[220:221], s[4:5], 0, v[152:153]
	s_addc_u32 s75, s5, 0
	s_add_i32 s73, s60, s42
	global_load_lds_dwordx4 v[220:221], off
	v_lshl_add_u64 v[222:223], s[74:75], 0, v[148:149]
	s_mov_b32 m0, s73
	v_lshl_add_u64 v[224:225], s[40:41], 0, v[150:151]
	global_load_lds_dwordx4 v[222:223], off
	v_lshl_add_u64 v[222:223], s[74:75], 0, v[152:153]
	s_add_i32 m0, s73, 0x2000
	s_nop 0
	global_load_lds_dwordx4 v[222:223], off
	v_lshl_add_u64 v[222:223], s[40:41], 0, v[146:147]
	s_mov_b32 m0, s50
	s_nop 0
	global_load_lds_dwordx4 v[222:223], off
	s_mov_b32 m0, s51
	s_nop 0
	global_load_lds_dwordx4 v[224:225], off
	s_waitcnt vmcnt(8)
	s_waitcnt lgkmcnt(0)
	s_barrier
	s_setprio 1
	s_waitcnt lgkmcnt(0)
	v_mfma_f32_16x16x32_bf16 v[62:65], v[98:101], v[186:189], v[62:65]
	v_mfma_f32_16x16x32_bf16 v[58:61], v[106:109], v[186:189], v[58:61]
	v_mfma_f32_16x16x32_bf16 v[46:49], v[98:101], v[194:197], v[46:49]
	v_mfma_f32_16x16x32_bf16 v[42:45], v[106:109], v[194:197], v[42:45]
	v_mfma_f32_16x16x32_bf16 v[30:33], v[98:101], v[202:205], v[30:33]
	v_mfma_f32_16x16x32_bf16 v[26:29], v[106:109], v[202:205], v[26:29]
	v_mfma_f32_16x16x32_bf16 v[14:17], v[98:101], v[210:213], v[14:17]
	v_mfma_f32_16x16x32_bf16 v[10:13], v[106:109], v[210:213], v[10:13]
	v_mfma_f32_16x16x32_bf16 v[62:65], v[102:105], v[190:193], v[62:65]
	v_mfma_f32_16x16x32_bf16 v[58:61], v[110:113], v[190:193], v[58:61]
	v_mfma_f32_16x16x32_bf16 v[46:49], v[102:105], v[198:201], v[46:49]
	v_mfma_f32_16x16x32_bf16 v[42:45], v[110:113], v[198:201], v[42:45]
	v_mfma_f32_16x16x32_bf16 v[30:33], v[102:105], v[206:209], v[30:33]
	v_mfma_f32_16x16x32_bf16 v[26:29], v[110:113], v[206:209], v[26:29]
	v_mfma_f32_16x16x32_bf16 v[14:17], v[102:105], v[214:217], v[14:17]
	v_mfma_f32_16x16x32_bf16 v[10:13], v[110:113], v[214:217], v[10:13]
	s_setprio 0
	s_setprio 1
	v_mfma_f32_16x16x32_bf16 v[54:57], v[162:165], v[186:189], v[54:57]
	v_mfma_f32_16x16x32_bf16 v[50:53], v[178:181], v[186:189], v[50:53]
	v_mfma_f32_16x16x32_bf16 v[38:41], v[162:165], v[194:197], v[38:41]
	v_mfma_f32_16x16x32_bf16 v[34:37], v[178:181], v[194:197], v[34:37]
	v_mfma_f32_16x16x32_bf16 v[22:25], v[162:165], v[202:205], v[22:25]
	v_mfma_f32_16x16x32_bf16 v[18:21], v[178:181], v[202:205], v[18:21]
	v_mfma_f32_16x16x32_bf16 v[6:9], v[162:165], v[210:213], v[6:9]
	v_mfma_f32_16x16x32_bf16 v[2:5], v[178:181], v[210:213], v[2:5]
	v_mfma_f32_16x16x32_bf16 v[54:57], v[168:171], v[190:193], v[54:57]
	v_mfma_f32_16x16x32_bf16 v[50:53], v[182:185], v[190:193], v[50:53]
	v_mfma_f32_16x16x32_bf16 v[38:41], v[168:171], v[198:201], v[38:41]
	v_mfma_f32_16x16x32_bf16 v[34:37], v[182:185], v[198:201], v[34:37]
	v_mfma_f32_16x16x32_bf16 v[22:25], v[168:171], v[206:209], v[22:25]
	v_mfma_f32_16x16x32_bf16 v[18:21], v[182:185], v[206:209], v[18:21]
	v_mfma_f32_16x16x32_bf16 v[6:9], v[168:171], v[214:217], v[6:9]
	v_mfma_f32_16x16x32_bf16 v[2:5], v[182:185], v[214:217], v[2:5]
	s_setprio 0
	s_barrier
	s_add_i32 s73, 0, 0x18000
	s_add_i32 s74, 0, 0x1c000
	v_add_u32_e32 v110, s73, v167
	v_add_u32_e32 v177, s74, v167
	ds_read_b128 v[98:101], v110
	ds_read_b128 v[102:105], v110 offset:1024
	ds_read_b128 v[106:109], v110 offset:2048
	ds_read_b128 v[110:113], v110 offset:3072
	ds_read_b128 v[162:165], v177
	ds_read_b128 v[168:171], v177 offset:1024
	ds_read_b128 v[178:181], v177 offset:2048
	ds_read_b128 v[182:185], v177 offset:3072
	s_add_u32 s40, s40, 0x80000
	s_addc_u32 s41, s41, 0
	s_mov_b32 m0, s52
	v_lshl_add_u64 v[226:227], s[40:41], 0, v[146:147]
	ds_read_b128 v[186:189], v175 offset:32768
	ds_read_b128 v[190:193], v175 offset:33792
	ds_read_b128 v[194:197], v175 offset:34816
	ds_read_b128 v[198:201], v175 offset:35840
	ds_read_b128 v[202:205], v175 offset:36864
	ds_read_b128 v[206:209], v175 offset:37888
	ds_read_b128 v[210:213], v175 offset:38912
	ds_read_b128 v[214:217], v175 offset:39936
	global_load_lds_dwordx4 v[226:227], off
	v_lshl_add_u64 v[226:227], s[40:41], 0, v[150:151]
	s_mov_b32 m0, s53
	s_nop 0
	global_load_lds_dwordx4 v[226:227], off
	s_waitcnt vmcnt(8)
	s_waitcnt lgkmcnt(0)
	s_barrier
	s_setprio 1
	s_waitcnt lgkmcnt(0)
	v_mfma_f32_16x16x32_bf16 v[142:145], v[98:101], v[186:189], v[142:145]
	v_mfma_f32_16x16x32_bf16 v[138:141], v[106:109], v[186:189], v[138:141]
	v_mfma_f32_16x16x32_bf16 v[126:129], v[98:101], v[194:197], v[126:129]
	v_mfma_f32_16x16x32_bf16 v[122:125], v[106:109], v[194:197], v[122:125]
	v_mfma_f32_16x16x32_bf16 v[94:97], v[98:101], v[202:205], v[94:97]
	v_mfma_f32_16x16x32_bf16 v[90:93], v[106:109], v[202:205], v[90:93]
	v_mfma_f32_16x16x32_bf16 v[78:81], v[98:101], v[210:213], v[78:81]
	v_mfma_f32_16x16x32_bf16 v[74:77], v[106:109], v[210:213], v[74:77]
	v_mfma_f32_16x16x32_bf16 v[142:145], v[102:105], v[190:193], v[142:145]
	v_mfma_f32_16x16x32_bf16 v[138:141], v[110:113], v[190:193], v[138:141]
	v_mfma_f32_16x16x32_bf16 v[126:129], v[102:105], v[198:201], v[126:129]
	v_mfma_f32_16x16x32_bf16 v[122:125], v[110:113], v[198:201], v[122:125]
	v_mfma_f32_16x16x32_bf16 v[94:97], v[102:105], v[206:209], v[94:97]
	v_mfma_f32_16x16x32_bf16 v[90:93], v[110:113], v[206:209], v[90:93]
	v_mfma_f32_16x16x32_bf16 v[78:81], v[102:105], v[214:217], v[78:81]
	v_mfma_f32_16x16x32_bf16 v[74:77], v[110:113], v[214:217], v[74:77]
	s_setprio 0
	s_setprio 1
	v_mfma_f32_16x16x32_bf16 v[134:137], v[162:165], v[186:189], v[134:137]
	v_mfma_f32_16x16x32_bf16 v[130:133], v[178:181], v[186:189], v[130:133]
	v_mfma_f32_16x16x32_bf16 v[118:121], v[162:165], v[194:197], v[118:121]
	v_mfma_f32_16x16x32_bf16 v[114:117], v[178:181], v[194:197], v[114:117]
	v_mfma_f32_16x16x32_bf16 v[86:89], v[162:165], v[202:205], v[86:89]
	v_mfma_f32_16x16x32_bf16 v[82:85], v[178:181], v[202:205], v[82:85]
	v_mfma_f32_16x16x32_bf16 v[70:73], v[162:165], v[210:213], v[70:73]
	v_mfma_f32_16x16x32_bf16 v[66:69], v[178:181], v[210:213], v[66:69]
	v_mfma_f32_16x16x32_bf16 v[134:137], v[168:171], v[190:193], v[134:137]
	v_mfma_f32_16x16x32_bf16 v[130:133], v[182:185], v[190:193], v[130:133]
	v_mfma_f32_16x16x32_bf16 v[118:121], v[168:171], v[198:201], v[118:121]
	v_mfma_f32_16x16x32_bf16 v[114:117], v[182:185], v[198:201], v[114:117]
	v_mfma_f32_16x16x32_bf16 v[86:89], v[168:171], v[206:209], v[86:89]
	v_mfma_f32_16x16x32_bf16 v[82:85], v[182:185], v[206:209], v[82:85]
	v_mfma_f32_16x16x32_bf16 v[70:73], v[168:171], v[214:217], v[70:73]
	v_mfma_f32_16x16x32_bf16 v[66:69], v[182:185], v[214:217], v[66:69]
	s_setprio 0
	s_barrier
	s_add_i32 s40, s73, s42
	v_lshl_add_u64 v[218:219], v[218:219], 0, s[16:17]
	s_mov_b32 m0, s40
	ds_read_b128 v[186:189], v175 offset:49152
	ds_read_b128 v[190:193], v175 offset:50176
	ds_read_b128 v[194:197], v175 offset:51200
	ds_read_b128 v[198:201], v175 offset:52224
	ds_read_b128 v[202:205], v175 offset:53248
	ds_read_b128 v[206:209], v175 offset:54272
	ds_read_b128 v[210:213], v175 offset:55296
	ds_read_b128 v[214:217], v175 offset:56320
	global_load_lds_dwordx4 v[218:219], off
	s_add_i32 m0, s40, 0x2000
	s_add_u32 s4, s4, 0x80080
	v_lshl_add_u64 v[218:219], v[220:221], 0, s[16:17]
	s_addc_u32 s5, s5, 0
	s_add_i32 s40, s74, s42
	global_load_lds_dwordx4 v[218:219], off
	v_lshl_add_u64 v[218:219], s[4:5], 0, v[148:149]
	s_mov_b32 m0, s40
	s_nop 0
	global_load_lds_dwordx4 v[218:219], off
	v_lshl_add_u64 v[218:219], s[4:5], 0, v[152:153]
	s_add_i32 m0, s40, 0x2000
	s_nop 0
	global_load_lds_dwordx4 v[218:219], off
	v_lshl_add_u64 v[218:219], v[222:223], 0, s[16:17]
	s_mov_b32 m0, s56
	s_nop 0
	global_load_lds_dwordx4 v[218:219], off
	v_lshl_add_u64 v[218:219], v[224:225], 0, s[16:17]
	s_mov_b32 m0, s57
	s_nop 0
	global_load_lds_dwordx4 v[218:219], off
	s_waitcnt vmcnt(8)
	s_waitcnt lgkmcnt(0)
	s_barrier
	s_setprio 1
	s_waitcnt lgkmcnt(0)
	v_mfma_f32_16x16x32_bf16 v[62:65], v[98:101], v[186:189], v[62:65]
	v_mfma_f32_16x16x32_bf16 v[58:61], v[106:109], v[186:189], v[58:61]
	v_mfma_f32_16x16x32_bf16 v[46:49], v[98:101], v[194:197], v[46:49]
	v_mfma_f32_16x16x32_bf16 v[42:45], v[106:109], v[194:197], v[42:45]
	v_mfma_f32_16x16x32_bf16 v[30:33], v[98:101], v[202:205], v[30:33]
	v_mfma_f32_16x16x32_bf16 v[26:29], v[106:109], v[202:205], v[26:29]
	v_mfma_f32_16x16x32_bf16 v[14:17], v[98:101], v[210:213], v[14:17]
	v_mfma_f32_16x16x32_bf16 v[10:13], v[106:109], v[210:213], v[10:13]
	v_mfma_f32_16x16x32_bf16 v[62:65], v[102:105], v[190:193], v[62:65]
	v_mfma_f32_16x16x32_bf16 v[58:61], v[110:113], v[190:193], v[58:61]
	v_mfma_f32_16x16x32_bf16 v[46:49], v[102:105], v[198:201], v[46:49]
	v_mfma_f32_16x16x32_bf16 v[42:45], v[110:113], v[198:201], v[42:45]
	v_mfma_f32_16x16x32_bf16 v[30:33], v[102:105], v[206:209], v[30:33]
	v_mfma_f32_16x16x32_bf16 v[26:29], v[110:113], v[206:209], v[26:29]
	v_mfma_f32_16x16x32_bf16 v[14:17], v[102:105], v[214:217], v[14:17]
	v_mfma_f32_16x16x32_bf16 v[10:13], v[110:113], v[214:217], v[10:13]
	s_setprio 0
	s_setprio 1
	v_mfma_f32_16x16x32_bf16 v[54:57], v[162:165], v[186:189], v[54:57]
	v_mfma_f32_16x16x32_bf16 v[50:53], v[178:181], v[186:189], v[50:53]
	v_mfma_f32_16x16x32_bf16 v[38:41], v[162:165], v[194:197], v[38:41]
	v_mfma_f32_16x16x32_bf16 v[34:37], v[178:181], v[194:197], v[34:37]
	v_mfma_f32_16x16x32_bf16 v[22:25], v[162:165], v[202:205], v[22:25]
	v_mfma_f32_16x16x32_bf16 v[18:21], v[178:181], v[202:205], v[18:21]
	v_mfma_f32_16x16x32_bf16 v[6:9], v[162:165], v[210:213], v[6:9]
	v_mfma_f32_16x16x32_bf16 v[2:5], v[178:181], v[210:213], v[2:5]
	v_mfma_f32_16x16x32_bf16 v[54:57], v[168:171], v[190:193], v[54:57]
	v_mfma_f32_16x16x32_bf16 v[50:53], v[182:185], v[190:193], v[50:53]
	v_mfma_f32_16x16x32_bf16 v[38:41], v[168:171], v[198:201], v[38:41]
	v_mfma_f32_16x16x32_bf16 v[34:37], v[182:185], v[198:201], v[34:37]
	v_mfma_f32_16x16x32_bf16 v[22:25], v[168:171], v[206:209], v[22:25]
	v_mfma_f32_16x16x32_bf16 v[18:21], v[182:185], v[206:209], v[18:21]
	v_mfma_f32_16x16x32_bf16 v[6:9], v[168:171], v[214:217], v[6:9]
	v_mfma_f32_16x16x32_bf16 v[2:5], v[182:185], v[214:217], v[2:5]
	s_setprio 0
	s_barrier
	s_add_i32 s72, s72, 2
	s_add_u32 s38, s38, 0x100
	s_addc_u32 s39, s39, 0
	s_add_u32 s68, s68, 0x100
	s_addc_u32 s69, s69, 0
	s_cmp_gt_u32 s72, 29
	s_cbranch_scc0 .LBB0_559
	s_and_b64 vcc, exec, s[18:19]
	s_cbranch_vccz .LBB0_562
	s_barrier

.LBB0_637:
	ds_read_b128 v[130:133], v217
	ds_read_b128 v[134:137], v217 offset:1024
	ds_read_b128 v[154:157], v217 offset:2048
	ds_read_b128 v[158:161], v217 offset:3072
	ds_read_b128 v[162:165], v218
	ds_read_b128 v[168:171], v218 offset:1024
	ds_read_b128 v[172:175], v218 offset:2048
	ds_read_b128 v[176:179], v218 offset:3072
	s_add_u32 s4, s42, 0xffe00080
	s_addc_u32 s5, s43, -1
	s_cmpk_eq_i32 s77, 0x7c
	s_cselect_b32 s53, s31, s5
	s_cselect_b32 s52, s73, s4
	s_cselect_b32 s5, s29, s76
	s_cselect_b32 s4, s74, s75
	v_lshl_add_u64 v[212:213], s[42:43], 0, v[146:147]
	s_add_i32 m0, s39, 0xc000
	ds_read_b128 v[180:183], v219
	ds_read_b128 v[184:187], v219 offset:1024
	ds_read_b128 v[188:191], v219 offset:2048
	ds_read_b128 v[192:195], v219 offset:3072
	ds_read_b128 v[196:199], v219 offset:4096
	ds_read_b128 v[200:203], v219 offset:5120
	ds_read_b128 v[204:207], v219 offset:6144
	ds_read_b128 v[208:211], v219 offset:7168
	global_load_lds_dwordx4 v[212:213], off
	v_lshl_add_u64 v[212:213], s[42:43], 0, v[148:149]
	s_add_i32 m0, s39, 0xe000
	s_nop 0
	global_load_lds_dwordx4 v[212:213], off
	s_waitcnt vmcnt(8)
	s_waitcnt lgkmcnt(0)
	s_barrier
	s_setprio 1
	s_waitcnt lgkmcnt(0)
	v_mfma_f32_16x16x32_bf16 v[86:89], v[130:133], v[180:183], v[86:89]
	v_mfma_f32_16x16x32_bf16 v[82:85], v[154:157], v[180:183], v[82:85]
	v_mfma_f32_16x16x32_bf16 v[94:97], v[130:133], v[188:191], v[94:97]
	v_mfma_f32_16x16x32_bf16 v[90:93], v[154:157], v[188:191], v[90:93]
	v_mfma_f32_16x16x32_bf16 v[110:113], v[130:133], v[196:199], v[110:113]
	v_mfma_f32_16x16x32_bf16 v[106:109], v[154:157], v[196:199], v[106:109]
	v_mfma_f32_16x16x32_bf16 v[118:121], v[130:133], v[204:207], v[118:121]
	v_mfma_f32_16x16x32_bf16 v[114:117], v[154:157], v[204:207], v[114:117]
	v_mfma_f32_16x16x32_bf16 v[86:89], v[134:137], v[184:187], v[86:89]
	v_mfma_f32_16x16x32_bf16 v[82:85], v[158:161], v[184:187], v[82:85]
	v_mfma_f32_16x16x32_bf16 v[94:97], v[134:137], v[192:195], v[94:97]
	v_mfma_f32_16x16x32_bf16 v[90:93], v[158:161], v[192:195], v[90:93]
	v_mfma_f32_16x16x32_bf16 v[110:113], v[134:137], v[200:203], v[110:113]
	v_mfma_f32_16x16x32_bf16 v[106:109], v[158:161], v[200:203], v[106:109]
	v_mfma_f32_16x16x32_bf16 v[118:121], v[134:137], v[208:211], v[118:121]
	v_mfma_f32_16x16x32_bf16 v[114:117], v[158:161], v[208:211], v[114:117]
	s_setprio 0
	s_setprio 1
	v_mfma_f32_16x16x32_bf16 v[62:65], v[162:165], v[180:183], v[62:65]
	v_mfma_f32_16x16x32_bf16 v[58:61], v[172:175], v[180:183], v[58:61]
	v_mfma_f32_16x16x32_bf16 v[54:57], v[162:165], v[188:191], v[54:57]
	v_mfma_f32_16x16x32_bf16 v[50:53], v[172:175], v[188:191], v[50:53]
	v_mfma_f32_16x16x32_bf16 v[46:49], v[162:165], v[196:199], v[46:49]
	v_mfma_f32_16x16x32_bf16 v[42:45], v[172:175], v[196:199], v[42:45]
	v_mfma_f32_16x16x32_bf16 v[38:41], v[162:165], v[204:207], v[38:41]
	v_mfma_f32_16x16x32_bf16 v[34:37], v[172:175], v[204:207], v[34:37]
	v_mfma_f32_16x16x32_bf16 v[62:65], v[168:171], v[184:187], v[62:65]
	v_mfma_f32_16x16x32_bf16 v[58:61], v[176:179], v[184:187], v[58:61]
	v_mfma_f32_16x16x32_bf16 v[54:57], v[168:171], v[192:195], v[54:57]
	v_mfma_f32_16x16x32_bf16 v[50:53], v[176:179], v[192:195], v[50:53]
	v_mfma_f32_16x16x32_bf16 v[46:49], v[168:171], v[200:203], v[46:49]
	v_mfma_f32_16x16x32_bf16 v[42:45], v[176:179], v[200:203], v[42:45]
	v_mfma_f32_16x16x32_bf16 v[38:41], v[168:171], v[208:211], v[38:41]
	v_mfma_f32_16x16x32_bf16 v[34:37], v[176:179], v[208:211], v[34:37]
	s_setprio 0
	s_barrier
	s_add_i32 s78, s69, s54
	v_lshl_add_u64 v[212:213], s[4:5], 0, v[140:141]
	s_mov_b32 m0, s78
	ds_read_b128 v[180:183], v219 offset:16384
	ds_read_b128 v[184:187], v219 offset:17408
	ds_read_b128 v[188:191], v219 offset:18432
	ds_read_b128 v[192:195], v219 offset:19456
	ds_read_b128 v[196:199], v219 offset:20480
	ds_read_b128 v[200:203], v219 offset:21504
	ds_read_b128 v[204:207], v219 offset:22528
	ds_read_b128 v[208:211], v219 offset:23552
	global_load_lds_dwordx4 v[212:213], off
	s_add_i32 m0, s78, 0x2000
	s_add_u32 s78, s4, 0x200000
	v_lshl_add_u64 v[214:215], s[4:5], 0, v[144:145]
	s_addc_u32 s79, s5, 0
	s_add_i32 s80, s72, s54
	global_load_lds_dwordx4 v[214:215], off
	v_lshl_add_u64 v[222:223], s[78:79], 0, v[140:141]
	s_mov_b32 m0, s80
	v_lshl_add_u64 v[224:225], s[52:53], 0, v[142:143]
	global_load_lds_dwordx4 v[222:223], off
	v_lshl_add_u64 v[222:223], s[78:79], 0, v[144:145]
	s_add_i32 m0, s80, 0x2000
	s_nop 0
	global_load_lds_dwordx4 v[222:223], off
	v_lshl_add_u64 v[222:223], s[52:53], 0, v[138:139]
	s_mov_b32 m0, s39
	s_nop 0
	global_load_lds_dwordx4 v[222:223], off
	s_mov_b32 m0, s41
	s_nop 0
	global_load_lds_dwordx4 v[224:225], off
	s_waitcnt vmcnt(8)
	s_waitcnt lgkmcnt(0)
	s_barrier
	s_setprio 1
	s_waitcnt lgkmcnt(0)
	v_mfma_f32_16x16x32_bf16 v[126:129], v[130:133], v[180:183], v[126:129]
	v_mfma_f32_16x16x32_bf16 v[122:125], v[154:157], v[180:183], v[122:125]
	v_mfma_f32_16x16x32_bf16 v[102:105], v[130:133], v[188:191], v[102:105]
	v_mfma_f32_16x16x32_bf16 v[98:101], v[154:157], v[188:191], v[98:101]
	v_mfma_f32_16x16x32_bf16 v[78:81], v[130:133], v[196:199], v[78:81]
	v_mfma_f32_16x16x32_bf16 v[74:77], v[154:157], v[196:199], v[74:77]
	v_mfma_f32_16x16x32_bf16 v[70:73], v[130:133], v[204:207], v[70:73]
	v_mfma_f32_16x16x32_bf16 v[66:69], v[154:157], v[204:207], v[66:69]
	v_mfma_f32_16x16x32_bf16 v[126:129], v[134:137], v[184:187], v[126:129]
	v_mfma_f32_16x16x32_bf16 v[122:125], v[158:161], v[184:187], v[122:125]
	v_mfma_f32_16x16x32_bf16 v[102:105], v[134:137], v[192:195], v[102:105]
	v_mfma_f32_16x16x32_bf16 v[98:101], v[158:161], v[192:195], v[98:101]
	v_mfma_f32_16x16x32_bf16 v[78:81], v[134:137], v[200:203], v[78:81]
	v_mfma_f32_16x16x32_bf16 v[74:77], v[158:161], v[200:203], v[74:77]
	v_mfma_f32_16x16x32_bf16 v[70:73], v[134:137], v[208:211], v[70:73]
	v_mfma_f32_16x16x32_bf16 v[66:69], v[158:161], v[208:211], v[66:69]
	s_setprio 0
	s_setprio 1
	v_mfma_f32_16x16x32_bf16 v[30:33], v[162:165], v[180:183], v[30:33]
	v_mfma_f32_16x16x32_bf16 v[26:29], v[172:175], v[180:183], v[26:29]
	v_mfma_f32_16x16x32_bf16 v[22:25], v[162:165], v[188:191], v[22:25]
	v_mfma_f32_16x16x32_bf16 v[18:21], v[172:175], v[188:191], v[18:21]
	v_mfma_f32_16x16x32_bf16 v[14:17], v[162:165], v[196:199], v[14:17]
	v_mfma_f32_16x16x32_bf16 v[10:13], v[172:175], v[196:199], v[10:13]
	v_mfma_f32_16x16x32_bf16 v[6:9], v[162:165], v[204:207], v[6:9]
	v_mfma_f32_16x16x32_bf16 v[2:5], v[172:175], v[204:207], v[2:5]
	v_mfma_f32_16x16x32_bf16 v[30:33], v[168:171], v[184:187], v[30:33]
	v_mfma_f32_16x16x32_bf16 v[26:29], v[176:179], v[184:187], v[26:29]
	v_mfma_f32_16x16x32_bf16 v[22:25], v[168:171], v[192:195], v[22:25]
	v_mfma_f32_16x16x32_bf16 v[18:21], v[176:179], v[192:195], v[18:21]
	v_mfma_f32_16x16x32_bf16 v[14:17], v[168:171], v[200:203], v[14:17]
	v_mfma_f32_16x16x32_bf16 v[10:13], v[176:179], v[200:203], v[10:13]
	v_mfma_f32_16x16x32_bf16 v[6:9], v[168:171], v[208:211], v[6:9]
	v_mfma_f32_16x16x32_bf16 v[2:5], v[176:179], v[208:211], v[2:5]
	s_setprio 0
	s_barrier
	s_add_i32 s78, 0, 0x18000
	s_add_i32 s79, 0, 0x1c000
	v_add_u32_e32 v158, s78, v167
	v_add_u32_e32 v176, s79, v167
	ds_read_b128 v[130:133], v158
	ds_read_b128 v[134:137], v158 offset:1024
	ds_read_b128 v[154:157], v158 offset:2048
	ds_read_b128 v[158:161], v158 offset:3072
	ds_read_b128 v[162:165], v176
	ds_read_b128 v[168:171], v176 offset:1024
	ds_read_b128 v[172:175], v176 offset:2048
	ds_read_b128 v[176:179], v176 offset:3072
	s_add_u32 s52, s52, 0x200000
	s_addc_u32 s53, s53, 0
	s_mov_b32 m0, s55
	v_lshl_add_u64 v[226:227], s[52:53], 0, v[138:139]
	ds_read_b128 v[180:183], v219 offset:32768
	ds_read_b128 v[184:187], v219 offset:33792
	ds_read_b128 v[188:191], v219 offset:34816
	ds_read_b128 v[192:195], v219 offset:35840
	ds_read_b128 v[196:199], v219 offset:36864
	ds_read_b128 v[200:203], v219 offset:37888
	ds_read_b128 v[204:207], v219 offset:38912
	ds_read_b128 v[208:211], v219 offset:39936
	global_load_lds_dwordx4 v[226:227], off
	v_lshl_add_u64 v[226:227], s[52:53], 0, v[142:143]
	s_mov_b32 m0, s56
	s_nop 0
	global_load_lds_dwordx4 v[226:227], off
	s_waitcnt vmcnt(8)
	s_waitcnt lgkmcnt(0)
	s_barrier
	s_setprio 1
	s_waitcnt lgkmcnt(0)
	v_mfma_f32_16x16x32_bf16 v[86:89], v[130:133], v[180:183], v[86:89]
	v_mfma_f32_16x16x32_bf16 v[82:85], v[154:157], v[180:183], v[82:85]
	v_mfma_f32_16x16x32_bf16 v[94:97], v[130:133], v[188:191], v[94:97]
	v_mfma_f32_16x16x32_bf16 v[90:93], v[154:157], v[188:191], v[90:93]
	v_mfma_f32_16x16x32_bf16 v[110:113], v[130:133], v[196:199], v[110:113]
	v_mfma_f32_16x16x32_bf16 v[106:109], v[154:157], v[196:199], v[106:109]
	v_mfma_f32_16x16x32_bf16 v[118:121], v[130:133], v[204:207], v[118:121]
	v_mfma_f32_16x16x32_bf16 v[114:117], v[154:157], v[204:207], v[114:117]
	v_mfma_f32_16x16x32_bf16 v[86:89], v[134:137], v[184:187], v[86:89]
	v_mfma_f32_16x16x32_bf16 v[82:85], v[158:161], v[184:187], v[82:85]
	v_mfma_f32_16x16x32_bf16 v[94:97], v[134:137], v[192:195], v[94:97]
	v_mfma_f32_16x16x32_bf16 v[90:93], v[158:161], v[192:195], v[90:93]
	v_mfma_f32_16x16x32_bf16 v[110:113], v[134:137], v[200:203], v[110:113]
	v_mfma_f32_16x16x32_bf16 v[106:109], v[158:161], v[200:203], v[106:109]
	v_mfma_f32_16x16x32_bf16 v[118:121], v[134:137], v[208:211], v[118:121]
	v_mfma_f32_16x16x32_bf16 v[114:117], v[158:161], v[208:211], v[114:117]
	s_setprio 0
	s_setprio 1
	v_mfma_f32_16x16x32_bf16 v[62:65], v[162:165], v[180:183], v[62:65]
	v_mfma_f32_16x16x32_bf16 v[58:61], v[172:175], v[180:183], v[58:61]
	v_mfma_f32_16x16x32_bf16 v[54:57], v[162:165], v[188:191], v[54:57]
	v_mfma_f32_16x16x32_bf16 v[50:53], v[172:175], v[188:191], v[50:53]
	v_mfma_f32_16x16x32_bf16 v[46:49], v[162:165], v[196:199], v[46:49]
	v_mfma_f32_16x16x32_bf16 v[42:45], v[172:175], v[196:199], v[42:45]
	v_mfma_f32_16x16x32_bf16 v[38:41], v[162:165], v[204:207], v[38:41]
	v_mfma_f32_16x16x32_bf16 v[34:37], v[172:175], v[204:207], v[34:37]
	v_mfma_f32_16x16x32_bf16 v[62:65], v[168:171], v[184:187], v[62:65]
	v_mfma_f32_16x16x32_bf16 v[58:61], v[176:179], v[184:187], v[58:61]
	v_mfma_f32_16x16x32_bf16 v[54:57], v[168:171], v[192:195], v[54:57]
	v_mfma_f32_16x16x32_bf16 v[50:53], v[176:179], v[192:195], v[50:53]
	v_mfma_f32_16x16x32_bf16 v[46:49], v[168:171], v[200:203], v[46:49]
	v_mfma_f32_16x16x32_bf16 v[42:45], v[176:179], v[200:203], v[42:45]
	v_mfma_f32_16x16x32_bf16 v[38:41], v[168:171], v[208:211], v[38:41]
	v_mfma_f32_16x16x32_bf16 v[34:37], v[176:179], v[208:211], v[34:37]
	s_setprio 0
	s_barrier
	s_add_i32 s52, s78, s54
	v_lshl_add_u64 v[212:213], v[212:213], 0, s[16:17]
	s_mov_b32 m0, s52
	ds_read_b128 v[180:183], v219 offset:49152
	ds_read_b128 v[184:187], v219 offset:50176
	ds_read_b128 v[188:191], v219 offset:51200
	ds_read_b128 v[192:195], v219 offset:52224
	ds_read_b128 v[196:199], v219 offset:53248
	ds_read_b128 v[200:203], v219 offset:54272
	ds_read_b128 v[204:207], v219 offset:55296
	ds_read_b128 v[208:211], v219 offset:56320
	global_load_lds_dwordx4 v[212:213], off
	s_add_i32 m0, s52, 0x2000
	s_add_u32 s4, s4, 0x200080
	v_lshl_add_u64 v[212:213], v[214:215], 0, s[16:17]
	s_addc_u32 s5, s5, 0
	s_add_i32 s52, s79, s54
	global_load_lds_dwordx4 v[212:213], off
	v_lshl_add_u64 v[212:213], s[4:5], 0, v[140:141]
	s_mov_b32 m0, s52
	s_nop 0
	global_load_lds_dwordx4 v[212:213], off
	v_lshl_add_u64 v[212:213], s[4:5], 0, v[144:145]
	s_add_i32 m0, s52, 0x2000
	s_nop 0
	global_load_lds_dwordx4 v[212:213], off
	v_lshl_add_u64 v[212:213], v[222:223], 0, s[16:17]
	s_mov_b32 m0, s66
	s_nop 0
	global_load_lds_dwordx4 v[212:213], off
	v_lshl_add_u64 v[212:213], v[224:225], 0, s[16:17]
	s_mov_b32 m0, s67
	s_nop 0
	global_load_lds_dwordx4 v[212:213], off
	s_waitcnt vmcnt(8)
	s_waitcnt lgkmcnt(0)
	s_barrier
	s_setprio 1
	s_waitcnt lgkmcnt(0)
	v_mfma_f32_16x16x32_bf16 v[126:129], v[130:133], v[180:183], v[126:129]
	v_mfma_f32_16x16x32_bf16 v[122:125], v[154:157], v[180:183], v[122:125]
	v_mfma_f32_16x16x32_bf16 v[102:105], v[130:133], v[188:191], v[102:105]
	v_mfma_f32_16x16x32_bf16 v[98:101], v[154:157], v[188:191], v[98:101]
	v_mfma_f32_16x16x32_bf16 v[78:81], v[130:133], v[196:199], v[78:81]
	v_mfma_f32_16x16x32_bf16 v[74:77], v[154:157], v[196:199], v[74:77]
	v_mfma_f32_16x16x32_bf16 v[70:73], v[130:133], v[204:207], v[70:73]
	v_mfma_f32_16x16x32_bf16 v[66:69], v[154:157], v[204:207], v[66:69]
	v_mfma_f32_16x16x32_bf16 v[126:129], v[134:137], v[184:187], v[126:129]
	v_mfma_f32_16x16x32_bf16 v[122:125], v[158:161], v[184:187], v[122:125]
	v_mfma_f32_16x16x32_bf16 v[102:105], v[134:137], v[192:195], v[102:105]
	v_mfma_f32_16x16x32_bf16 v[98:101], v[158:161], v[192:195], v[98:101]
	v_mfma_f32_16x16x32_bf16 v[78:81], v[134:137], v[200:203], v[78:81]
	v_mfma_f32_16x16x32_bf16 v[74:77], v[158:161], v[200:203], v[74:77]
	v_mfma_f32_16x16x32_bf16 v[70:73], v[134:137], v[208:211], v[70:73]
	v_mfma_f32_16x16x32_bf16 v[66:69], v[158:161], v[208:211], v[66:69]
	s_setprio 0
	s_setprio 1
	v_mfma_f32_16x16x32_bf16 v[30:33], v[162:165], v[180:183], v[30:33]
	v_mfma_f32_16x16x32_bf16 v[26:29], v[172:175], v[180:183], v[26:29]
	v_mfma_f32_16x16x32_bf16 v[22:25], v[162:165], v[188:191], v[22:25]
	v_mfma_f32_16x16x32_bf16 v[18:21], v[172:175], v[188:191], v[18:21]
	v_mfma_f32_16x16x32_bf16 v[14:17], v[162:165], v[196:199], v[14:17]
	v_mfma_f32_16x16x32_bf16 v[10:13], v[172:175], v[196:199], v[10:13]
	v_mfma_f32_16x16x32_bf16 v[6:9], v[162:165], v[204:207], v[6:9]
	v_mfma_f32_16x16x32_bf16 v[2:5], v[172:175], v[204:207], v[2:5]
	v_mfma_f32_16x16x32_bf16 v[30:33], v[168:171], v[184:187], v[30:33]
	v_mfma_f32_16x16x32_bf16 v[26:29], v[176:179], v[184:187], v[26:29]
	v_mfma_f32_16x16x32_bf16 v[22:25], v[168:171], v[192:195], v[22:25]
	v_mfma_f32_16x16x32_bf16 v[18:21], v[176:179], v[192:195], v[18:21]
	v_mfma_f32_16x16x32_bf16 v[14:17], v[168:171], v[200:203], v[14:17]
	v_mfma_f32_16x16x32_bf16 v[10:13], v[176:179], v[200:203], v[10:13]
	v_mfma_f32_16x16x32_bf16 v[6:9], v[168:171], v[208:211], v[6:9]
	v_mfma_f32_16x16x32_bf16 v[2:5], v[176:179], v[208:211], v[2:5]
	s_setprio 0
	s_barrier
	s_add_i32 s77, s77, 2
	s_add_u32 s42, s42, 0x100
	s_addc_u32 s43, s43, 0
	s_add_u32 s75, s75, 0x100
	s_addc_u32 s76, s76, 0
	s_cmpk_gt_u32 s77, 0x7d
	s_cbranch_scc0 .LBB0_637
	s_and_b64 vcc, exec, s[18:19]
	s_cbranch_vccz .LBB0_640
	s_barrier

.LBB0_727:
	ds_read_b128 v[94:97], v182
	ds_read_b128 v[102:105], v182 offset:1024
	ds_read_b128 v[106:109], v182 offset:2048
	ds_read_b128 v[110:113], v182 offset:3072
	ds_read_b128 v[118:121], v183
	ds_read_b128 v[126:129], v183 offset:1024
	ds_read_b128 v[178:181], v183 offset:2048
	ds_read_b128 v[188:191], v183 offset:3072
	s_add_u32 s4, s34, 0xfff80080
	s_addc_u32 s5, s35, -1
	s_cmp_eq_u32 s67, 28
	s_cselect_b32 s37, s9, s5
	s_cselect_b32 s36, s11, s4
	s_cselect_b32 s5, s25, s66
	s_cselect_b32 s4, s27, s65
	v_lshl_add_u64 v[224:225], s[34:35], 0, v[170:171]
	s_add_i32 m0, s39, 0xc000
	ds_read_b128 v[192:195], v184
	ds_read_b128 v[196:199], v184 offset:1024
	ds_read_b128 v[200:203], v184 offset:2048
	ds_read_b128 v[204:207], v184 offset:3072
	ds_read_b128 v[208:211], v184 offset:4096
	ds_read_b128 v[212:215], v184 offset:5120
	ds_read_b128 v[216:219], v184 offset:6144
	ds_read_b128 v[220:223], v184 offset:7168
	global_load_lds_dwordx4 v[224:225], off
	v_lshl_add_u64 v[224:225], s[34:35], 0, v[172:173]
	s_add_i32 m0, s39, 0xe000
	s_nop 0
	global_load_lds_dwordx4 v[224:225], off
	s_waitcnt vmcnt(8)
	s_waitcnt lgkmcnt(0)
	s_barrier
	s_setprio 1
	s_waitcnt lgkmcnt(0)
	v_mfma_f32_16x16x32_bf16 v[150:153], v[94:97], v[192:195], v[150:153]
	v_mfma_f32_16x16x32_bf16 v[146:149], v[106:109], v[192:195], v[146:149]
	v_mfma_f32_16x16x32_bf16 v[134:137], v[94:97], v[200:203], v[134:137]
	v_mfma_f32_16x16x32_bf16 v[130:133], v[106:109], v[200:203], v[130:133]
	v_mfma_f32_16x16x32_bf16 v[98:101], v[94:97], v[208:211], v[98:101]
	v_mfma_f32_16x16x32_bf16 v[90:93], v[106:109], v[208:211], v[90:93]
	v_mfma_f32_16x16x32_bf16 v[78:81], v[94:97], v[216:219], v[78:81]
	v_mfma_f32_16x16x32_bf16 v[74:77], v[106:109], v[216:219], v[74:77]
	v_mfma_f32_16x16x32_bf16 v[150:153], v[102:105], v[196:199], v[150:153]
	v_mfma_f32_16x16x32_bf16 v[146:149], v[110:113], v[196:199], v[146:149]
	v_mfma_f32_16x16x32_bf16 v[134:137], v[102:105], v[204:207], v[134:137]
	v_mfma_f32_16x16x32_bf16 v[130:133], v[110:113], v[204:207], v[130:133]
	v_mfma_f32_16x16x32_bf16 v[98:101], v[102:105], v[212:215], v[98:101]
	v_mfma_f32_16x16x32_bf16 v[90:93], v[110:113], v[212:215], v[90:93]
	v_mfma_f32_16x16x32_bf16 v[78:81], v[102:105], v[220:223], v[78:81]
	v_mfma_f32_16x16x32_bf16 v[74:77], v[110:113], v[220:223], v[74:77]
	s_setprio 0
	s_setprio 1
	v_mfma_f32_16x16x32_bf16 v[142:145], v[118:121], v[192:195], v[142:145]
	v_mfma_f32_16x16x32_bf16 v[138:141], v[178:181], v[192:195], v[138:141]
	v_mfma_f32_16x16x32_bf16 v[122:125], v[118:121], v[200:203], v[122:125]
	v_mfma_f32_16x16x32_bf16 v[114:117], v[178:181], v[200:203], v[114:117]
	v_mfma_f32_16x16x32_bf16 v[86:89], v[118:121], v[208:211], v[86:89]
	v_mfma_f32_16x16x32_bf16 v[82:85], v[178:181], v[208:211], v[82:85]
	v_mfma_f32_16x16x32_bf16 v[70:73], v[118:121], v[216:219], v[70:73]
	v_mfma_f32_16x16x32_bf16 v[66:69], v[178:181], v[216:219], v[66:69]
	v_mfma_f32_16x16x32_bf16 v[142:145], v[126:129], v[196:199], v[142:145]
	v_mfma_f32_16x16x32_bf16 v[138:141], v[188:191], v[196:199], v[138:141]
	v_mfma_f32_16x16x32_bf16 v[122:125], v[126:129], v[204:207], v[122:125]
	v_mfma_f32_16x16x32_bf16 v[114:117], v[188:191], v[204:207], v[114:117]
	v_mfma_f32_16x16x32_bf16 v[86:89], v[126:129], v[212:215], v[86:89]
	v_mfma_f32_16x16x32_bf16 v[82:85], v[188:191], v[212:215], v[82:85]
	v_mfma_f32_16x16x32_bf16 v[70:73], v[126:129], v[220:223], v[70:73]
	v_mfma_f32_16x16x32_bf16 v[66:69], v[188:191], v[220:223], v[66:69]
	s_setprio 0
	s_barrier
	s_add_i32 s68, s62, s38
	v_lshl_add_u64 v[224:225], s[4:5], 0, v[156:157]
	s_mov_b32 m0, s68
	ds_read_b128 v[192:195], v184 offset:16384
	ds_read_b128 v[196:199], v184 offset:17408
	ds_read_b128 v[200:203], v184 offset:18432
	ds_read_b128 v[204:207], v184 offset:19456
	ds_read_b128 v[208:211], v184 offset:20480
	ds_read_b128 v[212:215], v184 offset:21504
	ds_read_b128 v[216:219], v184 offset:22528
	ds_read_b128 v[220:223], v184 offset:23552
	global_load_lds_dwordx4 v[224:225], off
	s_add_i32 m0, s68, 0x2000
	s_add_u32 s68, s4, 0x80000
	v_lshl_add_u64 v[226:227], s[4:5], 0, v[160:161]
	s_addc_u32 s69, s5, 0
	s_add_i32 s70, s63, s38
	global_load_lds_dwordx4 v[226:227], off
	v_lshl_add_u64 v[228:229], s[68:69], 0, v[156:157]
	s_mov_b32 m0, s70
	v_lshl_add_u64 v[230:231], s[36:37], 0, v[158:159]
	global_load_lds_dwordx4 v[228:229], off
	v_lshl_add_u64 v[228:229], s[68:69], 0, v[160:161]
	s_add_i32 m0, s70, 0x2000
	s_nop 0
	global_load_lds_dwordx4 v[228:229], off
	v_lshl_add_u64 v[228:229], s[36:37], 0, v[154:155]
	s_mov_b32 m0, s39
	s_nop 0
	global_load_lds_dwordx4 v[228:229], off
	s_mov_b32 m0, s40
	s_nop 0
	global_load_lds_dwordx4 v[230:231], off
	s_waitcnt vmcnt(8)
	s_waitcnt lgkmcnt(0)
	s_barrier
	s_setprio 1
	s_waitcnt lgkmcnt(0)
	v_mfma_f32_16x16x32_bf16 v[62:65], v[94:97], v[192:195], v[62:65]
	v_mfma_f32_16x16x32_bf16 v[58:61], v[106:109], v[192:195], v[58:61]
	v_mfma_f32_16x16x32_bf16 v[46:49], v[94:97], v[200:203], v[46:49]
	v_mfma_f32_16x16x32_bf16 v[42:45], v[106:109], v[200:203], v[42:45]
	v_mfma_f32_16x16x32_bf16 v[30:33], v[94:97], v[208:211], v[30:33]
	v_mfma_f32_16x16x32_bf16 v[26:29], v[106:109], v[208:211], v[26:29]
	v_mfma_f32_16x16x32_bf16 v[14:17], v[94:97], v[216:219], v[14:17]
	v_mfma_f32_16x16x32_bf16 v[10:13], v[106:109], v[216:219], v[10:13]
	v_mfma_f32_16x16x32_bf16 v[62:65], v[102:105], v[196:199], v[62:65]
	v_mfma_f32_16x16x32_bf16 v[58:61], v[110:113], v[196:199], v[58:61]
	v_mfma_f32_16x16x32_bf16 v[46:49], v[102:105], v[204:207], v[46:49]
	v_mfma_f32_16x16x32_bf16 v[42:45], v[110:113], v[204:207], v[42:45]
	v_mfma_f32_16x16x32_bf16 v[30:33], v[102:105], v[212:215], v[30:33]
	v_mfma_f32_16x16x32_bf16 v[26:29], v[110:113], v[212:215], v[26:29]
	v_mfma_f32_16x16x32_bf16 v[14:17], v[102:105], v[220:223], v[14:17]
	v_mfma_f32_16x16x32_bf16 v[10:13], v[110:113], v[220:223], v[10:13]
	s_setprio 0
	s_setprio 1
	v_mfma_f32_16x16x32_bf16 v[54:57], v[118:121], v[192:195], v[54:57]
	v_mfma_f32_16x16x32_bf16 v[50:53], v[178:181], v[192:195], v[50:53]
	v_mfma_f32_16x16x32_bf16 v[38:41], v[118:121], v[200:203], v[38:41]
	v_mfma_f32_16x16x32_bf16 v[34:37], v[178:181], v[200:203], v[34:37]
	v_mfma_f32_16x16x32_bf16 v[22:25], v[118:121], v[208:211], v[22:25]
	v_mfma_f32_16x16x32_bf16 v[18:21], v[178:181], v[208:211], v[18:21]
	v_mfma_f32_16x16x32_bf16 v[6:9], v[118:121], v[216:219], v[6:9]
	v_mfma_f32_16x16x32_bf16 v[2:5], v[178:181], v[216:219], v[2:5]
	v_mfma_f32_16x16x32_bf16 v[54:57], v[126:129], v[196:199], v[54:57]
	v_mfma_f32_16x16x32_bf16 v[50:53], v[188:191], v[196:199], v[50:53]
	v_mfma_f32_16x16x32_bf16 v[38:41], v[126:129], v[204:207], v[38:41]
	v_mfma_f32_16x16x32_bf16 v[34:37], v[188:191], v[204:207], v[34:37]
	v_mfma_f32_16x16x32_bf16 v[22:25], v[126:129], v[212:215], v[22:25]
	v_mfma_f32_16x16x32_bf16 v[18:21], v[188:191], v[212:215], v[18:21]
	v_mfma_f32_16x16x32_bf16 v[6:9], v[126:129], v[220:223], v[6:9]
	v_mfma_f32_16x16x32_bf16 v[2:5], v[188:191], v[220:223], v[2:5]
	s_setprio 0
	s_barrier
	s_add_i32 s68, 0, 0x18000
	s_add_i32 s69, 0, 0x1c000
	v_add_u32_e32 v110, s68, v167
	v_add_u32_e32 v187, s69, v167
	ds_read_b128 v[94:97], v110
	ds_read_b128 v[102:105], v110 offset:1024
	ds_read_b128 v[106:109], v110 offset:2048
	ds_read_b128 v[110:113], v110 offset:3072
	ds_read_b128 v[118:121], v187
	ds_read_b128 v[126:129], v187 offset:1024
	ds_read_b128 v[178:181], v187 offset:2048
	ds_read_b128 v[188:191], v187 offset:3072
	s_add_u32 s36, s36, 0x80000
	s_addc_u32 s37, s37, 0
	s_mov_b32 m0, s41
	v_lshl_add_u64 v[232:233], s[36:37], 0, v[154:155]
	ds_read_b128 v[192:195], v184 offset:32768
	ds_read_b128 v[196:199], v184 offset:33792
	ds_read_b128 v[200:203], v184 offset:34816
	ds_read_b128 v[204:207], v184 offset:35840
	ds_read_b128 v[208:211], v184 offset:36864
	ds_read_b128 v[212:215], v184 offset:37888
	ds_read_b128 v[216:219], v184 offset:38912
	ds_read_b128 v[220:223], v184 offset:39936
	global_load_lds_dwordx4 v[232:233], off
	v_lshl_add_u64 v[232:233], s[36:37], 0, v[158:159]
	s_mov_b32 m0, s42
	s_nop 0
	global_load_lds_dwordx4 v[232:233], off
	s_waitcnt vmcnt(8)
	s_waitcnt lgkmcnt(0)
	s_barrier
	s_setprio 1
	s_waitcnt lgkmcnt(0)
	v_mfma_f32_16x16x32_bf16 v[150:153], v[94:97], v[192:195], v[150:153]
	v_mfma_f32_16x16x32_bf16 v[146:149], v[106:109], v[192:195], v[146:149]
	v_mfma_f32_16x16x32_bf16 v[134:137], v[94:97], v[200:203], v[134:137]
	v_mfma_f32_16x16x32_bf16 v[130:133], v[106:109], v[200:203], v[130:133]
	v_mfma_f32_16x16x32_bf16 v[98:101], v[94:97], v[208:211], v[98:101]
	v_mfma_f32_16x16x32_bf16 v[90:93], v[106:109], v[208:211], v[90:93]
	v_mfma_f32_16x16x32_bf16 v[78:81], v[94:97], v[216:219], v[78:81]
	v_mfma_f32_16x16x32_bf16 v[74:77], v[106:109], v[216:219], v[74:77]
	v_mfma_f32_16x16x32_bf16 v[150:153], v[102:105], v[196:199], v[150:153]
	v_mfma_f32_16x16x32_bf16 v[146:149], v[110:113], v[196:199], v[146:149]
	v_mfma_f32_16x16x32_bf16 v[134:137], v[102:105], v[204:207], v[134:137]
	v_mfma_f32_16x16x32_bf16 v[130:133], v[110:113], v[204:207], v[130:133]
	v_mfma_f32_16x16x32_bf16 v[98:101], v[102:105], v[212:215], v[98:101]
	v_mfma_f32_16x16x32_bf16 v[90:93], v[110:113], v[212:215], v[90:93]
	v_mfma_f32_16x16x32_bf16 v[78:81], v[102:105], v[220:223], v[78:81]
	v_mfma_f32_16x16x32_bf16 v[74:77], v[110:113], v[220:223], v[74:77]
	s_setprio 0
	s_setprio 1
	v_mfma_f32_16x16x32_bf16 v[142:145], v[118:121], v[192:195], v[142:145]
	v_mfma_f32_16x16x32_bf16 v[138:141], v[178:181], v[192:195], v[138:141]
	v_mfma_f32_16x16x32_bf16 v[122:125], v[118:121], v[200:203], v[122:125]
	v_mfma_f32_16x16x32_bf16 v[114:117], v[178:181], v[200:203], v[114:117]
	v_mfma_f32_16x16x32_bf16 v[86:89], v[118:121], v[208:211], v[86:89]
	v_mfma_f32_16x16x32_bf16 v[82:85], v[178:181], v[208:211], v[82:85]
	v_mfma_f32_16x16x32_bf16 v[70:73], v[118:121], v[216:219], v[70:73]
	v_mfma_f32_16x16x32_bf16 v[66:69], v[178:181], v[216:219], v[66:69]
	v_mfma_f32_16x16x32_bf16 v[142:145], v[126:129], v[196:199], v[142:145]
	v_mfma_f32_16x16x32_bf16 v[138:141], v[188:191], v[196:199], v[138:141]
	v_mfma_f32_16x16x32_bf16 v[122:125], v[126:129], v[204:207], v[122:125]
	v_mfma_f32_16x16x32_bf16 v[114:117], v[188:191], v[204:207], v[114:117]
	v_mfma_f32_16x16x32_bf16 v[86:89], v[126:129], v[212:215], v[86:89]
	v_mfma_f32_16x16x32_bf16 v[82:85], v[188:191], v[212:215], v[82:85]
	v_mfma_f32_16x16x32_bf16 v[70:73], v[126:129], v[220:223], v[70:73]
	v_mfma_f32_16x16x32_bf16 v[66:69], v[188:191], v[220:223], v[66:69]
	s_setprio 0
	s_barrier
	s_add_i32 s36, s68, s38
	v_lshl_add_u64 v[224:225], v[224:225], 0, s[16:17]
	s_mov_b32 m0, s36
	ds_read_b128 v[192:195], v184 offset:49152
	ds_read_b128 v[196:199], v184 offset:50176
	ds_read_b128 v[200:203], v184 offset:51200
	ds_read_b128 v[204:207], v184 offset:52224
	ds_read_b128 v[208:211], v184 offset:53248
	ds_read_b128 v[212:215], v184 offset:54272
	ds_read_b128 v[216:219], v184 offset:55296
	ds_read_b128 v[220:223], v184 offset:56320
	global_load_lds_dwordx4 v[224:225], off
	s_add_i32 m0, s36, 0x2000
	s_add_u32 s4, s4, 0x80080
	v_lshl_add_u64 v[224:225], v[226:227], 0, s[16:17]
	s_addc_u32 s5, s5, 0
	s_add_i32 s36, s69, s38
	global_load_lds_dwordx4 v[224:225], off
	v_lshl_add_u64 v[224:225], s[4:5], 0, v[156:157]
	s_mov_b32 m0, s36
	s_nop 0
	global_load_lds_dwordx4 v[224:225], off
	v_lshl_add_u64 v[224:225], s[4:5], 0, v[160:161]
	s_add_i32 m0, s36, 0x2000
	s_nop 0
	global_load_lds_dwordx4 v[224:225], off
	v_lshl_add_u64 v[224:225], v[228:229], 0, s[16:17]
	s_mov_b32 m0, s58
	s_nop 0
	global_load_lds_dwordx4 v[224:225], off
	v_lshl_add_u64 v[224:225], v[230:231], 0, s[16:17]
	s_mov_b32 m0, s59
	s_nop 0
	global_load_lds_dwordx4 v[224:225], off
	s_waitcnt vmcnt(8)
	s_waitcnt lgkmcnt(0)
	s_barrier
	s_setprio 1
	s_waitcnt lgkmcnt(0)
	v_mfma_f32_16x16x32_bf16 v[62:65], v[94:97], v[192:195], v[62:65]
	v_mfma_f32_16x16x32_bf16 v[58:61], v[106:109], v[192:195], v[58:61]
	v_mfma_f32_16x16x32_bf16 v[46:49], v[94:97], v[200:203], v[46:49]
	v_mfma_f32_16x16x32_bf16 v[42:45], v[106:109], v[200:203], v[42:45]
	v_mfma_f32_16x16x32_bf16 v[30:33], v[94:97], v[208:211], v[30:33]
	v_mfma_f32_16x16x32_bf16 v[26:29], v[106:109], v[208:211], v[26:29]
	v_mfma_f32_16x16x32_bf16 v[14:17], v[94:97], v[216:219], v[14:17]
	v_mfma_f32_16x16x32_bf16 v[10:13], v[106:109], v[216:219], v[10:13]
	v_mfma_f32_16x16x32_bf16 v[62:65], v[102:105], v[196:199], v[62:65]
	v_mfma_f32_16x16x32_bf16 v[58:61], v[110:113], v[196:199], v[58:61]
	v_mfma_f32_16x16x32_bf16 v[46:49], v[102:105], v[204:207], v[46:49]
	v_mfma_f32_16x16x32_bf16 v[42:45], v[110:113], v[204:207], v[42:45]
	v_mfma_f32_16x16x32_bf16 v[30:33], v[102:105], v[212:215], v[30:33]
	v_mfma_f32_16x16x32_bf16 v[26:29], v[110:113], v[212:215], v[26:29]
	v_mfma_f32_16x16x32_bf16 v[14:17], v[102:105], v[220:223], v[14:17]
	v_mfma_f32_16x16x32_bf16 v[10:13], v[110:113], v[220:223], v[10:13]
	s_setprio 0
	s_setprio 1
	v_mfma_f32_16x16x32_bf16 v[54:57], v[118:121], v[192:195], v[54:57]
	v_mfma_f32_16x16x32_bf16 v[50:53], v[178:181], v[192:195], v[50:53]
	v_mfma_f32_16x16x32_bf16 v[38:41], v[118:121], v[200:203], v[38:41]
	v_mfma_f32_16x16x32_bf16 v[34:37], v[178:181], v[200:203], v[34:37]
	v_mfma_f32_16x16x32_bf16 v[22:25], v[118:121], v[208:211], v[22:25]
	v_mfma_f32_16x16x32_bf16 v[18:21], v[178:181], v[208:211], v[18:21]
	v_mfma_f32_16x16x32_bf16 v[6:9], v[118:121], v[216:219], v[6:9]
	v_mfma_f32_16x16x32_bf16 v[2:5], v[178:181], v[216:219], v[2:5]
	v_mfma_f32_16x16x32_bf16 v[54:57], v[126:129], v[196:199], v[54:57]
	v_mfma_f32_16x16x32_bf16 v[50:53], v[188:191], v[196:199], v[50:53]
	v_mfma_f32_16x16x32_bf16 v[38:41], v[126:129], v[204:207], v[38:41]
	v_mfma_f32_16x16x32_bf16 v[34:37], v[188:191], v[204:207], v[34:37]
	v_mfma_f32_16x16x32_bf16 v[22:25], v[126:129], v[212:215], v[22:25]
	v_mfma_f32_16x16x32_bf16 v[18:21], v[188:191], v[212:215], v[18:21]
	v_mfma_f32_16x16x32_bf16 v[6:9], v[126:129], v[220:223], v[6:9]
	v_mfma_f32_16x16x32_bf16 v[2:5], v[188:191], v[220:223], v[2:5]
	s_setprio 0
	s_barrier
	s_add_i32 s67, s67, 2
	s_add_u32 s34, s34, 0x100
	s_addc_u32 s35, s35, 0
	s_add_u32 s65, s65, 0x100
	s_addc_u32 s66, s66, 0
	s_cmp_gt_u32 s67, 29
	s_cbranch_scc0 .LBB0_727
	s_and_b64 vcc, exec, s[22:23]
	s_cbranch_vccz .LBB0_730
	s_barrier

.LBB0_813:
	ds_read_b128 v[66:69], v184
	ds_read_b128 v[70:73], v184 offset:1024
	ds_read_b128 v[82:85], v184 offset:2048
	ds_read_b128 v[86:89], v184 offset:3072
	ds_read_b128 v[162:165], v185
	ds_read_b128 v[188:191], v185 offset:1024
	ds_read_b128 v[192:195], v185 offset:2048
	ds_read_b128 v[196:199], v185 offset:3072
	s_add_u32 s4, s36, 0xfff80080
	s_addc_u32 s5, s37, -1
	s_cmp_eq_u32 s77, 60
	s_cselect_b32 s39, s71, s5
	s_cselect_b32 s38, s72, s4
	s_cselect_b32 s5, s73, s76
	s_cselect_b32 s4, s74, s75
	s_mov_b32 m0, s65
	v_lshl_add_u64 v[232:233], s[36:37], 0, v[154:155]
	ds_read_b128 v[200:203], v186
	ds_read_b128 v[204:207], v186 offset:1024
	ds_read_b128 v[208:211], v186 offset:2048
	ds_read_b128 v[212:215], v186 offset:3072
	ds_read_b128 v[216:219], v186 offset:4096
	ds_read_b128 v[220:223], v186 offset:5120
	ds_read_b128 v[224:227], v186 offset:6144
	ds_read_b128 v[228:231], v186 offset:7168
	global_load_lds_dwordx4 v[232:233], off
	v_lshl_add_u64 v[232:233], s[36:37], 0, v[160:161]
	s_add_i32 m0, s53, 0xe000
	s_nop 0
	global_load_lds_dwordx4 v[232:233], off
	s_waitcnt vmcnt(8)
	s_waitcnt lgkmcnt(0)
	s_barrier
	s_setprio 1
	s_waitcnt lgkmcnt(0)
	v_mfma_f32_16x16x32_bf16 v[142:145], v[66:69], v[200:203], v[142:145]
	v_mfma_f32_16x16x32_bf16 v[138:141], v[82:85], v[200:203], v[138:141]
	v_mfma_f32_16x16x32_bf16 v[126:129], v[66:69], v[208:211], v[126:129]
	v_mfma_f32_16x16x32_bf16 v[122:125], v[82:85], v[208:211], v[122:125]
	v_mfma_f32_16x16x32_bf16 v[110:113], v[66:69], v[216:219], v[110:113]
	v_mfma_f32_16x16x32_bf16 v[106:109], v[82:85], v[216:219], v[106:109]
	v_mfma_f32_16x16x32_bf16 v[94:97], v[66:69], v[224:227], v[94:97]
	v_mfma_f32_16x16x32_bf16 v[90:93], v[82:85], v[224:227], v[90:93]
	v_mfma_f32_16x16x32_bf16 v[142:145], v[70:73], v[204:207], v[142:145]
	v_mfma_f32_16x16x32_bf16 v[138:141], v[86:89], v[204:207], v[138:141]
	v_mfma_f32_16x16x32_bf16 v[126:129], v[70:73], v[212:215], v[126:129]
	v_mfma_f32_16x16x32_bf16 v[122:125], v[86:89], v[212:215], v[122:125]
	v_mfma_f32_16x16x32_bf16 v[110:113], v[70:73], v[220:223], v[110:113]
	v_mfma_f32_16x16x32_bf16 v[106:109], v[86:89], v[220:223], v[106:109]
	v_mfma_f32_16x16x32_bf16 v[94:97], v[70:73], v[228:231], v[94:97]
	v_mfma_f32_16x16x32_bf16 v[90:93], v[86:89], v[228:231], v[90:93]
	s_setprio 0
	s_setprio 1
	v_mfma_f32_16x16x32_bf16 v[134:137], v[162:165], v[200:203], v[134:137]
	v_mfma_f32_16x16x32_bf16 v[130:133], v[192:195], v[200:203], v[130:133]
	v_mfma_f32_16x16x32_bf16 v[118:121], v[162:165], v[208:211], v[118:121]
	v_mfma_f32_16x16x32_bf16 v[114:117], v[192:195], v[208:211], v[114:117]
	v_mfma_f32_16x16x32_bf16 v[102:105], v[162:165], v[216:219], v[102:105]
	v_mfma_f32_16x16x32_bf16 v[98:101], v[192:195], v[216:219], v[98:101]
	v_mfma_f32_16x16x32_bf16 v[78:81], v[162:165], v[224:227], v[78:81]
	v_mfma_f32_16x16x32_bf16 v[74:77], v[192:195], v[224:227], v[74:77]
	v_mfma_f32_16x16x32_bf16 v[134:137], v[188:191], v[204:207], v[134:137]
	v_mfma_f32_16x16x32_bf16 v[130:133], v[196:199], v[204:207], v[130:133]
	v_mfma_f32_16x16x32_bf16 v[118:121], v[188:191], v[212:215], v[118:121]
	v_mfma_f32_16x16x32_bf16 v[114:117], v[196:199], v[212:215], v[114:117]
	v_mfma_f32_16x16x32_bf16 v[102:105], v[188:191], v[220:223], v[102:105]
	v_mfma_f32_16x16x32_bf16 v[98:101], v[196:199], v[220:223], v[98:101]
	v_mfma_f32_16x16x32_bf16 v[78:81], v[188:191], v[228:231], v[78:81]
	v_mfma_f32_16x16x32_bf16 v[74:77], v[196:199], v[228:231], v[74:77]
	s_setprio 0
	s_barrier
	s_add_i32 s68, s43, s52
	v_lshl_add_u64 v[232:233], s[4:5], 0, v[150:151]
	s_mov_b32 m0, s68
	ds_read_b128 v[200:203], v186 offset:16384
	ds_read_b128 v[204:207], v186 offset:17408
	ds_read_b128 v[208:211], v186 offset:18432
	ds_read_b128 v[212:215], v186 offset:19456
	ds_read_b128 v[216:219], v186 offset:20480
	ds_read_b128 v[220:223], v186 offset:21504
	ds_read_b128 v[224:227], v186 offset:22528
	ds_read_b128 v[228:231], v186 offset:23552
	global_load_lds_dwordx4 v[232:233], off
	s_add_i32 m0, s68, 0x2000
	s_add_u32 s78, s4, 0x100000
	v_lshl_add_u64 v[234:235], s[4:5], 0, v[152:153]
	s_addc_u32 s79, s5, 0
	s_add_i32 s68, s64, s52
	global_load_lds_dwordx4 v[234:235], off
	v_lshl_add_u64 v[236:237], s[78:79], 0, v[150:151]
	s_mov_b32 m0, s68
	v_lshl_add_u64 v[238:239], s[38:39], 0, v[146:147]
	global_load_lds_dwordx4 v[236:237], off
	v_lshl_add_u64 v[236:237], s[78:79], 0, v[152:153]
	s_add_i32 m0, s68, 0x2000
	s_nop 0
	global_load_lds_dwordx4 v[236:237], off
	v_lshl_add_u64 v[236:237], s[38:39], 0, v[148:149]
	s_mov_b32 m0, s53
	s_nop 0
	global_load_lds_dwordx4 v[236:237], off
	s_mov_b32 m0, s54
	s_nop 0
	global_load_lds_dwordx4 v[238:239], off
	s_waitcnt vmcnt(8)
	s_waitcnt lgkmcnt(0)
	s_barrier
	s_setprio 1
	s_waitcnt lgkmcnt(0)
	v_mfma_f32_16x16x32_bf16 v[62:65], v[66:69], v[200:203], v[62:65]
	v_mfma_f32_16x16x32_bf16 v[58:61], v[82:85], v[200:203], v[58:61]
	v_mfma_f32_16x16x32_bf16 v[46:49], v[66:69], v[208:211], v[46:49]
	v_mfma_f32_16x16x32_bf16 v[42:45], v[82:85], v[208:211], v[42:45]
	v_mfma_f32_16x16x32_bf16 v[30:33], v[66:69], v[216:219], v[30:33]
	v_mfma_f32_16x16x32_bf16 v[26:29], v[82:85], v[216:219], v[26:29]
	v_mfma_f32_16x16x32_bf16 v[14:17], v[66:69], v[224:227], v[14:17]
	v_mfma_f32_16x16x32_bf16 v[10:13], v[82:85], v[224:227], v[10:13]
	v_mfma_f32_16x16x32_bf16 v[62:65], v[70:73], v[204:207], v[62:65]
	v_mfma_f32_16x16x32_bf16 v[58:61], v[86:89], v[204:207], v[58:61]
	v_mfma_f32_16x16x32_bf16 v[46:49], v[70:73], v[212:215], v[46:49]
	v_mfma_f32_16x16x32_bf16 v[42:45], v[86:89], v[212:215], v[42:45]
	v_mfma_f32_16x16x32_bf16 v[30:33], v[70:73], v[220:223], v[30:33]
	v_mfma_f32_16x16x32_bf16 v[26:29], v[86:89], v[220:223], v[26:29]
	v_mfma_f32_16x16x32_bf16 v[14:17], v[70:73], v[228:231], v[14:17]
	v_mfma_f32_16x16x32_bf16 v[10:13], v[86:89], v[228:231], v[10:13]
	s_setprio 0
	s_setprio 1
	v_mfma_f32_16x16x32_bf16 v[54:57], v[162:165], v[200:203], v[54:57]
	v_mfma_f32_16x16x32_bf16 v[50:53], v[192:195], v[200:203], v[50:53]
	v_mfma_f32_16x16x32_bf16 v[38:41], v[162:165], v[208:211], v[38:41]
	v_mfma_f32_16x16x32_bf16 v[34:37], v[192:195], v[208:211], v[34:37]
	v_mfma_f32_16x16x32_bf16 v[22:25], v[162:165], v[216:219], v[22:25]
	v_mfma_f32_16x16x32_bf16 v[18:21], v[192:195], v[216:219], v[18:21]
	v_mfma_f32_16x16x32_bf16 v[6:9], v[162:165], v[224:227], v[6:9]
	v_mfma_f32_16x16x32_bf16 v[2:5], v[192:195], v[224:227], v[2:5]
	v_mfma_f32_16x16x32_bf16 v[54:57], v[188:191], v[204:207], v[54:57]
	v_mfma_f32_16x16x32_bf16 v[50:53], v[196:199], v[204:207], v[50:53]
	v_mfma_f32_16x16x32_bf16 v[38:41], v[188:191], v[212:215], v[38:41]
	v_mfma_f32_16x16x32_bf16 v[34:37], v[196:199], v[212:215], v[34:37]
	v_mfma_f32_16x16x32_bf16 v[22:25], v[188:191], v[220:223], v[22:25]
	v_mfma_f32_16x16x32_bf16 v[18:21], v[196:199], v[220:223], v[18:21]
	v_mfma_f32_16x16x32_bf16 v[6:9], v[188:191], v[228:231], v[6:9]
	v_mfma_f32_16x16x32_bf16 v[2:5], v[196:199], v[228:231], v[2:5]
	s_setprio 0
	s_barrier
	s_add_i32 s68, 0, 0x18000
	s_add_i32 s78, 0, 0x1c000
	v_add_u32_e32 v86, s68, v182
	v_add_u32_e32 v187, s78, v182
	ds_read_b128 v[66:69], v86
	ds_read_b128 v[70:73], v86 offset:1024
	ds_read_b128 v[82:85], v86 offset:2048
	ds_read_b128 v[86:89], v86 offset:3072
	ds_read_b128 v[162:165], v187
	ds_read_b128 v[188:191], v187 offset:1024
	ds_read_b128 v[192:195], v187 offset:2048
	ds_read_b128 v[196:199], v187 offset:3072
	s_add_u32 s38, s38, 0x80000
	s_addc_u32 s39, s39, 0
	s_mov_b32 m0, s55
	v_lshl_add_u64 v[240:241], s[38:39], 0, v[148:149]
	ds_read_b128 v[200:203], v186 offset:32768
	ds_read_b128 v[204:207], v186 offset:33792
	ds_read_b128 v[208:211], v186 offset:34816
	ds_read_b128 v[212:215], v186 offset:35840
	ds_read_b128 v[216:219], v186 offset:36864
	ds_read_b128 v[220:223], v186 offset:37888
	ds_read_b128 v[224:227], v186 offset:38912
	ds_read_b128 v[228:231], v186 offset:39936
	global_load_lds_dwordx4 v[240:241], off
	v_lshl_add_u64 v[240:241], s[38:39], 0, v[146:147]
	s_mov_b32 m0, s56
	s_nop 0
	global_load_lds_dwordx4 v[240:241], off
	s_waitcnt vmcnt(8)
	s_waitcnt lgkmcnt(0)
	s_barrier
	s_setprio 1
	s_waitcnt lgkmcnt(0)
	v_mfma_f32_16x16x32_bf16 v[142:145], v[66:69], v[200:203], v[142:145]
	v_mfma_f32_16x16x32_bf16 v[138:141], v[82:85], v[200:203], v[138:141]
	v_mfma_f32_16x16x32_bf16 v[126:129], v[66:69], v[208:211], v[126:129]
	v_mfma_f32_16x16x32_bf16 v[122:125], v[82:85], v[208:211], v[122:125]
	v_mfma_f32_16x16x32_bf16 v[110:113], v[66:69], v[216:219], v[110:113]
	v_mfma_f32_16x16x32_bf16 v[106:109], v[82:85], v[216:219], v[106:109]
	v_mfma_f32_16x16x32_bf16 v[94:97], v[66:69], v[224:227], v[94:97]
	v_mfma_f32_16x16x32_bf16 v[90:93], v[82:85], v[224:227], v[90:93]
	v_mfma_f32_16x16x32_bf16 v[142:145], v[70:73], v[204:207], v[142:145]
	v_mfma_f32_16x16x32_bf16 v[138:141], v[86:89], v[204:207], v[138:141]
	v_mfma_f32_16x16x32_bf16 v[126:129], v[70:73], v[212:215], v[126:129]
	v_mfma_f32_16x16x32_bf16 v[122:125], v[86:89], v[212:215], v[122:125]
	v_mfma_f32_16x16x32_bf16 v[110:113], v[70:73], v[220:223], v[110:113]
	v_mfma_f32_16x16x32_bf16 v[106:109], v[86:89], v[220:223], v[106:109]
	v_mfma_f32_16x16x32_bf16 v[94:97], v[70:73], v[228:231], v[94:97]
	v_mfma_f32_16x16x32_bf16 v[90:93], v[86:89], v[228:231], v[90:93]
	s_setprio 0
	s_setprio 1
	v_mfma_f32_16x16x32_bf16 v[134:137], v[162:165], v[200:203], v[134:137]
	v_mfma_f32_16x16x32_bf16 v[130:133], v[192:195], v[200:203], v[130:133]
	v_mfma_f32_16x16x32_bf16 v[118:121], v[162:165], v[208:211], v[118:121]
	v_mfma_f32_16x16x32_bf16 v[114:117], v[192:195], v[208:211], v[114:117]
	v_mfma_f32_16x16x32_bf16 v[102:105], v[162:165], v[216:219], v[102:105]
	v_mfma_f32_16x16x32_bf16 v[98:101], v[192:195], v[216:219], v[98:101]
	v_mfma_f32_16x16x32_bf16 v[78:81], v[162:165], v[224:227], v[78:81]
	v_mfma_f32_16x16x32_bf16 v[74:77], v[192:195], v[224:227], v[74:77]
	v_mfma_f32_16x16x32_bf16 v[134:137], v[188:191], v[204:207], v[134:137]
	v_mfma_f32_16x16x32_bf16 v[130:133], v[196:199], v[204:207], v[130:133]
	v_mfma_f32_16x16x32_bf16 v[118:121], v[188:191], v[212:215], v[118:121]
	v_mfma_f32_16x16x32_bf16 v[114:117], v[196:199], v[212:215], v[114:117]
	v_mfma_f32_16x16x32_bf16 v[102:105], v[188:191], v[220:223], v[102:105]
	v_mfma_f32_16x16x32_bf16 v[98:101], v[196:199], v[220:223], v[98:101]
	v_mfma_f32_16x16x32_bf16 v[78:81], v[188:191], v[228:231], v[78:81]
	v_mfma_f32_16x16x32_bf16 v[74:77], v[196:199], v[228:231], v[74:77]
	s_setprio 0
	s_barrier
	s_add_i32 s38, s68, s52
	v_lshl_add_u64 v[232:233], v[232:233], 0, s[14:15]
	s_mov_b32 m0, s38
	ds_read_b128 v[200:203], v186 offset:49152
	ds_read_b128 v[204:207], v186 offset:50176
	ds_read_b128 v[208:211], v186 offset:51200
	ds_read_b128 v[212:215], v186 offset:52224
	ds_read_b128 v[216:219], v186 offset:53248
	ds_read_b128 v[220:223], v186 offset:54272
	ds_read_b128 v[224:227], v186 offset:55296
	ds_read_b128 v[228:231], v186 offset:56320
	global_load_lds_dwordx4 v[232:233], off
	s_add_i32 m0, s38, 0x2000
	s_add_u32 s4, s4, 0x100080
	v_lshl_add_u64 v[232:233], v[234:235], 0, s[14:15]
	s_addc_u32 s5, s5, 0
	s_add_i32 s38, s78, s52
	global_load_lds_dwordx4 v[232:233], off
	v_lshl_add_u64 v[232:233], s[4:5], 0, v[150:151]
	s_mov_b32 m0, s38
	s_nop 0
	global_load_lds_dwordx4 v[232:233], off
	v_lshl_add_u64 v[232:233], s[4:5], 0, v[152:153]
	s_add_i32 m0, s38, 0x2000
	s_nop 0
	global_load_lds_dwordx4 v[232:233], off
	v_lshl_add_u64 v[232:233], v[236:237], 0, s[14:15]
	s_mov_b32 m0, s62
	s_nop 0
	global_load_lds_dwordx4 v[232:233], off
	v_lshl_add_u64 v[232:233], v[238:239], 0, s[14:15]
	s_mov_b32 m0, s63
	s_nop 0
	global_load_lds_dwordx4 v[232:233], off
	s_waitcnt vmcnt(8)
	s_waitcnt lgkmcnt(0)
	s_barrier
	s_setprio 1
	s_waitcnt lgkmcnt(0)
	v_mfma_f32_16x16x32_bf16 v[62:65], v[66:69], v[200:203], v[62:65]
	v_mfma_f32_16x16x32_bf16 v[58:61], v[82:85], v[200:203], v[58:61]
	v_mfma_f32_16x16x32_bf16 v[46:49], v[66:69], v[208:211], v[46:49]
	v_mfma_f32_16x16x32_bf16 v[42:45], v[82:85], v[208:211], v[42:45]
	v_mfma_f32_16x16x32_bf16 v[30:33], v[66:69], v[216:219], v[30:33]
	v_mfma_f32_16x16x32_bf16 v[26:29], v[82:85], v[216:219], v[26:29]
	v_mfma_f32_16x16x32_bf16 v[14:17], v[66:69], v[224:227], v[14:17]
	v_mfma_f32_16x16x32_bf16 v[10:13], v[82:85], v[224:227], v[10:13]
	v_mfma_f32_16x16x32_bf16 v[62:65], v[70:73], v[204:207], v[62:65]
	v_mfma_f32_16x16x32_bf16 v[58:61], v[86:89], v[204:207], v[58:61]
	v_mfma_f32_16x16x32_bf16 v[46:49], v[70:73], v[212:215], v[46:49]
	v_mfma_f32_16x16x32_bf16 v[42:45], v[86:89], v[212:215], v[42:45]
	v_mfma_f32_16x16x32_bf16 v[30:33], v[70:73], v[220:223], v[30:33]
	v_mfma_f32_16x16x32_bf16 v[26:29], v[86:89], v[220:223], v[26:29]
	v_mfma_f32_16x16x32_bf16 v[14:17], v[70:73], v[228:231], v[14:17]
	v_mfma_f32_16x16x32_bf16 v[10:13], v[86:89], v[228:231], v[10:13]
	s_setprio 0
	s_setprio 1
	v_mfma_f32_16x16x32_bf16 v[54:57], v[162:165], v[200:203], v[54:57]
	v_mfma_f32_16x16x32_bf16 v[50:53], v[192:195], v[200:203], v[50:53]
	v_mfma_f32_16x16x32_bf16 v[38:41], v[162:165], v[208:211], v[38:41]
	v_mfma_f32_16x16x32_bf16 v[34:37], v[192:195], v[208:211], v[34:37]
	v_mfma_f32_16x16x32_bf16 v[22:25], v[162:165], v[216:219], v[22:25]
	v_mfma_f32_16x16x32_bf16 v[18:21], v[192:195], v[216:219], v[18:21]
	v_mfma_f32_16x16x32_bf16 v[6:9], v[162:165], v[224:227], v[6:9]
	v_mfma_f32_16x16x32_bf16 v[2:5], v[192:195], v[224:227], v[2:5]
	v_mfma_f32_16x16x32_bf16 v[54:57], v[188:191], v[204:207], v[54:57]
	v_mfma_f32_16x16x32_bf16 v[50:53], v[196:199], v[204:207], v[50:53]
	v_mfma_f32_16x16x32_bf16 v[38:41], v[188:191], v[212:215], v[38:41]
	v_mfma_f32_16x16x32_bf16 v[34:37], v[196:199], v[212:215], v[34:37]
	v_mfma_f32_16x16x32_bf16 v[22:25], v[188:191], v[220:223], v[22:25]
	v_mfma_f32_16x16x32_bf16 v[18:21], v[196:199], v[220:223], v[18:21]
	v_mfma_f32_16x16x32_bf16 v[6:9], v[188:191], v[228:231], v[6:9]
	v_mfma_f32_16x16x32_bf16 v[2:5], v[196:199], v[228:231], v[2:5]
	s_setprio 0
	s_barrier
	s_add_i32 s77, s77, 2
	s_add_u32 s36, s36, 0x100
	s_addc_u32 s37, s37, 0
	s_add_u32 s75, s75, 0x100
	s_addc_u32 s76, s76, 0
	s_cmp_gt_u32 s77, 61
	s_cbranch_scc0 .LBB0_813
	s_and_b64 vcc, exec, s[16:17]
	s_cbranch_vccz .LBB0_816
	s_barrier

.LBB0_823:
	s_mov_b64 s[30:31], s[8:9]
	s_mov_b32 s8, s63
	s_ashr_i32 s63, s59, 5
	s_cmp_lt_i32 s59, 64
	s_mov_b64 s[34:35], s[4:5]
	s_cselect_b64 s[4:5], -1, 0
	s_and_b64 s[4:5], s[4:5], exec
	s_cselect_b32 s4, s63, s8
	s_ashr_i32 s5, s4, 31
	s_lshl_b64 s[4:5], s[4:5], 17
	s_add_u32 s4, s33, s4
	s_addc_u32 s5, s36, s5
	s_cmp_lt_i32 s59, 64
	s_cselect_b64 s[8:9], -1, 0
	s_and_b64 s[8:9], s[8:9], exec
	s_cselect_b32 s8, s59, s26
	s_cselect_b32 s26, s4, s34
	s_cselect_b32 s27, s5, s35
	s_ashr_i32 s9, s8, 31
	ds_read_b128 v[2:5], v78
	ds_read_b128 v[6:9], v78 offset:1024
	ds_read_b128 v[10:13], v78 offset:2048
	ds_read_b128 v[14:17], v78 offset:3072
	s_lshl_b64 s[8:9], s[8:9], 17
	s_add_u32 s8, s0, s8
	s_addc_u32 s9, s1, s9
	s_cmp_lt_i32 s59, 64
	s_cselect_b64 s[24:25], -1, 0
	s_and_b64 s[28:29], s[24:25], exec
	s_cselect_b32 s29, s9, s31
	s_cselect_b32 s28, s8, s30
	s_add_u32 s64, s30, 0x10080
	s_addc_u32 s65, s31, 0
	s_mov_b32 m0, s57
	v_lshl_add_u64 v[50:51], s[64:65], 0, v[72:73]
	ds_read_b128 v[18:21], v79
	ds_read_b128 v[22:25], v79 offset:1024
	ds_read_b128 v[26:29], v79 offset:2048
	ds_read_b128 v[30:33], v79 offset:3072
	ds_read_b128 v[34:37], v79 offset:4096
	ds_read_b128 v[38:41], v79 offset:5120
	ds_read_b128 v[42:45], v79 offset:6144
	ds_read_b128 v[46:49], v79 offset:7168
	global_load_lds_dwordx4 v[50:51], off
	v_lshl_add_u64 v[50:51], s[64:65], 0, v[68:69]
	s_mov_b32 m0, s58
	s_nop 0
	global_load_lds_dwordx4 v[50:51], off
	s_waitcnt vmcnt(8)
	s_waitcnt lgkmcnt(0)
	s_barrier
	s_setprio 1
	s_waitcnt lgkmcnt(0)
	v_mfma_f32_16x16x32_bf16 v[50:53], v[2:5], v[18:21], 0
	v_mfma_f32_16x16x32_bf16 v[18:21], v[10:13], v[18:21], 0
	v_mfma_f32_16x16x32_bf16 v[50:53], v[6:9], v[22:25], v[50:53]
	v_mfma_f32_16x16x32_bf16 v[18:21], v[14:17], v[22:25], v[18:21]
	v_mfma_f32_16x16x32_bf16 v[22:25], v[2:5], v[26:29], 0
	v_mfma_f32_16x16x32_bf16 v[26:29], v[10:13], v[26:29], 0
	v_mfma_f32_16x16x32_bf16 v[22:25], v[6:9], v[30:33], v[22:25]
	v_mfma_f32_16x16x32_bf16 v[26:29], v[14:17], v[30:33], v[26:29]
	v_mfma_f32_16x16x32_bf16 v[30:33], v[2:5], v[34:37], 0
	v_mfma_f32_16x16x32_bf16 v[34:37], v[10:13], v[34:37], 0
	v_mfma_f32_16x16x32_bf16 v[30:33], v[6:9], v[38:41], v[30:33]
	v_mfma_f32_16x16x32_bf16 v[34:37], v[14:17], v[38:41], v[34:37]
	v_mfma_f32_16x16x32_bf16 v[38:41], v[2:5], v[42:45], 0
	v_mfma_f32_16x16x32_bf16 v[42:45], v[10:13], v[42:45], 0
	v_mfma_f32_16x16x32_bf16 v[38:41], v[6:9], v[46:49], v[38:41]
	v_mfma_f32_16x16x32_bf16 v[42:45], v[14:17], v[46:49], v[42:45]
	s_setprio 0
	s_setprio 1
	s_setprio 0
	s_barrier
	v_lshl_add_u64 v[130:131], s[34:35], 0, v[70:71]
	s_mov_b32 m0, s43
	v_lshl_add_u64 v[98:99], v[130:131], 0, s[14:15]
	v_lshl_add_u64 v[132:133], s[34:35], 0, v[66:67]
	s_add_u32 s64, s34, 0x10100
	ds_read_b128 v[46:49], v79 offset:16384
	ds_read_b128 v[54:57], v79 offset:17408
	ds_read_b128 v[58:61], v79 offset:18432
	ds_read_b128 v[62:65], v79 offset:19456
	ds_read_b128 v[82:85], v79 offset:20480
	ds_read_b128 v[86:89], v79 offset:21504
	ds_read_b128 v[90:93], v79 offset:22528
	ds_read_b128 v[94:97], v79 offset:23552
	global_load_lds_dwordx4 v[98:99], off
	v_lshl_add_u64 v[98:99], v[132:133], 0, s[14:15]
	s_mov_b32 m0, s60
	s_addc_u32 s65, s35, 0
	global_load_lds_dwordx4 v[98:99], off
	v_lshl_add_u64 v[98:99], s[64:65], 0, v[70:71]
	s_mov_b32 m0, s38
	v_lshl_add_u64 v[134:135], s[30:31], 0, v[72:73]
	global_load_lds_dwordx4 v[98:99], off
	v_lshl_add_u64 v[98:99], s[64:65], 0, v[66:67]
	s_mov_b32 m0, s39
	v_lshl_add_u64 v[136:137], s[30:31], 0, v[68:69]
	global_load_lds_dwordx4 v[98:99], off
	v_lshl_add_u64 v[98:99], v[134:135], 0, s[14:15]
	s_mov_b32 m0, s37
	s_nop 0
	global_load_lds_dwordx4 v[98:99], off
	v_lshl_add_u64 v[98:99], v[136:137], 0, s[14:15]
	s_mov_b32 m0, s40
	s_nop 0
	global_load_lds_dwordx4 v[98:99], off
	s_waitcnt vmcnt(8)
	s_waitcnt lgkmcnt(0)
	s_barrier
	s_setprio 1
	s_waitcnt lgkmcnt(0)
	v_mfma_f32_16x16x32_bf16 v[98:101], v[2:5], v[46:49], 0
	v_mfma_f32_16x16x32_bf16 v[46:49], v[10:13], v[46:49], 0
	v_mfma_f32_16x16x32_bf16 v[98:101], v[6:9], v[54:57], v[98:101]
	v_mfma_f32_16x16x32_bf16 v[46:49], v[14:17], v[54:57], v[46:49]
	v_mfma_f32_16x16x32_bf16 v[54:57], v[2:5], v[58:61], 0
	v_mfma_f32_16x16x32_bf16 v[58:61], v[10:13], v[58:61], 0
	v_mfma_f32_16x16x32_bf16 v[54:57], v[6:9], v[62:65], v[54:57]
	v_mfma_f32_16x16x32_bf16 v[58:61], v[14:17], v[62:65], v[58:61]
	v_mfma_f32_16x16x32_bf16 v[62:65], v[2:5], v[82:85], 0
	v_mfma_f32_16x16x32_bf16 v[2:5], v[2:5], v[90:93], 0
	v_mfma_f32_16x16x32_bf16 v[62:65], v[6:9], v[86:89], v[62:65]
	v_mfma_f32_16x16x32_bf16 v[2:5], v[6:9], v[94:97], v[2:5]
	v_mfma_f32_16x16x32_bf16 v[6:9], v[10:13], v[90:93], 0
	v_mfma_f32_16x16x32_bf16 v[82:85], v[10:13], v[82:85], 0
	v_mfma_f32_16x16x32_bf16 v[6:9], v[14:17], v[94:97], v[6:9]
	v_mfma_f32_16x16x32_bf16 v[82:85], v[14:17], v[86:89], v[82:85]
	s_setprio 0
	s_setprio 1
	s_setprio 0
	s_barrier
	ds_read_b128 v[10:13], v80
	ds_read_b128 v[14:17], v80 offset:1024
	ds_read_b128 v[86:89], v80 offset:2048
	ds_read_b128 v[90:93], v80 offset:3072
	s_add_u32 s64, s30, 0x10100
	s_addc_u32 s65, s31, 0
	s_mov_b32 m0, s41
	v_lshl_add_u64 v[138:139], s[64:65], 0, v[72:73]
	ds_read_b128 v[94:97], v79 offset:32768
	ds_read_b128 v[102:105], v79 offset:33792
	ds_read_b128 v[106:109], v79 offset:34816
	ds_read_b128 v[110:113], v79 offset:35840
	ds_read_b128 v[114:117], v79 offset:36864
	ds_read_b128 v[118:121], v79 offset:37888
	ds_read_b128 v[122:125], v79 offset:38912
	ds_read_b128 v[126:129], v79 offset:39936
	global_load_lds_dwordx4 v[138:139], off
	v_lshl_add_u64 v[138:139], s[64:65], 0, v[68:69]
	s_mov_b32 m0, s42
	s_nop 0
	global_load_lds_dwordx4 v[138:139], off
	s_waitcnt vmcnt(8)
	s_waitcnt lgkmcnt(0)
	s_barrier
	s_setprio 1
	s_waitcnt lgkmcnt(0)
	v_mfma_f32_16x16x32_bf16 v[50:53], v[10:13], v[94:97], v[50:53]
	v_mfma_f32_16x16x32_bf16 v[18:21], v[86:89], v[94:97], v[18:21]
	v_mfma_f32_16x16x32_bf16 v[22:25], v[10:13], v[106:109], v[22:25]
	v_mfma_f32_16x16x32_bf16 v[26:29], v[86:89], v[106:109], v[26:29]
	v_mfma_f32_16x16x32_bf16 v[30:33], v[10:13], v[114:117], v[30:33]
	v_mfma_f32_16x16x32_bf16 v[34:37], v[86:89], v[114:117], v[34:37]
	v_mfma_f32_16x16x32_bf16 v[38:41], v[10:13], v[122:125], v[38:41]
	v_mfma_f32_16x16x32_bf16 v[42:45], v[86:89], v[122:125], v[42:45]
	v_mfma_f32_16x16x32_bf16 v[50:53], v[14:17], v[102:105], v[50:53]
	v_mfma_f32_16x16x32_bf16 v[18:21], v[90:93], v[102:105], v[18:21]
	v_mfma_f32_16x16x32_bf16 v[22:25], v[14:17], v[110:113], v[22:25]
	v_mfma_f32_16x16x32_bf16 v[26:29], v[90:93], v[110:113], v[26:29]
	v_mfma_f32_16x16x32_bf16 v[30:33], v[14:17], v[118:121], v[30:33]
	v_mfma_f32_16x16x32_bf16 v[34:37], v[90:93], v[118:121], v[34:37]
	v_mfma_f32_16x16x32_bf16 v[38:41], v[14:17], v[126:129], v[38:41]
	v_mfma_f32_16x16x32_bf16 v[42:45], v[90:93], v[126:129], v[42:45]
	s_setprio 0
	s_setprio 1
	s_setprio 0
	s_barrier
	s_mov_b32 m0, s61
	v_lshl_add_u64 v[130:131], v[130:131], 0, s[16:17]
	s_add_u32 s34, s34, 0x10180
	ds_read_b128 v[94:97], v79 offset:49152
	ds_read_b128 v[102:105], v79 offset:50176
	ds_read_b128 v[106:109], v79 offset:51200
	ds_read_b128 v[110:113], v79 offset:52224
	ds_read_b128 v[114:117], v79 offset:53248
	ds_read_b128 v[118:121], v79 offset:54272
	ds_read_b128 v[122:125], v79 offset:55296
	ds_read_b128 v[126:129], v79 offset:56320
	global_load_lds_dwordx4 v[130:131], off
	v_lshl_add_u64 v[130:131], v[132:133], 0, s[16:17]
	s_mov_b32 m0, s62
	s_addc_u32 s35, s35, 0
	global_load_lds_dwordx4 v[130:131], off
	v_lshl_add_u64 v[130:131], s[34:35], 0, v[70:71]
	s_mov_b32 m0, s55
	s_nop 0
	global_load_lds_dwordx4 v[130:131], off
	v_lshl_add_u64 v[130:131], s[34:35], 0, v[66:67]
	s_mov_b32 m0, s56
	s_nop 0
	global_load_lds_dwordx4 v[130:131], off
	v_lshl_add_u64 v[130:131], v[134:135], 0, s[16:17]
	s_mov_b32 m0, s53
	s_nop 0
	global_load_lds_dwordx4 v[130:131], off
	v_lshl_add_u64 v[130:131], v[136:137], 0, s[16:17]
	s_mov_b32 m0, s54
	s_nop 0
	global_load_lds_dwordx4 v[130:131], off
	s_waitcnt vmcnt(8)
	s_waitcnt lgkmcnt(0)
	s_barrier
	s_setprio 1
	s_waitcnt lgkmcnt(0)
	v_mfma_f32_16x16x32_bf16 v[46:49], v[86:89], v[94:97], v[46:49]
	v_mfma_f32_16x16x32_bf16 v[54:57], v[10:13], v[106:109], v[54:57]
	v_mfma_f32_16x16x32_bf16 v[58:61], v[86:89], v[106:109], v[58:61]
	v_mfma_f32_16x16x32_bf16 v[62:65], v[10:13], v[114:117], v[62:65]
	v_mfma_f32_16x16x32_bf16 v[2:5], v[10:13], v[122:125], v[2:5]
	v_mfma_f32_16x16x32_bf16 v[6:9], v[86:89], v[122:125], v[6:9]
	v_mfma_f32_16x16x32_bf16 v[98:101], v[10:13], v[94:97], v[98:101]
	v_mfma_f32_16x16x32_bf16 v[46:49], v[90:93], v[102:105], v[46:49]
	v_mfma_f32_16x16x32_bf16 v[54:57], v[14:17], v[110:113], v[54:57]
	v_mfma_f32_16x16x32_bf16 v[58:61], v[90:93], v[110:113], v[58:61]
	v_mfma_f32_16x16x32_bf16 v[62:65], v[14:17], v[118:121], v[62:65]
	v_mfma_f32_16x16x32_bf16 v[82:85], v[86:89], v[114:117], v[82:85]
	v_mfma_f32_16x16x32_bf16 v[2:5], v[14:17], v[126:129], v[2:5]
	v_mfma_f32_16x16x32_bf16 v[6:9], v[90:93], v[126:129], v[6:9]
	v_mfma_f32_16x16x32_bf16 v[98:101], v[14:17], v[102:105], v[98:101]
	v_mfma_f32_16x16x32_bf16 v[82:85], v[90:93], v[118:121], v[82:85]
	s_setprio 0
	s_setprio 1
	s_setprio 0
	s_barrier
	ds_read_b128 v[10:13], v78
	ds_read_b128 v[14:17], v78 offset:1024
	ds_read_b128 v[86:89], v78 offset:2048
	ds_read_b128 v[90:93], v78 offset:3072
	s_add_u32 s30, s30, 0x10180
	s_addc_u32 s31, s31, 0
	s_mov_b32 m0, s57
	v_lshl_add_u64 v[130:131], s[30:31], 0, v[72:73]
	ds_read_b128 v[94:97], v79
	ds_read_b128 v[102:105], v79 offset:1024
	ds_read_b128 v[106:109], v79 offset:2048
	ds_read_b128 v[110:113], v79 offset:3072
	ds_read_b128 v[114:117], v79 offset:4096
	ds_read_b128 v[118:121], v79 offset:5120
	ds_read_b128 v[122:125], v79 offset:6144
	ds_read_b128 v[126:129], v79 offset:7168
	global_load_lds_dwordx4 v[130:131], off
	v_lshl_add_u64 v[130:131], s[30:31], 0, v[68:69]
	s_mov_b32 m0, s58
	s_nop 0
	global_load_lds_dwordx4 v[130:131], off
	s_waitcnt vmcnt(8)
	s_waitcnt lgkmcnt(0)
	s_barrier
	s_setprio 1
	s_waitcnt lgkmcnt(0)
	v_mfma_f32_16x16x32_bf16 v[50:53], v[10:13], v[94:97], v[50:53]
	v_mfma_f32_16x16x32_bf16 v[18:21], v[86:89], v[94:97], v[18:21]
	v_mfma_f32_16x16x32_bf16 v[22:25], v[10:13], v[106:109], v[22:25]
	v_mfma_f32_16x16x32_bf16 v[26:29], v[86:89], v[106:109], v[26:29]
	v_mfma_f32_16x16x32_bf16 v[30:33], v[10:13], v[114:117], v[30:33]
	v_mfma_f32_16x16x32_bf16 v[34:37], v[86:89], v[114:117], v[34:37]
	v_mfma_f32_16x16x32_bf16 v[38:41], v[10:13], v[122:125], v[38:41]
	v_mfma_f32_16x16x32_bf16 v[50:53], v[14:17], v[102:105], v[50:53]
	v_mfma_f32_16x16x32_bf16 v[18:21], v[90:93], v[102:105], v[18:21]
	v_mfma_f32_16x16x32_bf16 v[22:25], v[14:17], v[110:113], v[22:25]
	v_mfma_f32_16x16x32_bf16 v[26:29], v[90:93], v[110:113], v[26:29]
	v_mfma_f32_16x16x32_bf16 v[30:33], v[14:17], v[118:121], v[30:33]
	v_mfma_f32_16x16x32_bf16 v[34:37], v[90:93], v[118:121], v[34:37]
	v_mfma_f32_16x16x32_bf16 v[38:41], v[14:17], v[126:129], v[38:41]
	v_mfma_f32_16x16x32_bf16 v[42:45], v[86:89], v[122:125], v[42:45]
	v_mfma_f32_16x16x32_bf16 v[94:97], v[90:93], v[126:129], v[42:45]
	s_setprio 0
	s_setprio 1
	s_setprio 0
	s_barrier
	s_mov_b32 m0, s43
	v_lshl_add_u64 v[142:143], s[26:27], 0, v[70:71]
	s_add_u32 s30, s26, 0x10000
	ds_read_b128 v[42:45], v79 offset:16384
	ds_read_b128 v[102:105], v79 offset:17408
	ds_read_b128 v[106:109], v79 offset:18432
	ds_read_b128 v[110:113], v79 offset:19456
	ds_read_b128 v[114:117], v79 offset:20480
	ds_read_b128 v[118:121], v79 offset:21504
	ds_read_b128 v[122:125], v79 offset:22528
	ds_read_b128 v[126:129], v79 offset:23552
	global_load_lds_dwordx4 v[142:143], off
	v_lshl_add_u64 v[144:145], s[26:27], 0, v[66:67]
	s_mov_b32 m0, s60
	s_addc_u32 s31, s27, 0
	global_load_lds_dwordx4 v[144:145], off
	v_lshl_add_u64 v[130:131], s[30:31], 0, v[70:71]
	s_mov_b32 m0, s38
	v_lshl_add_u64 v[152:153], s[28:29], 0, v[72:73]
	global_load_lds_dwordx4 v[130:131], off
	v_lshl_add_u64 v[130:131], s[30:31], 0, v[66:67]
	s_mov_b32 m0, s39
	v_lshl_add_u64 v[154:155], s[28:29], 0, v[68:69]
	global_load_lds_dwordx4 v[130:131], off
	s_mov_b32 m0, s37
	s_nop 0
	global_load_lds_dwordx4 v[152:153], off
	s_mov_b32 m0, s40
	s_nop 0
	global_load_lds_dwordx4 v[154:155], off
	s_waitcnt vmcnt(8)
	s_waitcnt lgkmcnt(0)
	s_barrier
	s_setprio 1
	s_waitcnt lgkmcnt(0)
	v_mfma_f32_16x16x32_bf16 v[98:101], v[10:13], v[42:45], v[98:101]
	v_mfma_f32_16x16x32_bf16 v[42:45], v[86:89], v[42:45], v[46:49]
	v_mfma_f32_16x16x32_bf16 v[98:101], v[14:17], v[102:105], v[98:101]
	v_mfma_f32_16x16x32_bf16 v[102:105], v[90:93], v[102:105], v[42:45]
	v_mfma_f32_16x16x32_bf16 v[42:45], v[10:13], v[106:109], v[54:57]
	v_mfma_f32_16x16x32_bf16 v[130:133], v[14:17], v[110:113], v[42:45]
	v_mfma_f32_16x16x32_bf16 v[42:45], v[86:89], v[106:109], v[58:61]
	v_mfma_f32_16x16x32_bf16 v[106:109], v[90:93], v[110:113], v[42:45]
	v_mfma_f32_16x16x32_bf16 v[42:45], v[10:13], v[114:117], v[62:65]
	v_mfma_f32_16x16x32_bf16 v[2:5], v[10:13], v[122:125], v[2:5]
	v_mfma_f32_16x16x32_bf16 v[6:9], v[86:89], v[122:125], v[6:9]
	v_mfma_f32_16x16x32_bf16 v[110:113], v[14:17], v[118:121], v[42:45]
	v_mfma_f32_16x16x32_bf16 v[42:45], v[86:89], v[114:117], v[82:85]
	v_mfma_f32_16x16x32_bf16 v[2:5], v[14:17], v[126:129], v[2:5]
	v_mfma_f32_16x16x32_bf16 v[6:9], v[90:93], v[126:129], v[6:9]
	v_mfma_f32_16x16x32_bf16 v[82:85], v[90:93], v[118:121], v[42:45]
	s_setprio 0
	s_setprio 1
	s_setprio 0
	s_barrier
	ds_read_b128 v[86:89], v80
	ds_read_b128 v[90:93], v80 offset:1024
	ds_read_b128 v[114:117], v80 offset:2048
	ds_read_b128 v[118:121], v80 offset:3072
	s_add_u32 s28, s28, 0x10000
	s_addc_u32 s29, s29, 0
	s_mov_b32 m0, s41
	v_lshl_add_u64 v[42:43], s[28:29], 0, v[72:73]
	ds_read_b128 v[10:13], v79 offset:32768
	ds_read_b128 v[14:17], v79 offset:33792
	ds_read_b128 v[46:49], v79 offset:34816
	ds_read_b128 v[54:57], v79 offset:35840
	ds_read_b128 v[122:125], v79 offset:36864
	ds_read_b128 v[126:129], v79 offset:37888
	ds_read_b128 v[134:137], v79 offset:38912
	ds_read_b128 v[138:141], v79 offset:39936
	global_load_lds_dwordx4 v[42:43], off
	v_lshl_add_u64 v[42:43], s[28:29], 0, v[68:69]
	s_mov_b32 m0, s42
	s_nop 0
	global_load_lds_dwordx4 v[42:43], off
	s_waitcnt vmcnt(8)
	s_waitcnt lgkmcnt(0)
	s_barrier
	s_setprio 1
	s_waitcnt lgkmcnt(0)
	v_mfma_f32_16x16x32_bf16 v[42:45], v[86:89], v[10:13], v[50:53]
	v_mfma_f32_16x16x32_bf16 v[10:13], v[114:117], v[10:13], v[18:21]
	v_mfma_f32_16x16x32_bf16 v[62:65], v[118:121], v[14:17], v[10:13]
	v_mfma_f32_16x16x32_bf16 v[10:13], v[86:89], v[46:49], v[22:25]
	v_mfma_f32_16x16x32_bf16 v[58:61], v[90:93], v[14:17], v[42:45]
	v_mfma_f32_16x16x32_bf16 v[42:45], v[90:93], v[54:57], v[10:13]
	v_mfma_f32_16x16x32_bf16 v[10:13], v[114:117], v[46:49], v[26:29]
	v_mfma_f32_16x16x32_bf16 v[46:49], v[118:121], v[54:57], v[10:13]
	v_mfma_f32_16x16x32_bf16 v[10:13], v[86:89], v[122:125], v[30:33]
	v_mfma_f32_16x16x32_bf16 v[26:29], v[90:93], v[126:129], v[10:13]
	v_mfma_f32_16x16x32_bf16 v[10:13], v[114:117], v[122:125], v[34:37]
	v_mfma_f32_16x16x32_bf16 v[30:33], v[118:121], v[126:129], v[10:13]
	v_mfma_f32_16x16x32_bf16 v[10:13], v[86:89], v[134:137], v[38:41]
	v_mfma_f32_16x16x32_bf16 v[14:17], v[114:117], v[134:137], v[94:97]
	v_mfma_f32_16x16x32_bf16 v[10:13], v[90:93], v[138:141], v[10:13]
	v_mfma_f32_16x16x32_bf16 v[14:17], v[118:121], v[138:141], v[14:17]
	s_setprio 0
	s_setprio 1
	s_setprio 0
	s_barrier
	s_mov_b32 m0, s61
	v_lshl_add_u64 v[34:35], v[142:143], 0, s[12:13]
	s_add_u32 s26, s26, 0x10080
	ds_read_b128 v[18:21], v79 offset:49152
	ds_read_b128 v[22:25], v79 offset:50176
	ds_read_b128 v[38:41], v79 offset:51200
	ds_read_b128 v[94:97], v79 offset:52224
	ds_read_b128 v[122:125], v79 offset:53248
	ds_read_b128 v[126:129], v79 offset:54272
	ds_read_b128 v[134:137], v79 offset:55296
	ds_read_b128 v[138:141], v79 offset:56320
	global_load_lds_dwordx4 v[34:35], off
	v_lshl_add_u64 v[34:35], v[144:145], 0, s[12:13]
	s_mov_b32 m0, s62
	s_addc_u32 s27, s27, 0
	global_load_lds_dwordx4 v[34:35], off
	v_lshl_add_u64 v[34:35], s[26:27], 0, v[70:71]
	s_mov_b32 m0, s55
	s_nop 0
	global_load_lds_dwordx4 v[34:35], off
	v_lshl_add_u64 v[34:35], s[26:27], 0, v[66:67]
	s_mov_b32 m0, s56
	s_nop 0
	global_load_lds_dwordx4 v[34:35], off
	v_lshl_add_u64 v[34:35], v[152:153], 0, s[12:13]
	s_mov_b32 m0, s53
	s_nop 0
	global_load_lds_dwordx4 v[34:35], off
	v_lshl_add_u64 v[34:35], v[154:155], 0, s[12:13]
	s_mov_b32 m0, s54
	s_nop 0
	global_load_lds_dwordx4 v[34:35], off
	s_waitcnt vmcnt(8)
	s_waitcnt lgkmcnt(0)
	s_barrier
	s_setprio 1
	s_waitcnt lgkmcnt(0)
	v_mfma_f32_16x16x32_bf16 v[34:37], v[86:89], v[18:21], v[98:101]
	v_mfma_f32_16x16x32_bf16 v[18:21], v[114:117], v[18:21], v[102:105]
	v_mfma_f32_16x16x32_bf16 v[54:57], v[118:121], v[22:25], v[18:21]
	v_mfma_f32_16x16x32_bf16 v[18:21], v[86:89], v[38:41], v[130:133]
	v_mfma_f32_16x16x32_bf16 v[50:53], v[90:93], v[22:25], v[34:37]
	v_mfma_f32_16x16x32_bf16 v[34:37], v[90:93], v[94:97], v[18:21]
	v_mfma_f32_16x16x32_bf16 v[18:21], v[114:117], v[38:41], v[106:109]
	v_mfma_f32_16x16x32_bf16 v[38:41], v[118:121], v[94:97], v[18:21]
	v_mfma_f32_16x16x32_bf16 v[18:21], v[86:89], v[122:125], v[110:113]
	v_mfma_f32_16x16x32_bf16 v[22:25], v[114:117], v[122:125], v[82:85]
	v_mfma_f32_16x16x32_bf16 v[2:5], v[86:89], v[134:137], v[2:5]
	v_mfma_f32_16x16x32_bf16 v[6:9], v[114:117], v[134:137], v[6:9]
	v_mfma_f32_16x16x32_bf16 v[18:21], v[90:93], v[126:129], v[18:21]
	v_mfma_f32_16x16x32_bf16 v[22:25], v[118:121], v[126:129], v[22:25]
	v_mfma_f32_16x16x32_bf16 v[2:5], v[90:93], v[138:141], v[2:5]
	v_mfma_f32_16x16x32_bf16 v[6:9], v[118:121], v[138:141], v[6:9]
	s_setprio 0
	s_setprio 1
	s_setprio 0
	s_barrier
	s_and_b64 vcc, exec, s[6:7]
	s_cbranch_vccnz .LBB0_825
	s_barrier

.LBB0_840:
	ds_read_b128 v[130:133], v193
	ds_read_b128 v[134:137], v193 offset:1024
	ds_read_b128 v[138:141], v193 offset:2048
	ds_read_b128 v[142:145], v193 offset:3072
	ds_read_b128 v[198:201], v194
	ds_read_b128 v[202:205], v194 offset:1024
	ds_read_b128 v[206:209], v194 offset:2048
	ds_read_b128 v[210:213], v194 offset:3072
	s_add_u32 s4, s10, 0xfff80080
	s_addc_u32 s5, s11, -1
	s_cmp_eq_u32 s43, 28
	s_cselect_b32 s13, s1, s5
	s_cselect_b32 s12, s14, s4
	s_cselect_b32 s5, s15, s30
	s_cselect_b32 s4, s16, s17
	v_lshl_add_u64 v[176:177], s[10:11], 0, v[164:165]
	s_add_i32 m0, s64, 0xc000
	ds_read_b128 v[214:217], v195
	ds_read_b128 v[218:221], v195 offset:1024
	ds_read_b128 v[222:225], v195 offset:2048
	ds_read_b128 v[226:229], v195 offset:3072
	ds_read_b128 v[230:233], v195 offset:4096
	ds_read_b128 v[234:237], v195 offset:5120
	ds_read_b128 v[238:241], v195 offset:6144
	ds_read_b128 v[242:245], v195 offset:7168
	global_load_lds_dwordx4 v[176:177], off
	v_lshl_add_u64 v[176:177], s[10:11], 0, v[168:169]
	s_add_i32 m0, s64, 0xe000
	s_nop 0
	global_load_lds_dwordx4 v[176:177], off
	s_waitcnt vmcnt(8)
	s_waitcnt lgkmcnt(0)
	s_barrier
	s_setprio 1
	s_waitcnt lgkmcnt(0)
	v_mfma_f32_16x16x32_bf16 v[126:129], v[130:133], v[214:217], v[126:129]
	v_mfma_f32_16x16x32_bf16 v[122:125], v[138:141], v[214:217], v[122:125]
	v_mfma_f32_16x16x32_bf16 v[110:113], v[130:133], v[222:225], v[110:113]
	v_mfma_f32_16x16x32_bf16 v[106:109], v[138:141], v[222:225], v[106:109]
	v_mfma_f32_16x16x32_bf16 v[94:97], v[130:133], v[230:233], v[94:97]
	v_mfma_f32_16x16x32_bf16 v[90:93], v[138:141], v[230:233], v[90:93]
	v_mfma_f32_16x16x32_bf16 v[78:81], v[130:133], v[238:241], v[78:81]
	v_mfma_f32_16x16x32_bf16 v[74:77], v[138:141], v[238:241], v[74:77]
	v_mfma_f32_16x16x32_bf16 v[126:129], v[134:137], v[218:221], v[126:129]
	v_mfma_f32_16x16x32_bf16 v[122:125], v[142:145], v[218:221], v[122:125]
	v_mfma_f32_16x16x32_bf16 v[110:113], v[134:137], v[226:229], v[110:113]
	v_mfma_f32_16x16x32_bf16 v[106:109], v[142:145], v[226:229], v[106:109]
	v_mfma_f32_16x16x32_bf16 v[94:97], v[134:137], v[234:237], v[94:97]
	v_mfma_f32_16x16x32_bf16 v[90:93], v[142:145], v[234:237], v[90:93]
	v_mfma_f32_16x16x32_bf16 v[78:81], v[134:137], v[242:245], v[78:81]
	v_mfma_f32_16x16x32_bf16 v[74:77], v[142:145], v[242:245], v[74:77]
	s_setprio 0
	s_setprio 1
	v_mfma_f32_16x16x32_bf16 v[118:121], v[198:201], v[214:217], v[118:121]
	v_mfma_f32_16x16x32_bf16 v[114:117], v[206:209], v[214:217], v[114:117]
	v_mfma_f32_16x16x32_bf16 v[102:105], v[198:201], v[222:225], v[102:105]
	v_mfma_f32_16x16x32_bf16 v[98:101], v[206:209], v[222:225], v[98:101]
	v_mfma_f32_16x16x32_bf16 v[86:89], v[198:201], v[230:233], v[86:89]
	v_mfma_f32_16x16x32_bf16 v[82:85], v[206:209], v[230:233], v[82:85]
	v_mfma_f32_16x16x32_bf16 v[70:73], v[198:201], v[238:241], v[70:73]
	v_mfma_f32_16x16x32_bf16 v[66:69], v[206:209], v[238:241], v[66:69]
	v_mfma_f32_16x16x32_bf16 v[118:121], v[202:205], v[218:221], v[118:121]
	v_mfma_f32_16x16x32_bf16 v[114:117], v[210:213], v[218:221], v[114:117]
	v_mfma_f32_16x16x32_bf16 v[102:105], v[202:205], v[226:229], v[102:105]
	v_mfma_f32_16x16x32_bf16 v[98:101], v[210:213], v[226:229], v[98:101]
	v_mfma_f32_16x16x32_bf16 v[86:89], v[202:205], v[234:237], v[86:89]
	v_mfma_f32_16x16x32_bf16 v[82:85], v[210:213], v[234:237], v[82:85]
	v_mfma_f32_16x16x32_bf16 v[70:73], v[202:205], v[242:245], v[70:73]
	v_mfma_f32_16x16x32_bf16 v[66:69], v[210:213], v[242:245], v[66:69]
	s_setprio 0
	s_barrier
	s_add_i32 s53, s72, s33
	v_lshl_add_u64 v[176:177], s[4:5], 0, v[150:151]
	s_mov_b32 m0, s53
	ds_read_b128 v[214:217], v195 offset:16384
	ds_read_b128 v[218:221], v195 offset:17408
	ds_read_b128 v[222:225], v195 offset:18432
	ds_read_b128 v[226:229], v195 offset:19456
	ds_read_b128 v[230:233], v195 offset:20480
	ds_read_b128 v[234:237], v195 offset:21504
	ds_read_b128 v[238:241], v195 offset:22528
	ds_read_b128 v[242:245], v195 offset:23552
	global_load_lds_dwordx4 v[176:177], off
	s_add_i32 m0, s53, 0x2000
	s_add_u32 s78, s4, 0x80000
	v_lshl_add_u64 v[246:247], s[4:5], 0, v[152:153]
	s_addc_u32 s79, s5, 0
	s_add_i32 s53, s73, s33
	global_load_lds_dwordx4 v[246:247], off
	v_lshl_add_u64 v[248:249], s[78:79], 0, v[150:151]
	s_mov_b32 m0, s53
	v_lshl_add_u64 v[250:251], s[12:13], 0, v[146:147]
	global_load_lds_dwordx4 v[248:249], off
	v_lshl_add_u64 v[248:249], s[78:79], 0, v[152:153]
	s_add_i32 m0, s53, 0x2000
	s_nop 0
	global_load_lds_dwordx4 v[248:249], off
	v_lshl_add_u64 v[248:249], s[12:13], 0, v[148:149]
	s_mov_b32 m0, s64
	s_nop 0
	global_load_lds_dwordx4 v[248:249], off
	s_mov_b32 m0, s65
	s_nop 0
	global_load_lds_dwordx4 v[250:251], off
	s_waitcnt vmcnt(8)
	s_waitcnt lgkmcnt(0)
	s_barrier
	s_setprio 1
	s_waitcnt lgkmcnt(0)
	v_mfma_f32_16x16x32_bf16 v[62:65], v[130:133], v[214:217], v[62:65]
	v_mfma_f32_16x16x32_bf16 v[58:61], v[138:141], v[214:217], v[58:61]
	v_mfma_f32_16x16x32_bf16 v[46:49], v[130:133], v[222:225], v[46:49]
	v_mfma_f32_16x16x32_bf16 v[42:45], v[138:141], v[222:225], v[42:45]
	v_mfma_f32_16x16x32_bf16 v[30:33], v[130:133], v[230:233], v[30:33]
	v_mfma_f32_16x16x32_bf16 v[26:29], v[138:141], v[230:233], v[26:29]
	v_mfma_f32_16x16x32_bf16 v[14:17], v[130:133], v[238:241], v[14:17]
	v_mfma_f32_16x16x32_bf16 v[10:13], v[138:141], v[238:241], v[10:13]
	v_mfma_f32_16x16x32_bf16 v[62:65], v[134:137], v[218:221], v[62:65]
	v_mfma_f32_16x16x32_bf16 v[58:61], v[142:145], v[218:221], v[58:61]
	v_mfma_f32_16x16x32_bf16 v[46:49], v[134:137], v[226:229], v[46:49]
	v_mfma_f32_16x16x32_bf16 v[42:45], v[142:145], v[226:229], v[42:45]
	v_mfma_f32_16x16x32_bf16 v[30:33], v[134:137], v[234:237], v[30:33]
	v_mfma_f32_16x16x32_bf16 v[26:29], v[142:145], v[234:237], v[26:29]
	v_mfma_f32_16x16x32_bf16 v[14:17], v[134:137], v[242:245], v[14:17]
	v_mfma_f32_16x16x32_bf16 v[10:13], v[142:145], v[242:245], v[10:13]
	s_setprio 0
	s_setprio 1
	v_mfma_f32_16x16x32_bf16 v[54:57], v[198:201], v[214:217], v[54:57]
	v_mfma_f32_16x16x32_bf16 v[50:53], v[206:209], v[214:217], v[50:53]
	v_mfma_f32_16x16x32_bf16 v[38:41], v[198:201], v[222:225], v[38:41]
	v_mfma_f32_16x16x32_bf16 v[34:37], v[206:209], v[222:225], v[34:37]
	v_mfma_f32_16x16x32_bf16 v[22:25], v[198:201], v[230:233], v[22:25]
	v_mfma_f32_16x16x32_bf16 v[18:21], v[206:209], v[230:233], v[18:21]
	v_mfma_f32_16x16x32_bf16 v[6:9], v[198:201], v[238:241], v[6:9]
	v_mfma_f32_16x16x32_bf16 v[2:5], v[206:209], v[238:241], v[2:5]
	v_mfma_f32_16x16x32_bf16 v[54:57], v[202:205], v[218:221], v[54:57]
	v_mfma_f32_16x16x32_bf16 v[50:53], v[210:213], v[218:221], v[50:53]
	v_mfma_f32_16x16x32_bf16 v[38:41], v[202:205], v[226:229], v[38:41]
	v_mfma_f32_16x16x32_bf16 v[34:37], v[210:213], v[226:229], v[34:37]
	v_mfma_f32_16x16x32_bf16 v[22:25], v[202:205], v[234:237], v[22:25]
	v_mfma_f32_16x16x32_bf16 v[18:21], v[210:213], v[234:237], v[18:21]
	v_mfma_f32_16x16x32_bf16 v[6:9], v[202:205], v[242:245], v[6:9]
	v_mfma_f32_16x16x32_bf16 v[2:5], v[210:213], v[242:245], v[2:5]
	s_setprio 0
	s_barrier
	s_add_i32 s53, 0, 0x18000
	s_add_i32 s78, 0, 0x1c000
	v_add_u32_e32 v142, s53, v191
	v_add_u32_e32 v156, s78, v191
	ds_read_b128 v[130:133], v142
	ds_read_b128 v[134:137], v142 offset:1024
	ds_read_b128 v[138:141], v142 offset:2048
	ds_read_b128 v[142:145], v142 offset:3072
	ds_read_b128 v[198:201], v156
	ds_read_b128 v[202:205], v156 offset:1024
	ds_read_b128 v[206:209], v156 offset:2048
	ds_read_b128 v[210:213], v156 offset:3072
	s_add_u32 s12, s12, 0x80000
	s_addc_u32 s13, s13, 0
	s_mov_b32 m0, s66
	v_lshl_add_u64 v[252:253], s[12:13], 0, v[148:149]
	ds_read_b128 v[214:217], v195 offset:32768
	ds_read_b128 v[218:221], v195 offset:33792
	ds_read_b128 v[222:225], v195 offset:34816
	ds_read_b128 v[226:229], v195 offset:35840
	ds_read_b128 v[230:233], v195 offset:36864
	ds_read_b128 v[234:237], v195 offset:37888
	ds_read_b128 v[238:241], v195 offset:38912
	ds_read_b128 v[242:245], v195 offset:39936
	global_load_lds_dwordx4 v[252:253], off
	v_lshl_add_u64 v[252:253], s[12:13], 0, v[146:147]
	s_mov_b32 m0, s67
	s_nop 0
	global_load_lds_dwordx4 v[252:253], off
	s_waitcnt vmcnt(8)
	s_waitcnt lgkmcnt(0)
	s_barrier
	s_setprio 1
	s_waitcnt lgkmcnt(0)
	v_mfma_f32_16x16x32_bf16 v[126:129], v[130:133], v[214:217], v[126:129]
	v_mfma_f32_16x16x32_bf16 v[122:125], v[138:141], v[214:217], v[122:125]
	v_mfma_f32_16x16x32_bf16 v[110:113], v[130:133], v[222:225], v[110:113]
	v_mfma_f32_16x16x32_bf16 v[106:109], v[138:141], v[222:225], v[106:109]
	v_mfma_f32_16x16x32_bf16 v[94:97], v[130:133], v[230:233], v[94:97]
	v_mfma_f32_16x16x32_bf16 v[90:93], v[138:141], v[230:233], v[90:93]
	v_mfma_f32_16x16x32_bf16 v[78:81], v[130:133], v[238:241], v[78:81]
	v_mfma_f32_16x16x32_bf16 v[74:77], v[138:141], v[238:241], v[74:77]
	v_mfma_f32_16x16x32_bf16 v[126:129], v[134:137], v[218:221], v[126:129]
	v_mfma_f32_16x16x32_bf16 v[122:125], v[142:145], v[218:221], v[122:125]
	v_mfma_f32_16x16x32_bf16 v[110:113], v[134:137], v[226:229], v[110:113]
	v_mfma_f32_16x16x32_bf16 v[106:109], v[142:145], v[226:229], v[106:109]
	v_mfma_f32_16x16x32_bf16 v[94:97], v[134:137], v[234:237], v[94:97]
	v_mfma_f32_16x16x32_bf16 v[90:93], v[142:145], v[234:237], v[90:93]
	v_mfma_f32_16x16x32_bf16 v[78:81], v[134:137], v[242:245], v[78:81]
	v_mfma_f32_16x16x32_bf16 v[74:77], v[142:145], v[242:245], v[74:77]
	s_setprio 0
	s_setprio 1
	v_mfma_f32_16x16x32_bf16 v[118:121], v[198:201], v[214:217], v[118:121]
	v_mfma_f32_16x16x32_bf16 v[114:117], v[206:209], v[214:217], v[114:117]
	v_mfma_f32_16x16x32_bf16 v[102:105], v[198:201], v[222:225], v[102:105]
	v_mfma_f32_16x16x32_bf16 v[98:101], v[206:209], v[222:225], v[98:101]
	v_mfma_f32_16x16x32_bf16 v[86:89], v[198:201], v[230:233], v[86:89]
	v_mfma_f32_16x16x32_bf16 v[82:85], v[206:209], v[230:233], v[82:85]
	v_mfma_f32_16x16x32_bf16 v[70:73], v[198:201], v[238:241], v[70:73]
	v_mfma_f32_16x16x32_bf16 v[66:69], v[206:209], v[238:241], v[66:69]
	v_mfma_f32_16x16x32_bf16 v[118:121], v[202:205], v[218:221], v[118:121]
	v_mfma_f32_16x16x32_bf16 v[114:117], v[210:213], v[218:221], v[114:117]
	v_mfma_f32_16x16x32_bf16 v[102:105], v[202:205], v[226:229], v[102:105]
	v_mfma_f32_16x16x32_bf16 v[98:101], v[210:213], v[226:229], v[98:101]
	v_mfma_f32_16x16x32_bf16 v[86:89], v[202:205], v[234:237], v[86:89]
	v_mfma_f32_16x16x32_bf16 v[82:85], v[210:213], v[234:237], v[82:85]
	v_mfma_f32_16x16x32_bf16 v[70:73], v[202:205], v[242:245], v[70:73]
	v_mfma_f32_16x16x32_bf16 v[66:69], v[210:213], v[242:245], v[66:69]
	s_setprio 0
	s_barrier
	s_add_i32 s12, s53, s33
	v_lshl_add_u64 v[176:177], v[176:177], 0, s[34:35]
	s_mov_b32 m0, s12
	ds_read_b128 v[214:217], v195 offset:49152
	ds_read_b128 v[218:221], v195 offset:50176
	ds_read_b128 v[222:225], v195 offset:51200
	ds_read_b128 v[226:229], v195 offset:52224
	ds_read_b128 v[230:233], v195 offset:53248
	ds_read_b128 v[234:237], v195 offset:54272
	ds_read_b128 v[238:241], v195 offset:55296
	ds_read_b128 v[242:245], v195 offset:56320
	global_load_lds_dwordx4 v[176:177], off
	s_add_i32 m0, s12, 0x2000
	s_add_u32 s4, s4, 0x80080
	v_lshl_add_u64 v[176:177], v[246:247], 0, s[34:35]
	s_addc_u32 s5, s5, 0
	s_add_i32 s12, s78, s33
	global_load_lds_dwordx4 v[176:177], off
	v_lshl_add_u64 v[176:177], s[4:5], 0, v[150:151]
	s_mov_b32 m0, s12
	s_nop 0
	global_load_lds_dwordx4 v[176:177], off
	v_lshl_add_u64 v[176:177], s[4:5], 0, v[152:153]
	s_add_i32 m0, s12, 0x2000
	s_nop 0
	global_load_lds_dwordx4 v[176:177], off
	v_lshl_add_u64 v[176:177], v[248:249], 0, s[34:35]
	s_mov_b32 m0, s69
	s_nop 0
	global_load_lds_dwordx4 v[176:177], off
	v_lshl_add_u64 v[176:177], v[250:251], 0, s[34:35]
	s_mov_b32 m0, s70
	s_nop 0
	global_load_lds_dwordx4 v[176:177], off
	s_waitcnt vmcnt(8)
	s_waitcnt lgkmcnt(0)
	s_barrier
	s_setprio 1
	s_waitcnt lgkmcnt(0)
	v_mfma_f32_16x16x32_bf16 v[62:65], v[130:133], v[214:217], v[62:65]
	v_mfma_f32_16x16x32_bf16 v[58:61], v[138:141], v[214:217], v[58:61]
	v_mfma_f32_16x16x32_bf16 v[46:49], v[130:133], v[222:225], v[46:49]
	v_mfma_f32_16x16x32_bf16 v[42:45], v[138:141], v[222:225], v[42:45]
	v_mfma_f32_16x16x32_bf16 v[30:33], v[130:133], v[230:233], v[30:33]
	v_mfma_f32_16x16x32_bf16 v[26:29], v[138:141], v[230:233], v[26:29]
	v_mfma_f32_16x16x32_bf16 v[14:17], v[130:133], v[238:241], v[14:17]
	v_mfma_f32_16x16x32_bf16 v[10:13], v[138:141], v[238:241], v[10:13]
	v_mfma_f32_16x16x32_bf16 v[62:65], v[134:137], v[218:221], v[62:65]
	v_mfma_f32_16x16x32_bf16 v[58:61], v[142:145], v[218:221], v[58:61]
	v_mfma_f32_16x16x32_bf16 v[46:49], v[134:137], v[226:229], v[46:49]
	v_mfma_f32_16x16x32_bf16 v[42:45], v[142:145], v[226:229], v[42:45]
	v_mfma_f32_16x16x32_bf16 v[30:33], v[134:137], v[234:237], v[30:33]
	v_mfma_f32_16x16x32_bf16 v[26:29], v[142:145], v[234:237], v[26:29]
	v_mfma_f32_16x16x32_bf16 v[14:17], v[134:137], v[242:245], v[14:17]
	v_mfma_f32_16x16x32_bf16 v[10:13], v[142:145], v[242:245], v[10:13]
	s_setprio 0
	s_setprio 1
	v_mfma_f32_16x16x32_bf16 v[54:57], v[198:201], v[214:217], v[54:57]
	v_mfma_f32_16x16x32_bf16 v[50:53], v[206:209], v[214:217], v[50:53]
	v_mfma_f32_16x16x32_bf16 v[38:41], v[198:201], v[222:225], v[38:41]
	v_mfma_f32_16x16x32_bf16 v[34:37], v[206:209], v[222:225], v[34:37]
	v_mfma_f32_16x16x32_bf16 v[22:25], v[198:201], v[230:233], v[22:25]
	v_mfma_f32_16x16x32_bf16 v[18:21], v[206:209], v[230:233], v[18:21]
	v_mfma_f32_16x16x32_bf16 v[6:9], v[198:201], v[238:241], v[6:9]
	v_mfma_f32_16x16x32_bf16 v[2:5], v[206:209], v[238:241], v[2:5]
	v_mfma_f32_16x16x32_bf16 v[54:57], v[202:205], v[218:221], v[54:57]
	v_mfma_f32_16x16x32_bf16 v[50:53], v[210:213], v[218:221], v[50:53]
	v_mfma_f32_16x16x32_bf16 v[38:41], v[202:205], v[226:229], v[38:41]
	v_mfma_f32_16x16x32_bf16 v[34:37], v[210:213], v[226:229], v[34:37]
	v_mfma_f32_16x16x32_bf16 v[22:25], v[202:205], v[234:237], v[22:25]
	v_mfma_f32_16x16x32_bf16 v[18:21], v[210:213], v[234:237], v[18:21]
	v_mfma_f32_16x16x32_bf16 v[6:9], v[202:205], v[242:245], v[6:9]
	v_mfma_f32_16x16x32_bf16 v[2:5], v[210:213], v[242:245], v[2:5]
	s_setprio 0
	s_barrier
	s_add_i32 s43, s43, 2
	s_add_u32 s10, s10, 0x100
	s_addc_u32 s11, s11, 0
	s_add_u32 s17, s17, 0x100
	s_addc_u32 s30, s30, 0
	s_cmp_gt_u32 s43, 29
	s_cbranch_scc0 .LBB0_840
	s_and_b64 vcc, exec, s[36:37]
	s_cbranch_vccz .LBB0_843
	s_barrier

.LBB0_870:
	ds_read_b128 v[130:133], v1
	ds_read_b128 v[134:137], v1 offset:1024
	ds_read_b128 v[138:141], v1 offset:2048
	ds_read_b128 v[142:145], v1 offset:3072
	ds_read_b128 v[180:183], v155
	ds_read_b128 v[184:187], v155 offset:1024
	ds_read_b128 v[188:191], v155 offset:2048
	ds_read_b128 v[192:195], v155 offset:3072
	s_add_u32 s4, s6, 0xfff80080
	s_addc_u32 s5, s7, -1
	s_cmp_eq_u32 s27, 28
	s_cselect_b32 s9, s1, s5
	s_cselect_b32 s8, s10, s4
	s_cselect_b32 s5, s11, s21
	s_cselect_b32 s4, s12, s13
	v_lshl_add_u64 v[172:173], s[6:7], 0, v[164:165]
	s_add_i32 m0, s53, 0xc000
	ds_read_b128 v[196:199], v167
	ds_read_b128 v[200:203], v167 offset:1024
	ds_read_b128 v[204:207], v167 offset:2048
	ds_read_b128 v[208:211], v167 offset:3072
	ds_read_b128 v[212:215], v167 offset:4096
	ds_read_b128 v[216:219], v167 offset:5120
	ds_read_b128 v[220:223], v167 offset:6144
	ds_read_b128 v[224:227], v167 offset:7168
	global_load_lds_dwordx4 v[172:173], off
	v_lshl_add_u64 v[172:173], s[6:7], 0, v[168:169]
	s_add_i32 m0, s53, 0xe000
	s_nop 0
	global_load_lds_dwordx4 v[172:173], off
	s_waitcnt vmcnt(8)
	s_waitcnt lgkmcnt(0)
	s_barrier
	s_setprio 1
	s_waitcnt lgkmcnt(0)
	v_mfma_f32_16x16x32_bf16 v[126:129], v[130:133], v[196:199], v[126:129]
	v_mfma_f32_16x16x32_bf16 v[122:125], v[138:141], v[196:199], v[122:125]
	v_mfma_f32_16x16x32_bf16 v[110:113], v[130:133], v[204:207], v[110:113]
	v_mfma_f32_16x16x32_bf16 v[106:109], v[138:141], v[204:207], v[106:109]
	v_mfma_f32_16x16x32_bf16 v[94:97], v[130:133], v[212:215], v[94:97]
	v_mfma_f32_16x16x32_bf16 v[90:93], v[138:141], v[212:215], v[90:93]
	v_mfma_f32_16x16x32_bf16 v[78:81], v[130:133], v[220:223], v[78:81]
	v_mfma_f32_16x16x32_bf16 v[74:77], v[138:141], v[220:223], v[74:77]
	v_mfma_f32_16x16x32_bf16 v[126:129], v[134:137], v[200:203], v[126:129]
	v_mfma_f32_16x16x32_bf16 v[122:125], v[142:145], v[200:203], v[122:125]
	v_mfma_f32_16x16x32_bf16 v[110:113], v[134:137], v[208:211], v[110:113]
	v_mfma_f32_16x16x32_bf16 v[106:109], v[142:145], v[208:211], v[106:109]
	v_mfma_f32_16x16x32_bf16 v[94:97], v[134:137], v[216:219], v[94:97]
	v_mfma_f32_16x16x32_bf16 v[90:93], v[142:145], v[216:219], v[90:93]
	v_mfma_f32_16x16x32_bf16 v[78:81], v[134:137], v[224:227], v[78:81]
	v_mfma_f32_16x16x32_bf16 v[74:77], v[142:145], v[224:227], v[74:77]
	s_setprio 0
	s_setprio 1
	v_mfma_f32_16x16x32_bf16 v[118:121], v[180:183], v[196:199], v[118:121]
	v_mfma_f32_16x16x32_bf16 v[114:117], v[188:191], v[196:199], v[114:117]
	v_mfma_f32_16x16x32_bf16 v[102:105], v[180:183], v[204:207], v[102:105]
	v_mfma_f32_16x16x32_bf16 v[98:101], v[188:191], v[204:207], v[98:101]
	v_mfma_f32_16x16x32_bf16 v[86:89], v[180:183], v[212:215], v[86:89]
	v_mfma_f32_16x16x32_bf16 v[82:85], v[188:191], v[212:215], v[82:85]
	v_mfma_f32_16x16x32_bf16 v[70:73], v[180:183], v[220:223], v[70:73]
	v_mfma_f32_16x16x32_bf16 v[66:69], v[188:191], v[220:223], v[66:69]
	v_mfma_f32_16x16x32_bf16 v[118:121], v[184:187], v[200:203], v[118:121]
	v_mfma_f32_16x16x32_bf16 v[114:117], v[192:195], v[200:203], v[114:117]
	v_mfma_f32_16x16x32_bf16 v[102:105], v[184:187], v[208:211], v[102:105]
	v_mfma_f32_16x16x32_bf16 v[98:101], v[192:195], v[208:211], v[98:101]
	v_mfma_f32_16x16x32_bf16 v[86:89], v[184:187], v[216:219], v[86:89]
	v_mfma_f32_16x16x32_bf16 v[82:85], v[192:195], v[216:219], v[82:85]
	v_mfma_f32_16x16x32_bf16 v[70:73], v[184:187], v[224:227], v[70:73]
	v_mfma_f32_16x16x32_bf16 v[66:69], v[192:195], v[224:227], v[66:69]
	s_setprio 0
	s_barrier
	s_add_i32 s28, s65, s3
	v_lshl_add_u64 v[172:173], s[4:5], 0, v[150:151]
	s_mov_b32 m0, s28
	ds_read_b128 v[196:199], v167 offset:16384
	ds_read_b128 v[200:203], v167 offset:17408
	ds_read_b128 v[204:207], v167 offset:18432
	ds_read_b128 v[208:211], v167 offset:19456
	ds_read_b128 v[212:215], v167 offset:20480
	ds_read_b128 v[216:219], v167 offset:21504
	ds_read_b128 v[220:223], v167 offset:22528
	ds_read_b128 v[224:227], v167 offset:23552
	global_load_lds_dwordx4 v[172:173], off
	s_add_i32 m0, s28, 0x2000
	s_add_u32 s70, s4, 0x80000
	v_lshl_add_u64 v[228:229], s[4:5], 0, v[152:153]
	s_addc_u32 s71, s5, 0
	s_add_i32 s28, s66, s3
	global_load_lds_dwordx4 v[228:229], off
	v_lshl_add_u64 v[230:231], s[70:71], 0, v[150:151]
	s_mov_b32 m0, s28
	v_lshl_add_u64 v[232:233], s[8:9], 0, v[146:147]
	global_load_lds_dwordx4 v[230:231], off
	v_lshl_add_u64 v[230:231], s[70:71], 0, v[152:153]
	s_add_i32 m0, s28, 0x2000
	s_nop 0
	global_load_lds_dwordx4 v[230:231], off
	v_lshl_add_u64 v[230:231], s[8:9], 0, v[148:149]
	s_mov_b32 m0, s53
	s_nop 0
	global_load_lds_dwordx4 v[230:231], off
	s_mov_b32 m0, s54
	s_nop 0
	global_load_lds_dwordx4 v[232:233], off
	s_waitcnt vmcnt(8)
	s_waitcnt lgkmcnt(0)
	s_barrier
	s_setprio 1
	s_waitcnt lgkmcnt(0)
	v_mfma_f32_16x16x32_bf16 v[62:65], v[130:133], v[196:199], v[62:65]
	v_mfma_f32_16x16x32_bf16 v[58:61], v[138:141], v[196:199], v[58:61]
	v_mfma_f32_16x16x32_bf16 v[46:49], v[130:133], v[204:207], v[46:49]
	v_mfma_f32_16x16x32_bf16 v[42:45], v[138:141], v[204:207], v[42:45]
	v_mfma_f32_16x16x32_bf16 v[30:33], v[130:133], v[212:215], v[30:33]
	v_mfma_f32_16x16x32_bf16 v[26:29], v[138:141], v[212:215], v[26:29]
	v_mfma_f32_16x16x32_bf16 v[14:17], v[130:133], v[220:223], v[14:17]
	v_mfma_f32_16x16x32_bf16 v[10:13], v[138:141], v[220:223], v[10:13]
	v_mfma_f32_16x16x32_bf16 v[62:65], v[134:137], v[200:203], v[62:65]
	v_mfma_f32_16x16x32_bf16 v[58:61], v[142:145], v[200:203], v[58:61]
	v_mfma_f32_16x16x32_bf16 v[46:49], v[134:137], v[208:211], v[46:49]
	v_mfma_f32_16x16x32_bf16 v[42:45], v[142:145], v[208:211], v[42:45]
	v_mfma_f32_16x16x32_bf16 v[30:33], v[134:137], v[216:219], v[30:33]
	v_mfma_f32_16x16x32_bf16 v[26:29], v[142:145], v[216:219], v[26:29]
	v_mfma_f32_16x16x32_bf16 v[14:17], v[134:137], v[224:227], v[14:17]
	v_mfma_f32_16x16x32_bf16 v[10:13], v[142:145], v[224:227], v[10:13]
	s_setprio 0
	s_setprio 1
	v_mfma_f32_16x16x32_bf16 v[54:57], v[180:183], v[196:199], v[54:57]
	v_mfma_f32_16x16x32_bf16 v[50:53], v[188:191], v[196:199], v[50:53]
	v_mfma_f32_16x16x32_bf16 v[38:41], v[180:183], v[204:207], v[38:41]
	v_mfma_f32_16x16x32_bf16 v[34:37], v[188:191], v[204:207], v[34:37]
	v_mfma_f32_16x16x32_bf16 v[22:25], v[180:183], v[212:215], v[22:25]
	v_mfma_f32_16x16x32_bf16 v[18:21], v[188:191], v[212:215], v[18:21]
	v_mfma_f32_16x16x32_bf16 v[6:9], v[180:183], v[220:223], v[6:9]
	v_mfma_f32_16x16x32_bf16 v[2:5], v[188:191], v[220:223], v[2:5]
	v_mfma_f32_16x16x32_bf16 v[54:57], v[184:187], v[200:203], v[54:57]
	v_mfma_f32_16x16x32_bf16 v[50:53], v[192:195], v[200:203], v[50:53]
	v_mfma_f32_16x16x32_bf16 v[38:41], v[184:187], v[208:211], v[38:41]
	v_mfma_f32_16x16x32_bf16 v[34:37], v[192:195], v[208:211], v[34:37]
	v_mfma_f32_16x16x32_bf16 v[22:25], v[184:187], v[216:219], v[22:25]
	v_mfma_f32_16x16x32_bf16 v[18:21], v[192:195], v[216:219], v[18:21]
	v_mfma_f32_16x16x32_bf16 v[6:9], v[184:187], v[224:227], v[6:9]
	v_mfma_f32_16x16x32_bf16 v[2:5], v[192:195], v[224:227], v[2:5]
	s_setprio 0
	s_barrier
	s_add_i32 s28, 0, 0x18000
	s_add_i32 s69, 0, 0x1c000
	v_add_u32_e32 v142, s28, v177
	v_add_u32_e32 v156, s69, v177
	ds_read_b128 v[130:133], v142
	ds_read_b128 v[134:137], v142 offset:1024
	ds_read_b128 v[138:141], v142 offset:2048
	ds_read_b128 v[142:145], v142 offset:3072
	ds_read_b128 v[180:183], v156
	ds_read_b128 v[184:187], v156 offset:1024
	ds_read_b128 v[188:191], v156 offset:2048
	ds_read_b128 v[192:195], v156 offset:3072
	s_add_u32 s8, s8, 0x80000
	s_addc_u32 s9, s9, 0
	s_mov_b32 m0, s55
	v_lshl_add_u64 v[234:235], s[8:9], 0, v[148:149]
	ds_read_b128 v[196:199], v167 offset:32768
	ds_read_b128 v[200:203], v167 offset:33792
	ds_read_b128 v[204:207], v167 offset:34816
	ds_read_b128 v[208:211], v167 offset:35840
	ds_read_b128 v[212:215], v167 offset:36864
	ds_read_b128 v[216:219], v167 offset:37888
	ds_read_b128 v[220:223], v167 offset:38912
	ds_read_b128 v[224:227], v167 offset:39936
	global_load_lds_dwordx4 v[234:235], off
	v_lshl_add_u64 v[234:235], s[8:9], 0, v[146:147]
	s_mov_b32 m0, s56
	s_nop 0
	global_load_lds_dwordx4 v[234:235], off
	s_waitcnt vmcnt(8)
	s_waitcnt lgkmcnt(0)
	s_barrier
	s_setprio 1
	s_waitcnt lgkmcnt(0)
	v_mfma_f32_16x16x32_bf16 v[126:129], v[130:133], v[196:199], v[126:129]
	v_mfma_f32_16x16x32_bf16 v[122:125], v[138:141], v[196:199], v[122:125]
	v_mfma_f32_16x16x32_bf16 v[110:113], v[130:133], v[204:207], v[110:113]
	v_mfma_f32_16x16x32_bf16 v[106:109], v[138:141], v[204:207], v[106:109]
	v_mfma_f32_16x16x32_bf16 v[94:97], v[130:133], v[212:215], v[94:97]
	v_mfma_f32_16x16x32_bf16 v[90:93], v[138:141], v[212:215], v[90:93]
	v_mfma_f32_16x16x32_bf16 v[78:81], v[130:133], v[220:223], v[78:81]
	v_mfma_f32_16x16x32_bf16 v[74:77], v[138:141], v[220:223], v[74:77]
	v_mfma_f32_16x16x32_bf16 v[126:129], v[134:137], v[200:203], v[126:129]
	v_mfma_f32_16x16x32_bf16 v[122:125], v[142:145], v[200:203], v[122:125]
	v_mfma_f32_16x16x32_bf16 v[110:113], v[134:137], v[208:211], v[110:113]
	v_mfma_f32_16x16x32_bf16 v[106:109], v[142:145], v[208:211], v[106:109]
	v_mfma_f32_16x16x32_bf16 v[94:97], v[134:137], v[216:219], v[94:97]
	v_mfma_f32_16x16x32_bf16 v[90:93], v[142:145], v[216:219], v[90:93]
	v_mfma_f32_16x16x32_bf16 v[78:81], v[134:137], v[224:227], v[78:81]
	v_mfma_f32_16x16x32_bf16 v[74:77], v[142:145], v[224:227], v[74:77]
	s_setprio 0
	s_setprio 1
	v_mfma_f32_16x16x32_bf16 v[118:121], v[180:183], v[196:199], v[118:121]
	v_mfma_f32_16x16x32_bf16 v[114:117], v[188:191], v[196:199], v[114:117]
	v_mfma_f32_16x16x32_bf16 v[102:105], v[180:183], v[204:207], v[102:105]
	v_mfma_f32_16x16x32_bf16 v[98:101], v[188:191], v[204:207], v[98:101]
	v_mfma_f32_16x16x32_bf16 v[86:89], v[180:183], v[212:215], v[86:89]
	v_mfma_f32_16x16x32_bf16 v[82:85], v[188:191], v[212:215], v[82:85]
	v_mfma_f32_16x16x32_bf16 v[70:73], v[180:183], v[220:223], v[70:73]
	v_mfma_f32_16x16x32_bf16 v[66:69], v[188:191], v[220:223], v[66:69]
	v_mfma_f32_16x16x32_bf16 v[118:121], v[184:187], v[200:203], v[118:121]
	v_mfma_f32_16x16x32_bf16 v[114:117], v[192:195], v[200:203], v[114:117]
	v_mfma_f32_16x16x32_bf16 v[102:105], v[184:187], v[208:211], v[102:105]
	v_mfma_f32_16x16x32_bf16 v[98:101], v[192:195], v[208:211], v[98:101]
	v_mfma_f32_16x16x32_bf16 v[86:89], v[184:187], v[216:219], v[86:89]
	v_mfma_f32_16x16x32_bf16 v[82:85], v[192:195], v[216:219], v[82:85]
	v_mfma_f32_16x16x32_bf16 v[70:73], v[184:187], v[224:227], v[70:73]
	v_mfma_f32_16x16x32_bf16 v[66:69], v[192:195], v[224:227], v[66:69]
	s_setprio 0
	s_barrier
	s_add_i32 s8, s28, s3
	v_lshl_add_u64 v[172:173], v[172:173], 0, s[30:31]
	s_mov_b32 m0, s8
	ds_read_b128 v[196:199], v167 offset:49152
	ds_read_b128 v[200:203], v167 offset:50176
	ds_read_b128 v[204:207], v167 offset:51200
	ds_read_b128 v[208:211], v167 offset:52224
	ds_read_b128 v[212:215], v167 offset:53248
	ds_read_b128 v[216:219], v167 offset:54272
	ds_read_b128 v[220:223], v167 offset:55296
	ds_read_b128 v[224:227], v167 offset:56320
	global_load_lds_dwordx4 v[172:173], off
	s_add_i32 m0, s8, 0x2000
	s_add_u32 s4, s4, 0x80080
	v_lshl_add_u64 v[172:173], v[228:229], 0, s[30:31]
	s_addc_u32 s5, s5, 0
	s_add_i32 s8, s69, s3
	global_load_lds_dwordx4 v[172:173], off
	v_lshl_add_u64 v[172:173], s[4:5], 0, v[150:151]
	s_mov_b32 m0, s8
	s_nop 0
	global_load_lds_dwordx4 v[172:173], off
	v_lshl_add_u64 v[172:173], s[4:5], 0, v[152:153]
	s_add_i32 m0, s8, 0x2000
	s_nop 0
	global_load_lds_dwordx4 v[172:173], off
	v_lshl_add_u64 v[172:173], v[230:231], 0, s[30:31]
	s_mov_b32 m0, s57
	s_nop 0
	global_load_lds_dwordx4 v[172:173], off
	v_lshl_add_u64 v[172:173], v[232:233], 0, s[30:31]
	s_mov_b32 m0, s64
	s_nop 0
	global_load_lds_dwordx4 v[172:173], off
	s_waitcnt vmcnt(8)
	s_waitcnt lgkmcnt(0)
	s_barrier
	s_setprio 1
	s_waitcnt lgkmcnt(0)
	v_mfma_f32_16x16x32_bf16 v[62:65], v[130:133], v[196:199], v[62:65]
	v_mfma_f32_16x16x32_bf16 v[58:61], v[138:141], v[196:199], v[58:61]
	v_mfma_f32_16x16x32_bf16 v[46:49], v[130:133], v[204:207], v[46:49]
	v_mfma_f32_16x16x32_bf16 v[42:45], v[138:141], v[204:207], v[42:45]
	v_mfma_f32_16x16x32_bf16 v[30:33], v[130:133], v[212:215], v[30:33]
	v_mfma_f32_16x16x32_bf16 v[26:29], v[138:141], v[212:215], v[26:29]
	v_mfma_f32_16x16x32_bf16 v[14:17], v[130:133], v[220:223], v[14:17]
	v_mfma_f32_16x16x32_bf16 v[10:13], v[138:141], v[220:223], v[10:13]
	v_mfma_f32_16x16x32_bf16 v[62:65], v[134:137], v[200:203], v[62:65]
	v_mfma_f32_16x16x32_bf16 v[58:61], v[142:145], v[200:203], v[58:61]
	v_mfma_f32_16x16x32_bf16 v[46:49], v[134:137], v[208:211], v[46:49]
	v_mfma_f32_16x16x32_bf16 v[42:45], v[142:145], v[208:211], v[42:45]
	v_mfma_f32_16x16x32_bf16 v[30:33], v[134:137], v[216:219], v[30:33]
	v_mfma_f32_16x16x32_bf16 v[26:29], v[142:145], v[216:219], v[26:29]
	v_mfma_f32_16x16x32_bf16 v[14:17], v[134:137], v[224:227], v[14:17]
	v_mfma_f32_16x16x32_bf16 v[10:13], v[142:145], v[224:227], v[10:13]
	s_setprio 0
	s_setprio 1
	v_mfma_f32_16x16x32_bf16 v[54:57], v[180:183], v[196:199], v[54:57]
	v_mfma_f32_16x16x32_bf16 v[50:53], v[188:191], v[196:199], v[50:53]
	v_mfma_f32_16x16x32_bf16 v[38:41], v[180:183], v[204:207], v[38:41]
	v_mfma_f32_16x16x32_bf16 v[34:37], v[188:191], v[204:207], v[34:37]
	v_mfma_f32_16x16x32_bf16 v[22:25], v[180:183], v[212:215], v[22:25]
	v_mfma_f32_16x16x32_bf16 v[18:21], v[188:191], v[212:215], v[18:21]
	v_mfma_f32_16x16x32_bf16 v[6:9], v[180:183], v[220:223], v[6:9]
	v_mfma_f32_16x16x32_bf16 v[2:5], v[188:191], v[220:223], v[2:5]
	v_mfma_f32_16x16x32_bf16 v[54:57], v[184:187], v[200:203], v[54:57]
	v_mfma_f32_16x16x32_bf16 v[50:53], v[192:195], v[200:203], v[50:53]
	v_mfma_f32_16x16x32_bf16 v[38:41], v[184:187], v[208:211], v[38:41]
	v_mfma_f32_16x16x32_bf16 v[34:37], v[192:195], v[208:211], v[34:37]
	v_mfma_f32_16x16x32_bf16 v[22:25], v[184:187], v[216:219], v[22:25]
	v_mfma_f32_16x16x32_bf16 v[18:21], v[192:195], v[216:219], v[18:21]
	v_mfma_f32_16x16x32_bf16 v[6:9], v[184:187], v[224:227], v[6:9]
	v_mfma_f32_16x16x32_bf16 v[2:5], v[192:195], v[224:227], v[2:5]
	s_setprio 0
	s_barrier
	s_add_i32 s27, s27, 2
	s_add_u32 s6, s6, 0x100
	s_addc_u32 s7, s7, 0
	s_add_u32 s13, s13, 0x100
	s_addc_u32 s21, s21, 0
	s_cmp_gt_u32 s27, 29
	s_cbranch_scc0 .LBB0_870
	s_and_b64 vcc, exec, s[34:35]
	s_cbranch_vccz .LBB0_873
	s_barrier

.LBB0_1072:
	ds_read_b128 v[130:133], v205
	ds_read_b128 v[134:137], v205 offset:1024
	ds_read_b128 v[154:157], v205 offset:2048
	ds_read_b128 v[158:161], v205 offset:3072
	ds_read_b128 v[162:165], v206
	ds_read_b128 v[168:171], v206 offset:1024
	ds_read_b128 v[172:175], v206 offset:2048
	ds_read_b128 v[176:179], v206 offset:3072
	s_add_u32 s42, s40, 0xfff80080
	s_addc_u32 s43, s41, -1
	s_cmp_eq_u32 s71, 28
	s_cselect_b32 s49, s29, s43
	s_cselect_b32 s48, s37, s42
	s_cselect_b32 s43, s27, s70
	s_cselect_b32 s42, s68, s69
	v_lshl_add_u64 v[218:219], s[40:41], 0, v[146:147]
	s_add_i32 m0, s39, 0xc000
	ds_read_b128 v[180:183], v207
	ds_read_b128 v[184:187], v207 offset:1024
	ds_read_b128 v[188:191], v207 offset:2048
	ds_read_b128 v[192:195], v207 offset:3072
	ds_read_b128 v[196:199], v207 offset:4096
	ds_read_b128 v[200:203], v207 offset:5120
	ds_read_b128 v[210:213], v207 offset:6144
	ds_read_b128 v[214:217], v207 offset:7168
	global_load_lds_dwordx4 v[218:219], off
	v_lshl_add_u64 v[218:219], s[40:41], 0, v[148:149]
	s_add_i32 m0, s39, 0xe000
	s_nop 0
	global_load_lds_dwordx4 v[218:219], off
	s_waitcnt vmcnt(8)
	s_waitcnt lgkmcnt(0)
	s_barrier
	s_setprio 1
	s_waitcnt lgkmcnt(0)
	v_mfma_f32_16x16x32_bf16 v[114:117], v[130:133], v[180:183], v[114:117]
	v_mfma_f32_16x16x32_bf16 v[110:113], v[154:157], v[180:183], v[110:113]
	v_mfma_f32_16x16x32_bf16 v[118:121], v[130:133], v[188:191], v[118:121]
	v_mfma_f32_16x16x32_bf16 v[106:109], v[154:157], v[188:191], v[106:109]
	v_mfma_f32_16x16x32_bf16 v[126:129], v[130:133], v[196:199], v[126:129]
	v_mfma_f32_16x16x32_bf16 v[122:125], v[154:157], v[196:199], v[122:125]
	v_mfma_f32_16x16x32_bf16 v[102:105], v[130:133], v[210:213], v[102:105]
	v_mfma_f32_16x16x32_bf16 v[98:101], v[154:157], v[210:213], v[98:101]
	v_mfma_f32_16x16x32_bf16 v[114:117], v[134:137], v[184:187], v[114:117]
	v_mfma_f32_16x16x32_bf16 v[110:113], v[158:161], v[184:187], v[110:113]
	v_mfma_f32_16x16x32_bf16 v[118:121], v[134:137], v[192:195], v[118:121]
	v_mfma_f32_16x16x32_bf16 v[106:109], v[158:161], v[192:195], v[106:109]
	v_mfma_f32_16x16x32_bf16 v[126:129], v[134:137], v[200:203], v[126:129]
	v_mfma_f32_16x16x32_bf16 v[122:125], v[158:161], v[200:203], v[122:125]
	v_mfma_f32_16x16x32_bf16 v[102:105], v[134:137], v[214:217], v[102:105]
	v_mfma_f32_16x16x32_bf16 v[98:101], v[158:161], v[214:217], v[98:101]
	s_setprio 0
	s_setprio 1
	v_mfma_f32_16x16x32_bf16 v[62:65], v[162:165], v[180:183], v[62:65]
	v_mfma_f32_16x16x32_bf16 v[58:61], v[172:175], v[180:183], v[58:61]
	v_mfma_f32_16x16x32_bf16 v[54:57], v[162:165], v[188:191], v[54:57]
	v_mfma_f32_16x16x32_bf16 v[50:53], v[172:175], v[188:191], v[50:53]
	v_mfma_f32_16x16x32_bf16 v[46:49], v[162:165], v[196:199], v[46:49]
	v_mfma_f32_16x16x32_bf16 v[42:45], v[172:175], v[196:199], v[42:45]
	v_mfma_f32_16x16x32_bf16 v[38:41], v[162:165], v[210:213], v[38:41]
	v_mfma_f32_16x16x32_bf16 v[34:37], v[172:175], v[210:213], v[34:37]
	v_mfma_f32_16x16x32_bf16 v[62:65], v[168:171], v[184:187], v[62:65]
	v_mfma_f32_16x16x32_bf16 v[58:61], v[176:179], v[184:187], v[58:61]
	v_mfma_f32_16x16x32_bf16 v[54:57], v[168:171], v[192:195], v[54:57]
	v_mfma_f32_16x16x32_bf16 v[50:53], v[176:179], v[192:195], v[50:53]
	v_mfma_f32_16x16x32_bf16 v[46:49], v[168:171], v[200:203], v[46:49]
	v_mfma_f32_16x16x32_bf16 v[42:45], v[176:179], v[200:203], v[42:45]
	v_mfma_f32_16x16x32_bf16 v[38:41], v[168:171], v[214:217], v[38:41]
	v_mfma_f32_16x16x32_bf16 v[34:37], v[176:179], v[214:217], v[34:37]
	s_setprio 0
	s_barrier
	s_add_i32 s72, s66, s52
	v_lshl_add_u64 v[218:219], s[42:43], 0, v[140:141]
	s_mov_b32 m0, s72
	ds_read_b128 v[180:183], v207 offset:16384
	ds_read_b128 v[184:187], v207 offset:17408
	ds_read_b128 v[188:191], v207 offset:18432
	ds_read_b128 v[192:195], v207 offset:19456
	ds_read_b128 v[196:199], v207 offset:20480
	ds_read_b128 v[200:203], v207 offset:21504
	ds_read_b128 v[210:213], v207 offset:22528
	ds_read_b128 v[214:217], v207 offset:23552
	global_load_lds_dwordx4 v[218:219], off
	s_add_i32 m0, s72, 0x2000
	s_add_u32 s72, s42, 0x80000
	v_lshl_add_u64 v[220:221], s[42:43], 0, v[144:145]
	s_addc_u32 s73, s43, 0
	s_add_i32 s74, s67, s52
	global_load_lds_dwordx4 v[220:221], off
	v_lshl_add_u64 v[222:223], s[72:73], 0, v[140:141]
	s_mov_b32 m0, s74
	v_lshl_add_u64 v[224:225], s[48:49], 0, v[142:143]
	global_load_lds_dwordx4 v[222:223], off
	v_lshl_add_u64 v[222:223], s[72:73], 0, v[144:145]
	s_add_i32 m0, s74, 0x2000
	s_nop 0
	global_load_lds_dwordx4 v[222:223], off
	v_lshl_add_u64 v[222:223], s[48:49], 0, v[138:139]
	s_mov_b32 m0, s39
	s_nop 0
	global_load_lds_dwordx4 v[222:223], off
	s_mov_b32 m0, s53
	s_nop 0
	global_load_lds_dwordx4 v[224:225], off
	s_waitcnt vmcnt(8)
	s_waitcnt lgkmcnt(0)
	s_barrier
	s_setprio 1
	s_waitcnt lgkmcnt(0)
	v_mfma_f32_16x16x32_bf16 v[94:97], v[130:133], v[180:183], v[94:97]
	v_mfma_f32_16x16x32_bf16 v[90:93], v[154:157], v[180:183], v[90:93]
	v_mfma_f32_16x16x32_bf16 v[86:89], v[130:133], v[188:191], v[86:89]
	v_mfma_f32_16x16x32_bf16 v[82:85], v[154:157], v[188:191], v[82:85]
	v_mfma_f32_16x16x32_bf16 v[78:81], v[130:133], v[196:199], v[78:81]
	v_mfma_f32_16x16x32_bf16 v[74:77], v[154:157], v[196:199], v[74:77]
	v_mfma_f32_16x16x32_bf16 v[70:73], v[130:133], v[210:213], v[70:73]
	v_mfma_f32_16x16x32_bf16 v[66:69], v[154:157], v[210:213], v[66:69]
	v_mfma_f32_16x16x32_bf16 v[94:97], v[134:137], v[184:187], v[94:97]
	v_mfma_f32_16x16x32_bf16 v[90:93], v[158:161], v[184:187], v[90:93]
	v_mfma_f32_16x16x32_bf16 v[86:89], v[134:137], v[192:195], v[86:89]
	v_mfma_f32_16x16x32_bf16 v[82:85], v[158:161], v[192:195], v[82:85]
	v_mfma_f32_16x16x32_bf16 v[78:81], v[134:137], v[200:203], v[78:81]
	v_mfma_f32_16x16x32_bf16 v[74:77], v[158:161], v[200:203], v[74:77]
	v_mfma_f32_16x16x32_bf16 v[70:73], v[134:137], v[214:217], v[70:73]
	v_mfma_f32_16x16x32_bf16 v[66:69], v[158:161], v[214:217], v[66:69]
	s_setprio 0
	s_setprio 1
	v_mfma_f32_16x16x32_bf16 v[30:33], v[162:165], v[180:183], v[30:33]
	v_mfma_f32_16x16x32_bf16 v[26:29], v[172:175], v[180:183], v[26:29]
	v_mfma_f32_16x16x32_bf16 v[22:25], v[162:165], v[188:191], v[22:25]
	v_mfma_f32_16x16x32_bf16 v[18:21], v[172:175], v[188:191], v[18:21]
	v_mfma_f32_16x16x32_bf16 v[14:17], v[162:165], v[196:199], v[14:17]
	v_mfma_f32_16x16x32_bf16 v[10:13], v[172:175], v[196:199], v[10:13]
	v_mfma_f32_16x16x32_bf16 v[6:9], v[162:165], v[210:213], v[6:9]
	v_mfma_f32_16x16x32_bf16 v[2:5], v[172:175], v[210:213], v[2:5]
	v_mfma_f32_16x16x32_bf16 v[30:33], v[168:171], v[184:187], v[30:33]
	v_mfma_f32_16x16x32_bf16 v[26:29], v[176:179], v[184:187], v[26:29]
	v_mfma_f32_16x16x32_bf16 v[22:25], v[168:171], v[192:195], v[22:25]
	v_mfma_f32_16x16x32_bf16 v[18:21], v[176:179], v[192:195], v[18:21]
	v_mfma_f32_16x16x32_bf16 v[14:17], v[168:171], v[200:203], v[14:17]
	v_mfma_f32_16x16x32_bf16 v[10:13], v[176:179], v[200:203], v[10:13]
	v_mfma_f32_16x16x32_bf16 v[6:9], v[168:171], v[214:217], v[6:9]
	v_mfma_f32_16x16x32_bf16 v[2:5], v[176:179], v[214:217], v[2:5]
	s_setprio 0
	s_barrier
	s_add_i32 s72, 0, 0x18000
	s_add_i32 s73, 0, 0x1c000
	v_add_u32_e32 v158, s72, v167
	v_add_u32_e32 v176, s73, v167
	ds_read_b128 v[130:133], v158
	ds_read_b128 v[134:137], v158 offset:1024
	ds_read_b128 v[154:157], v158 offset:2048
	ds_read_b128 v[158:161], v158 offset:3072
	ds_read_b128 v[162:165], v176
	ds_read_b128 v[168:171], v176 offset:1024
	ds_read_b128 v[172:175], v176 offset:2048
	ds_read_b128 v[176:179], v176 offset:3072
	s_add_u32 s48, s48, 0x80000
	s_addc_u32 s49, s49, 0
	s_mov_b32 m0, s54
	v_lshl_add_u64 v[226:227], s[48:49], 0, v[138:139]
	ds_read_b128 v[180:183], v207 offset:32768
	ds_read_b128 v[184:187], v207 offset:33792
	ds_read_b128 v[188:191], v207 offset:34816
	ds_read_b128 v[192:195], v207 offset:35840
	ds_read_b128 v[196:199], v207 offset:36864
	ds_read_b128 v[200:203], v207 offset:37888
	ds_read_b128 v[210:213], v207 offset:38912
	ds_read_b128 v[214:217], v207 offset:39936
	global_load_lds_dwordx4 v[226:227], off
	v_lshl_add_u64 v[226:227], s[48:49], 0, v[142:143]
	s_mov_b32 m0, s55
	s_nop 0
	global_load_lds_dwordx4 v[226:227], off
	s_waitcnt vmcnt(8)
	s_waitcnt lgkmcnt(0)
	s_barrier
	s_setprio 1
	s_waitcnt lgkmcnt(0)
	v_mfma_f32_16x16x32_bf16 v[114:117], v[130:133], v[180:183], v[114:117]
	v_mfma_f32_16x16x32_bf16 v[110:113], v[154:157], v[180:183], v[110:113]
	v_mfma_f32_16x16x32_bf16 v[118:121], v[130:133], v[188:191], v[118:121]
	v_mfma_f32_16x16x32_bf16 v[106:109], v[154:157], v[188:191], v[106:109]
	v_mfma_f32_16x16x32_bf16 v[126:129], v[130:133], v[196:199], v[126:129]
	v_mfma_f32_16x16x32_bf16 v[122:125], v[154:157], v[196:199], v[122:125]
	v_mfma_f32_16x16x32_bf16 v[102:105], v[130:133], v[210:213], v[102:105]
	v_mfma_f32_16x16x32_bf16 v[98:101], v[154:157], v[210:213], v[98:101]
	v_mfma_f32_16x16x32_bf16 v[114:117], v[134:137], v[184:187], v[114:117]
	v_mfma_f32_16x16x32_bf16 v[110:113], v[158:161], v[184:187], v[110:113]
	v_mfma_f32_16x16x32_bf16 v[118:121], v[134:137], v[192:195], v[118:121]
	v_mfma_f32_16x16x32_bf16 v[106:109], v[158:161], v[192:195], v[106:109]
	v_mfma_f32_16x16x32_bf16 v[126:129], v[134:137], v[200:203], v[126:129]
	v_mfma_f32_16x16x32_bf16 v[122:125], v[158:161], v[200:203], v[122:125]
	v_mfma_f32_16x16x32_bf16 v[102:105], v[134:137], v[214:217], v[102:105]
	v_mfma_f32_16x16x32_bf16 v[98:101], v[158:161], v[214:217], v[98:101]
	s_setprio 0
	s_setprio 1
	v_mfma_f32_16x16x32_bf16 v[62:65], v[162:165], v[180:183], v[62:65]
	v_mfma_f32_16x16x32_bf16 v[58:61], v[172:175], v[180:183], v[58:61]
	v_mfma_f32_16x16x32_bf16 v[54:57], v[162:165], v[188:191], v[54:57]
	v_mfma_f32_16x16x32_bf16 v[50:53], v[172:175], v[188:191], v[50:53]
	v_mfma_f32_16x16x32_bf16 v[46:49], v[162:165], v[196:199], v[46:49]
	v_mfma_f32_16x16x32_bf16 v[42:45], v[172:175], v[196:199], v[42:45]
	v_mfma_f32_16x16x32_bf16 v[38:41], v[162:165], v[210:213], v[38:41]
	v_mfma_f32_16x16x32_bf16 v[34:37], v[172:175], v[210:213], v[34:37]
	v_mfma_f32_16x16x32_bf16 v[62:65], v[168:171], v[184:187], v[62:65]
	v_mfma_f32_16x16x32_bf16 v[58:61], v[176:179], v[184:187], v[58:61]
	v_mfma_f32_16x16x32_bf16 v[54:57], v[168:171], v[192:195], v[54:57]
	v_mfma_f32_16x16x32_bf16 v[50:53], v[176:179], v[192:195], v[50:53]
	v_mfma_f32_16x16x32_bf16 v[46:49], v[168:171], v[200:203], v[46:49]
	v_mfma_f32_16x16x32_bf16 v[42:45], v[176:179], v[200:203], v[42:45]
	v_mfma_f32_16x16x32_bf16 v[38:41], v[168:171], v[214:217], v[38:41]
	v_mfma_f32_16x16x32_bf16 v[34:37], v[176:179], v[214:217], v[34:37]
	s_setprio 0
	s_barrier
	s_add_i32 s48, s72, s52
	v_lshl_add_u64 v[218:219], v[218:219], 0, s[14:15]
	s_mov_b32 m0, s48
	ds_read_b128 v[180:183], v207 offset:49152
	ds_read_b128 v[184:187], v207 offset:50176
	ds_read_b128 v[188:191], v207 offset:51200
	ds_read_b128 v[192:195], v207 offset:52224
	ds_read_b128 v[196:199], v207 offset:53248
	ds_read_b128 v[200:203], v207 offset:54272
	ds_read_b128 v[210:213], v207 offset:55296
	ds_read_b128 v[214:217], v207 offset:56320
	global_load_lds_dwordx4 v[218:219], off
	s_add_i32 m0, s48, 0x2000
	s_add_u32 s42, s42, 0x80080
	v_lshl_add_u64 v[218:219], v[220:221], 0, s[14:15]
	s_addc_u32 s43, s43, 0
	s_add_i32 s48, s73, s52
	global_load_lds_dwordx4 v[218:219], off
	v_lshl_add_u64 v[218:219], s[42:43], 0, v[140:141]
	s_mov_b32 m0, s48
	s_nop 0
	global_load_lds_dwordx4 v[218:219], off
	v_lshl_add_u64 v[218:219], s[42:43], 0, v[144:145]
	s_add_i32 m0, s48, 0x2000
	s_nop 0
	global_load_lds_dwordx4 v[218:219], off
	v_lshl_add_u64 v[218:219], v[222:223], 0, s[14:15]
	s_mov_b32 m0, s63
	s_nop 0
	global_load_lds_dwordx4 v[218:219], off
	v_lshl_add_u64 v[218:219], v[224:225], 0, s[14:15]
	s_mov_b32 m0, s64
	s_nop 0
	global_load_lds_dwordx4 v[218:219], off
	s_waitcnt vmcnt(8)
	s_waitcnt lgkmcnt(0)
	s_barrier
	s_setprio 1
	s_waitcnt lgkmcnt(0)
	v_mfma_f32_16x16x32_bf16 v[94:97], v[130:133], v[180:183], v[94:97]
	v_mfma_f32_16x16x32_bf16 v[90:93], v[154:157], v[180:183], v[90:93]
	v_mfma_f32_16x16x32_bf16 v[86:89], v[130:133], v[188:191], v[86:89]
	v_mfma_f32_16x16x32_bf16 v[82:85], v[154:157], v[188:191], v[82:85]
	v_mfma_f32_16x16x32_bf16 v[78:81], v[130:133], v[196:199], v[78:81]
	v_mfma_f32_16x16x32_bf16 v[74:77], v[154:157], v[196:199], v[74:77]
	v_mfma_f32_16x16x32_bf16 v[70:73], v[130:133], v[210:213], v[70:73]
	v_mfma_f32_16x16x32_bf16 v[66:69], v[154:157], v[210:213], v[66:69]
	v_mfma_f32_16x16x32_bf16 v[94:97], v[134:137], v[184:187], v[94:97]
	v_mfma_f32_16x16x32_bf16 v[90:93], v[158:161], v[184:187], v[90:93]
	v_mfma_f32_16x16x32_bf16 v[86:89], v[134:137], v[192:195], v[86:89]
	v_mfma_f32_16x16x32_bf16 v[82:85], v[158:161], v[192:195], v[82:85]
	v_mfma_f32_16x16x32_bf16 v[78:81], v[134:137], v[200:203], v[78:81]
	v_mfma_f32_16x16x32_bf16 v[74:77], v[158:161], v[200:203], v[74:77]
	v_mfma_f32_16x16x32_bf16 v[70:73], v[134:137], v[214:217], v[70:73]
	v_mfma_f32_16x16x32_bf16 v[66:69], v[158:161], v[214:217], v[66:69]
	s_setprio 0
	s_setprio 1
	v_mfma_f32_16x16x32_bf16 v[30:33], v[162:165], v[180:183], v[30:33]
	v_mfma_f32_16x16x32_bf16 v[26:29], v[172:175], v[180:183], v[26:29]
	v_mfma_f32_16x16x32_bf16 v[22:25], v[162:165], v[188:191], v[22:25]
	v_mfma_f32_16x16x32_bf16 v[18:21], v[172:175], v[188:191], v[18:21]
	v_mfma_f32_16x16x32_bf16 v[14:17], v[162:165], v[196:199], v[14:17]
	v_mfma_f32_16x16x32_bf16 v[10:13], v[172:175], v[196:199], v[10:13]
	v_mfma_f32_16x16x32_bf16 v[6:9], v[162:165], v[210:213], v[6:9]
	v_mfma_f32_16x16x32_bf16 v[2:5], v[172:175], v[210:213], v[2:5]
	v_mfma_f32_16x16x32_bf16 v[30:33], v[168:171], v[184:187], v[30:33]
	v_mfma_f32_16x16x32_bf16 v[26:29], v[176:179], v[184:187], v[26:29]
	v_mfma_f32_16x16x32_bf16 v[22:25], v[168:171], v[192:195], v[22:25]
	v_mfma_f32_16x16x32_bf16 v[18:21], v[176:179], v[192:195], v[18:21]
	v_mfma_f32_16x16x32_bf16 v[14:17], v[168:171], v[200:203], v[14:17]
	v_mfma_f32_16x16x32_bf16 v[10:13], v[176:179], v[200:203], v[10:13]
	v_mfma_f32_16x16x32_bf16 v[6:9], v[168:171], v[214:217], v[6:9]
	v_mfma_f32_16x16x32_bf16 v[2:5], v[176:179], v[214:217], v[2:5]
	s_setprio 0
	s_barrier
	s_add_i32 s71, s71, 2
	s_add_u32 s40, s40, 0x100
	s_addc_u32 s41, s41, 0
	s_add_u32 s69, s69, 0x100
	s_addc_u32 s70, s70, 0
	s_cmp_gt_u32 s71, 29
	s_cbranch_scc0 .LBB0_1072
	s_and_b64 vcc, exec, s[16:17]
	s_cbranch_vccz .LBB0_1075
	s_barrier

.LBB0_1164:
	ds_read_b128 v[98:101], v173
	ds_read_b128 v[102:105], v173 offset:1024
	ds_read_b128 v[106:109], v173 offset:2048
	ds_read_b128 v[110:113], v173 offset:3072
	ds_read_b128 v[162:165], v174
	ds_read_b128 v[168:171], v174 offset:1024
	ds_read_b128 v[178:181], v174 offset:2048
	ds_read_b128 v[182:185], v174 offset:3072
	s_add_u32 s36, s34, 0xfff80080
	s_addc_u32 s37, s35, -1
	s_cmp_eq_u32 s68, 28
	s_cselect_b32 s39, s27, s37
	s_cselect_b32 s38, s64, s36
	s_cselect_b32 s37, s25, s67
	s_cselect_b32 s36, s65, s66
	v_lshl_add_u64 v[218:219], s[34:35], 0, v[154:155]
	s_add_i32 m0, s42, 0xc000
	ds_read_b128 v[186:189], v175
	ds_read_b128 v[190:193], v175 offset:1024
	ds_read_b128 v[194:197], v175 offset:2048
	ds_read_b128 v[198:201], v175 offset:3072
	ds_read_b128 v[202:205], v175 offset:4096
	ds_read_b128 v[206:209], v175 offset:5120
	ds_read_b128 v[210:213], v175 offset:6144
	ds_read_b128 v[214:217], v175 offset:7168
	global_load_lds_dwordx4 v[218:219], off
	v_lshl_add_u64 v[218:219], s[34:35], 0, v[156:157]
	s_add_i32 m0, s42, 0xe000
	s_nop 0
	global_load_lds_dwordx4 v[218:219], off
	s_waitcnt vmcnt(8)
	s_waitcnt lgkmcnt(0)
	s_barrier
	s_setprio 1
	s_waitcnt lgkmcnt(0)
	v_mfma_f32_16x16x32_bf16 v[142:145], v[98:101], v[186:189], v[142:145]
	v_mfma_f32_16x16x32_bf16 v[138:141], v[106:109], v[186:189], v[138:141]
	v_mfma_f32_16x16x32_bf16 v[126:129], v[98:101], v[194:197], v[126:129]
	v_mfma_f32_16x16x32_bf16 v[122:125], v[106:109], v[194:197], v[122:125]
	v_mfma_f32_16x16x32_bf16 v[94:97], v[98:101], v[202:205], v[94:97]
	v_mfma_f32_16x16x32_bf16 v[90:93], v[106:109], v[202:205], v[90:93]
	v_mfma_f32_16x16x32_bf16 v[78:81], v[98:101], v[210:213], v[78:81]
	v_mfma_f32_16x16x32_bf16 v[74:77], v[106:109], v[210:213], v[74:77]
	v_mfma_f32_16x16x32_bf16 v[142:145], v[102:105], v[190:193], v[142:145]
	v_mfma_f32_16x16x32_bf16 v[138:141], v[110:113], v[190:193], v[138:141]
	v_mfma_f32_16x16x32_bf16 v[126:129], v[102:105], v[198:201], v[126:129]
	v_mfma_f32_16x16x32_bf16 v[122:125], v[110:113], v[198:201], v[122:125]
	v_mfma_f32_16x16x32_bf16 v[94:97], v[102:105], v[206:209], v[94:97]
	v_mfma_f32_16x16x32_bf16 v[90:93], v[110:113], v[206:209], v[90:93]
	v_mfma_f32_16x16x32_bf16 v[78:81], v[102:105], v[214:217], v[78:81]
	v_mfma_f32_16x16x32_bf16 v[74:77], v[110:113], v[214:217], v[74:77]
	s_setprio 0
	s_setprio 1
	v_mfma_f32_16x16x32_bf16 v[134:137], v[162:165], v[186:189], v[134:137]
	v_mfma_f32_16x16x32_bf16 v[130:133], v[178:181], v[186:189], v[130:133]
	v_mfma_f32_16x16x32_bf16 v[118:121], v[162:165], v[194:197], v[118:121]
	v_mfma_f32_16x16x32_bf16 v[114:117], v[178:181], v[194:197], v[114:117]
	v_mfma_f32_16x16x32_bf16 v[86:89], v[162:165], v[202:205], v[86:89]
	v_mfma_f32_16x16x32_bf16 v[82:85], v[178:181], v[202:205], v[82:85]
	v_mfma_f32_16x16x32_bf16 v[70:73], v[162:165], v[210:213], v[70:73]
	v_mfma_f32_16x16x32_bf16 v[66:69], v[178:181], v[210:213], v[66:69]
	v_mfma_f32_16x16x32_bf16 v[134:137], v[168:171], v[190:193], v[134:137]
	v_mfma_f32_16x16x32_bf16 v[130:133], v[182:185], v[190:193], v[130:133]
	v_mfma_f32_16x16x32_bf16 v[118:121], v[168:171], v[198:201], v[118:121]
	v_mfma_f32_16x16x32_bf16 v[114:117], v[182:185], v[198:201], v[114:117]
	v_mfma_f32_16x16x32_bf16 v[86:89], v[168:171], v[206:209], v[86:89]
	v_mfma_f32_16x16x32_bf16 v[82:85], v[182:185], v[206:209], v[82:85]
	v_mfma_f32_16x16x32_bf16 v[70:73], v[168:171], v[214:217], v[70:73]
	v_mfma_f32_16x16x32_bf16 v[66:69], v[182:185], v[214:217], v[66:69]
	s_setprio 0
	s_barrier
	s_add_i32 s69, s57, s40
	v_lshl_add_u64 v[218:219], s[36:37], 0, v[148:149]
	s_mov_b32 m0, s69
	ds_read_b128 v[186:189], v175 offset:16384
	ds_read_b128 v[190:193], v175 offset:17408
	ds_read_b128 v[194:197], v175 offset:18432
	ds_read_b128 v[198:201], v175 offset:19456
	ds_read_b128 v[202:205], v175 offset:20480
	ds_read_b128 v[206:209], v175 offset:21504
	ds_read_b128 v[210:213], v175 offset:22528
	ds_read_b128 v[214:217], v175 offset:23552
	global_load_lds_dwordx4 v[218:219], off
	s_add_i32 m0, s69, 0x2000
	s_add_u32 s70, s36, 0x80000
	v_lshl_add_u64 v[220:221], s[36:37], 0, v[152:153]
	s_addc_u32 s71, s37, 0
	s_add_i32 s69, s58, s40
	global_load_lds_dwordx4 v[220:221], off
	v_lshl_add_u64 v[222:223], s[70:71], 0, v[148:149]
	s_mov_b32 m0, s69
	v_lshl_add_u64 v[224:225], s[38:39], 0, v[150:151]
	global_load_lds_dwordx4 v[222:223], off
	v_lshl_add_u64 v[222:223], s[70:71], 0, v[152:153]
	s_add_i32 m0, s69, 0x2000
	s_nop 0
	global_load_lds_dwordx4 v[222:223], off
	v_lshl_add_u64 v[222:223], s[38:39], 0, v[146:147]
	s_mov_b32 m0, s42
	s_nop 0
	global_load_lds_dwordx4 v[222:223], off
	s_mov_b32 m0, s43
	s_nop 0
	global_load_lds_dwordx4 v[224:225], off
	s_waitcnt vmcnt(8)
	s_waitcnt lgkmcnt(0)
	s_barrier
	s_setprio 1
	s_waitcnt lgkmcnt(0)
	v_mfma_f32_16x16x32_bf16 v[62:65], v[98:101], v[186:189], v[62:65]
	v_mfma_f32_16x16x32_bf16 v[58:61], v[106:109], v[186:189], v[58:61]
	v_mfma_f32_16x16x32_bf16 v[46:49], v[98:101], v[194:197], v[46:49]
	v_mfma_f32_16x16x32_bf16 v[42:45], v[106:109], v[194:197], v[42:45]
	v_mfma_f32_16x16x32_bf16 v[30:33], v[98:101], v[202:205], v[30:33]
	v_mfma_f32_16x16x32_bf16 v[26:29], v[106:109], v[202:205], v[26:29]
	v_mfma_f32_16x16x32_bf16 v[14:17], v[98:101], v[210:213], v[14:17]
	v_mfma_f32_16x16x32_bf16 v[10:13], v[106:109], v[210:213], v[10:13]
	v_mfma_f32_16x16x32_bf16 v[62:65], v[102:105], v[190:193], v[62:65]
	v_mfma_f32_16x16x32_bf16 v[58:61], v[110:113], v[190:193], v[58:61]
	v_mfma_f32_16x16x32_bf16 v[46:49], v[102:105], v[198:201], v[46:49]
	v_mfma_f32_16x16x32_bf16 v[42:45], v[110:113], v[198:201], v[42:45]
	v_mfma_f32_16x16x32_bf16 v[30:33], v[102:105], v[206:209], v[30:33]
	v_mfma_f32_16x16x32_bf16 v[26:29], v[110:113], v[206:209], v[26:29]
	v_mfma_f32_16x16x32_bf16 v[14:17], v[102:105], v[214:217], v[14:17]
	v_mfma_f32_16x16x32_bf16 v[10:13], v[110:113], v[214:217], v[10:13]
	s_setprio 0
	s_setprio 1
	v_mfma_f32_16x16x32_bf16 v[54:57], v[162:165], v[186:189], v[54:57]
	v_mfma_f32_16x16x32_bf16 v[50:53], v[178:181], v[186:189], v[50:53]
	v_mfma_f32_16x16x32_bf16 v[38:41], v[162:165], v[194:197], v[38:41]
	v_mfma_f32_16x16x32_bf16 v[34:37], v[178:181], v[194:197], v[34:37]
	v_mfma_f32_16x16x32_bf16 v[22:25], v[162:165], v[202:205], v[22:25]
	v_mfma_f32_16x16x32_bf16 v[18:21], v[178:181], v[202:205], v[18:21]
	v_mfma_f32_16x16x32_bf16 v[6:9], v[162:165], v[210:213], v[6:9]
	v_mfma_f32_16x16x32_bf16 v[2:5], v[178:181], v[210:213], v[2:5]
	v_mfma_f32_16x16x32_bf16 v[54:57], v[168:171], v[190:193], v[54:57]
	v_mfma_f32_16x16x32_bf16 v[50:53], v[182:185], v[190:193], v[50:53]
	v_mfma_f32_16x16x32_bf16 v[38:41], v[168:171], v[198:201], v[38:41]
	v_mfma_f32_16x16x32_bf16 v[34:37], v[182:185], v[198:201], v[34:37]
	v_mfma_f32_16x16x32_bf16 v[22:25], v[168:171], v[206:209], v[22:25]
	v_mfma_f32_16x16x32_bf16 v[18:21], v[182:185], v[206:209], v[18:21]
	v_mfma_f32_16x16x32_bf16 v[6:9], v[168:171], v[214:217], v[6:9]
	v_mfma_f32_16x16x32_bf16 v[2:5], v[182:185], v[214:217], v[2:5]
	s_setprio 0
	s_barrier
	s_add_i32 s69, 0, 0x18000
	s_add_i32 s70, 0, 0x1c000
	v_add_u32_e32 v110, s69, v167
	v_add_u32_e32 v177, s70, v167
	ds_read_b128 v[98:101], v110
	ds_read_b128 v[102:105], v110 offset:1024
	ds_read_b128 v[106:109], v110 offset:2048
	ds_read_b128 v[110:113], v110 offset:3072
	ds_read_b128 v[162:165], v177
	ds_read_b128 v[168:171], v177 offset:1024
	ds_read_b128 v[178:181], v177 offset:2048
	ds_read_b128 v[182:185], v177 offset:3072
	s_add_u32 s38, s38, 0x80000
	s_addc_u32 s39, s39, 0
	s_mov_b32 m0, s46
	v_lshl_add_u64 v[226:227], s[38:39], 0, v[146:147]
	ds_read_b128 v[186:189], v175 offset:32768
	ds_read_b128 v[190:193], v175 offset:33792
	ds_read_b128 v[194:197], v175 offset:34816
	ds_read_b128 v[198:201], v175 offset:35840
	ds_read_b128 v[202:205], v175 offset:36864
	ds_read_b128 v[206:209], v175 offset:37888
	ds_read_b128 v[210:213], v175 offset:38912
	ds_read_b128 v[214:217], v175 offset:39936
	global_load_lds_dwordx4 v[226:227], off
	v_lshl_add_u64 v[226:227], s[38:39], 0, v[150:151]
	s_mov_b32 m0, s47
	s_nop 0
	global_load_lds_dwordx4 v[226:227], off
	s_waitcnt vmcnt(8)
	s_waitcnt lgkmcnt(0)
	s_barrier
	s_setprio 1
	s_waitcnt lgkmcnt(0)
	v_mfma_f32_16x16x32_bf16 v[142:145], v[98:101], v[186:189], v[142:145]
	v_mfma_f32_16x16x32_bf16 v[138:141], v[106:109], v[186:189], v[138:141]
	v_mfma_f32_16x16x32_bf16 v[126:129], v[98:101], v[194:197], v[126:129]
	v_mfma_f32_16x16x32_bf16 v[122:125], v[106:109], v[194:197], v[122:125]
	v_mfma_f32_16x16x32_bf16 v[94:97], v[98:101], v[202:205], v[94:97]
	v_mfma_f32_16x16x32_bf16 v[90:93], v[106:109], v[202:205], v[90:93]
	v_mfma_f32_16x16x32_bf16 v[78:81], v[98:101], v[210:213], v[78:81]
	v_mfma_f32_16x16x32_bf16 v[74:77], v[106:109], v[210:213], v[74:77]
	v_mfma_f32_16x16x32_bf16 v[142:145], v[102:105], v[190:193], v[142:145]
	v_mfma_f32_16x16x32_bf16 v[138:141], v[110:113], v[190:193], v[138:141]
	v_mfma_f32_16x16x32_bf16 v[126:129], v[102:105], v[198:201], v[126:129]
	v_mfma_f32_16x16x32_bf16 v[122:125], v[110:113], v[198:201], v[122:125]
	v_mfma_f32_16x16x32_bf16 v[94:97], v[102:105], v[206:209], v[94:97]
	v_mfma_f32_16x16x32_bf16 v[90:93], v[110:113], v[206:209], v[90:93]
	v_mfma_f32_16x16x32_bf16 v[78:81], v[102:105], v[214:217], v[78:81]
	v_mfma_f32_16x16x32_bf16 v[74:77], v[110:113], v[214:217], v[74:77]
	s_setprio 0
	s_setprio 1
	v_mfma_f32_16x16x32_bf16 v[134:137], v[162:165], v[186:189], v[134:137]
	v_mfma_f32_16x16x32_bf16 v[130:133], v[178:181], v[186:189], v[130:133]
	v_mfma_f32_16x16x32_bf16 v[118:121], v[162:165], v[194:197], v[118:121]
	v_mfma_f32_16x16x32_bf16 v[114:117], v[178:181], v[194:197], v[114:117]
	v_mfma_f32_16x16x32_bf16 v[86:89], v[162:165], v[202:205], v[86:89]
	v_mfma_f32_16x16x32_bf16 v[82:85], v[178:181], v[202:205], v[82:85]
	v_mfma_f32_16x16x32_bf16 v[70:73], v[162:165], v[210:213], v[70:73]
	v_mfma_f32_16x16x32_bf16 v[66:69], v[178:181], v[210:213], v[66:69]
	v_mfma_f32_16x16x32_bf16 v[134:137], v[168:171], v[190:193], v[134:137]
	v_mfma_f32_16x16x32_bf16 v[130:133], v[182:185], v[190:193], v[130:133]
	v_mfma_f32_16x16x32_bf16 v[118:121], v[168:171], v[198:201], v[118:121]
	v_mfma_f32_16x16x32_bf16 v[114:117], v[182:185], v[198:201], v[114:117]
	v_mfma_f32_16x16x32_bf16 v[86:89], v[168:171], v[206:209], v[86:89]
	v_mfma_f32_16x16x32_bf16 v[82:85], v[182:185], v[206:209], v[82:85]
	v_mfma_f32_16x16x32_bf16 v[70:73], v[168:171], v[214:217], v[70:73]
	v_mfma_f32_16x16x32_bf16 v[66:69], v[182:185], v[214:217], v[66:69]
	s_setprio 0
	s_barrier
	s_add_i32 s38, s69, s40
	v_lshl_add_u64 v[218:219], v[218:219], 0, s[12:13]
	s_mov_b32 m0, s38
	ds_read_b128 v[186:189], v175 offset:49152
	ds_read_b128 v[190:193], v175 offset:50176
	ds_read_b128 v[194:197], v175 offset:51200
	ds_read_b128 v[198:201], v175 offset:52224
	ds_read_b128 v[202:205], v175 offset:53248
	ds_read_b128 v[206:209], v175 offset:54272
	ds_read_b128 v[210:213], v175 offset:55296
	ds_read_b128 v[214:217], v175 offset:56320
	global_load_lds_dwordx4 v[218:219], off
	s_add_i32 m0, s38, 0x2000
	s_add_u32 s36, s36, 0x80080
	v_lshl_add_u64 v[218:219], v[220:221], 0, s[12:13]
	s_addc_u32 s37, s37, 0
	s_add_i32 s38, s70, s40
	global_load_lds_dwordx4 v[218:219], off
	v_lshl_add_u64 v[218:219], s[36:37], 0, v[148:149]
	s_mov_b32 m0, s38
	s_nop 0
	global_load_lds_dwordx4 v[218:219], off
	v_lshl_add_u64 v[218:219], s[36:37], 0, v[152:153]
	s_add_i32 m0, s38, 0x2000
	s_nop 0
	global_load_lds_dwordx4 v[218:219], off
	v_lshl_add_u64 v[218:219], v[222:223], 0, s[12:13]
	s_mov_b32 m0, s54
	s_nop 0
	global_load_lds_dwordx4 v[218:219], off
	v_lshl_add_u64 v[218:219], v[224:225], 0, s[12:13]
	s_mov_b32 m0, s55
	s_nop 0
	global_load_lds_dwordx4 v[218:219], off
	s_waitcnt vmcnt(8)
	s_waitcnt lgkmcnt(0)
	s_barrier
	s_setprio 1
	s_waitcnt lgkmcnt(0)
	v_mfma_f32_16x16x32_bf16 v[62:65], v[98:101], v[186:189], v[62:65]
	v_mfma_f32_16x16x32_bf16 v[58:61], v[106:109], v[186:189], v[58:61]
	v_mfma_f32_16x16x32_bf16 v[46:49], v[98:101], v[194:197], v[46:49]
	v_mfma_f32_16x16x32_bf16 v[42:45], v[106:109], v[194:197], v[42:45]
	v_mfma_f32_16x16x32_bf16 v[30:33], v[98:101], v[202:205], v[30:33]
	v_mfma_f32_16x16x32_bf16 v[26:29], v[106:109], v[202:205], v[26:29]
	v_mfma_f32_16x16x32_bf16 v[14:17], v[98:101], v[210:213], v[14:17]
	v_mfma_f32_16x16x32_bf16 v[10:13], v[106:109], v[210:213], v[10:13]
	v_mfma_f32_16x16x32_bf16 v[62:65], v[102:105], v[190:193], v[62:65]
	v_mfma_f32_16x16x32_bf16 v[58:61], v[110:113], v[190:193], v[58:61]
	v_mfma_f32_16x16x32_bf16 v[46:49], v[102:105], v[198:201], v[46:49]
	v_mfma_f32_16x16x32_bf16 v[42:45], v[110:113], v[198:201], v[42:45]
	v_mfma_f32_16x16x32_bf16 v[30:33], v[102:105], v[206:209], v[30:33]
	v_mfma_f32_16x16x32_bf16 v[26:29], v[110:113], v[206:209], v[26:29]
	v_mfma_f32_16x16x32_bf16 v[14:17], v[102:105], v[214:217], v[14:17]
	v_mfma_f32_16x16x32_bf16 v[10:13], v[110:113], v[214:217], v[10:13]
	s_setprio 0
	s_setprio 1
	v_mfma_f32_16x16x32_bf16 v[54:57], v[162:165], v[186:189], v[54:57]
	v_mfma_f32_16x16x32_bf16 v[50:53], v[178:181], v[186:189], v[50:53]
	v_mfma_f32_16x16x32_bf16 v[38:41], v[162:165], v[194:197], v[38:41]
	v_mfma_f32_16x16x32_bf16 v[34:37], v[178:181], v[194:197], v[34:37]
	v_mfma_f32_16x16x32_bf16 v[22:25], v[162:165], v[202:205], v[22:25]
	v_mfma_f32_16x16x32_bf16 v[18:21], v[178:181], v[202:205], v[18:21]
	v_mfma_f32_16x16x32_bf16 v[6:9], v[162:165], v[210:213], v[6:9]
	v_mfma_f32_16x16x32_bf16 v[2:5], v[178:181], v[210:213], v[2:5]
	v_mfma_f32_16x16x32_bf16 v[54:57], v[168:171], v[190:193], v[54:57]
	v_mfma_f32_16x16x32_bf16 v[50:53], v[182:185], v[190:193], v[50:53]
	v_mfma_f32_16x16x32_bf16 v[38:41], v[168:171], v[198:201], v[38:41]
	v_mfma_f32_16x16x32_bf16 v[34:37], v[182:185], v[198:201], v[34:37]
	v_mfma_f32_16x16x32_bf16 v[22:25], v[168:171], v[206:209], v[22:25]
	v_mfma_f32_16x16x32_bf16 v[18:21], v[182:185], v[206:209], v[18:21]
	v_mfma_f32_16x16x32_bf16 v[6:9], v[168:171], v[214:217], v[6:9]
	v_mfma_f32_16x16x32_bf16 v[2:5], v[182:185], v[214:217], v[2:5]
	s_setprio 0
	s_barrier
	s_add_i32 s68, s68, 2
	s_add_u32 s34, s34, 0x100
	s_addc_u32 s35, s35, 0
	s_add_u32 s66, s66, 0x100
	s_addc_u32 s67, s67, 0
	s_cmp_gt_u32 s68, 29
	s_cbranch_scc0 .LBB0_1164
	s_and_b64 vcc, exec, s[14:15]
	s_cbranch_vccz .LBB0_1167
	s_barrier

.LBB0_1240:
	ds_read_b128 v[130:133], v189
	ds_read_b128 v[134:137], v189 offset:1024
	ds_read_b128 v[138:141], v189 offset:2048
	ds_read_b128 v[142:145], v189 offset:3072
	ds_read_b128 v[146:149], v190
	ds_read_b128 v[150:153], v190 offset:1024
	ds_read_b128 v[154:157], v190 offset:2048
	ds_read_b128 v[158:161], v190 offset:3072
	s_add_u32 s34, s30, 0xffe00080
	s_addc_u32 s35, s31, -1
	s_cmpk_eq_i32 s63, 0x7c
	s_cselect_b32 s37, s23, s35
	s_cselect_b32 s36, s59, s34
	s_cselect_b32 s35, s21, s62
	s_cselect_b32 s34, s60, s61
	v_lshl_add_u64 v[216:217], s[30:31], 0, v[176:177]
	s_add_i32 m0, s29, 0xc000
	ds_read_b128 v[162:165], v191
	ds_read_b128 v[184:187], v191 offset:1024
	ds_read_b128 v[192:195], v191 offset:2048
	ds_read_b128 v[196:199], v191 offset:3072
	ds_read_b128 v[200:203], v191 offset:4096
	ds_read_b128 v[204:207], v191 offset:5120
	ds_read_b128 v[208:211], v191 offset:6144
	ds_read_b128 v[212:215], v191 offset:7168
	global_load_lds_dwordx4 v[216:217], off
	v_lshl_add_u64 v[216:217], s[30:31], 0, v[178:179]
	s_add_i32 m0, s29, 0xe000
	s_nop 0
	global_load_lds_dwordx4 v[216:217], off
	s_waitcnt vmcnt(8)
	s_waitcnt lgkmcnt(0)
	s_barrier
	s_setprio 1
	s_waitcnt lgkmcnt(0)
	v_mfma_f32_16x16x32_bf16 v[126:129], v[130:133], v[162:165], v[126:129]
	v_mfma_f32_16x16x32_bf16 v[122:125], v[138:141], v[162:165], v[122:125]
	v_mfma_f32_16x16x32_bf16 v[118:121], v[130:133], v[192:195], v[118:121]
	v_mfma_f32_16x16x32_bf16 v[106:109], v[138:141], v[192:195], v[106:109]
	v_mfma_f32_16x16x32_bf16 v[94:97], v[130:133], v[200:203], v[94:97]
	v_mfma_f32_16x16x32_bf16 v[90:93], v[138:141], v[200:203], v[90:93]
	v_mfma_f32_16x16x32_bf16 v[82:85], v[130:133], v[208:211], v[82:85]
	v_mfma_f32_16x16x32_bf16 v[74:77], v[138:141], v[208:211], v[74:77]
	v_mfma_f32_16x16x32_bf16 v[126:129], v[134:137], v[184:187], v[126:129]
	v_mfma_f32_16x16x32_bf16 v[122:125], v[142:145], v[184:187], v[122:125]
	v_mfma_f32_16x16x32_bf16 v[118:121], v[134:137], v[196:199], v[118:121]
	v_mfma_f32_16x16x32_bf16 v[106:109], v[142:145], v[196:199], v[106:109]
	v_mfma_f32_16x16x32_bf16 v[94:97], v[134:137], v[204:207], v[94:97]
	v_mfma_f32_16x16x32_bf16 v[90:93], v[142:145], v[204:207], v[90:93]
	v_mfma_f32_16x16x32_bf16 v[82:85], v[134:137], v[212:215], v[82:85]
	v_mfma_f32_16x16x32_bf16 v[74:77], v[142:145], v[212:215], v[74:77]
	s_setprio 0
	s_setprio 1
	v_mfma_f32_16x16x32_bf16 v[114:117], v[146:149], v[162:165], v[114:117]
	v_mfma_f32_16x16x32_bf16 v[110:113], v[154:157], v[162:165], v[110:113]
	v_mfma_f32_16x16x32_bf16 v[102:105], v[146:149], v[192:195], v[102:105]
	v_mfma_f32_16x16x32_bf16 v[98:101], v[154:157], v[192:195], v[98:101]
	v_mfma_f32_16x16x32_bf16 v[86:89], v[146:149], v[200:203], v[86:89]
	v_mfma_f32_16x16x32_bf16 v[78:81], v[154:157], v[200:203], v[78:81]
	v_mfma_f32_16x16x32_bf16 v[70:73], v[146:149], v[208:211], v[70:73]
	v_mfma_f32_16x16x32_bf16 v[66:69], v[154:157], v[208:211], v[66:69]
	v_mfma_f32_16x16x32_bf16 v[114:117], v[150:153], v[184:187], v[114:117]
	v_mfma_f32_16x16x32_bf16 v[110:113], v[158:161], v[184:187], v[110:113]
	v_mfma_f32_16x16x32_bf16 v[102:105], v[150:153], v[196:199], v[102:105]
	v_mfma_f32_16x16x32_bf16 v[98:101], v[158:161], v[196:199], v[98:101]
	v_mfma_f32_16x16x32_bf16 v[86:89], v[150:153], v[204:207], v[86:89]
	v_mfma_f32_16x16x32_bf16 v[78:81], v[158:161], v[204:207], v[78:81]
	v_mfma_f32_16x16x32_bf16 v[70:73], v[150:153], v[212:215], v[70:73]
	v_mfma_f32_16x16x32_bf16 v[66:69], v[158:161], v[212:215], v[66:69]
	s_setprio 0
	s_barrier
	s_add_i32 s64, s52, s38
	v_lshl_add_u64 v[216:217], s[34:35], 0, v[170:171]
	s_mov_b32 m0, s64
	ds_read_b128 v[162:165], v191 offset:16384
	ds_read_b128 v[184:187], v191 offset:17408
	ds_read_b128 v[192:195], v191 offset:18432
	ds_read_b128 v[196:199], v191 offset:19456
	ds_read_b128 v[200:203], v191 offset:20480
	ds_read_b128 v[204:207], v191 offset:21504
	ds_read_b128 v[208:211], v191 offset:22528
	ds_read_b128 v[212:215], v191 offset:23552
	global_load_lds_dwordx4 v[216:217], off
	s_add_i32 m0, s64, 0x2000
	s_add_u32 s64, s34, 0x200000
	v_lshl_add_u64 v[218:219], s[34:35], 0, v[174:175]
	s_addc_u32 s65, s35, 0
	s_add_i32 s66, s53, s38
	global_load_lds_dwordx4 v[218:219], off
	v_lshl_add_u64 v[220:221], s[64:65], 0, v[170:171]
	s_mov_b32 m0, s66
	v_lshl_add_u64 v[222:223], s[36:37], 0, v[172:173]
	global_load_lds_dwordx4 v[220:221], off
	v_lshl_add_u64 v[220:221], s[64:65], 0, v[174:175]
	s_add_i32 m0, s66, 0x2000
	s_nop 0
	global_load_lds_dwordx4 v[220:221], off
	v_lshl_add_u64 v[220:221], s[36:37], 0, v[168:169]
	s_mov_b32 m0, s29
	s_nop 0
	global_load_lds_dwordx4 v[220:221], off
	s_mov_b32 m0, s40
	s_nop 0
	global_load_lds_dwordx4 v[222:223], off
	s_waitcnt vmcnt(8)
	s_waitcnt lgkmcnt(0)
	s_barrier
	s_setprio 1
	s_waitcnt lgkmcnt(0)
	v_mfma_f32_16x16x32_bf16 v[62:65], v[130:133], v[162:165], v[62:65]
	v_mfma_f32_16x16x32_bf16 v[58:61], v[138:141], v[162:165], v[58:61]
	v_mfma_f32_16x16x32_bf16 v[54:57], v[130:133], v[192:195], v[54:57]
	v_mfma_f32_16x16x32_bf16 v[50:53], v[138:141], v[192:195], v[50:53]
	v_mfma_f32_16x16x32_bf16 v[38:41], v[130:133], v[200:203], v[38:41]
	v_mfma_f32_16x16x32_bf16 v[34:37], v[138:141], v[200:203], v[34:37]
	v_mfma_f32_16x16x32_bf16 v[22:25], v[130:133], v[208:211], v[22:25]
	v_mfma_f32_16x16x32_bf16 v[18:21], v[138:141], v[208:211], v[18:21]
	v_mfma_f32_16x16x32_bf16 v[62:65], v[134:137], v[184:187], v[62:65]
	v_mfma_f32_16x16x32_bf16 v[58:61], v[142:145], v[184:187], v[58:61]
	v_mfma_f32_16x16x32_bf16 v[54:57], v[134:137], v[196:199], v[54:57]
	v_mfma_f32_16x16x32_bf16 v[50:53], v[142:145], v[196:199], v[50:53]
	v_mfma_f32_16x16x32_bf16 v[38:41], v[134:137], v[204:207], v[38:41]
	v_mfma_f32_16x16x32_bf16 v[34:37], v[142:145], v[204:207], v[34:37]
	v_mfma_f32_16x16x32_bf16 v[22:25], v[134:137], v[212:215], v[22:25]
	v_mfma_f32_16x16x32_bf16 v[18:21], v[142:145], v[212:215], v[18:21]
	s_setprio 0
	s_setprio 1
	v_mfma_f32_16x16x32_bf16 v[46:49], v[146:149], v[162:165], v[46:49]
	v_mfma_f32_16x16x32_bf16 v[42:45], v[154:157], v[162:165], v[42:45]
	v_mfma_f32_16x16x32_bf16 v[30:33], v[146:149], v[192:195], v[30:33]
	v_mfma_f32_16x16x32_bf16 v[26:29], v[154:157], v[192:195], v[26:29]
	v_mfma_f32_16x16x32_bf16 v[14:17], v[146:149], v[200:203], v[14:17]
	v_mfma_f32_16x16x32_bf16 v[10:13], v[154:157], v[200:203], v[10:13]
	v_mfma_f32_16x16x32_bf16 v[6:9], v[146:149], v[208:211], v[6:9]
	v_mfma_f32_16x16x32_bf16 v[2:5], v[154:157], v[208:211], v[2:5]
	v_mfma_f32_16x16x32_bf16 v[46:49], v[150:153], v[184:187], v[46:49]
	v_mfma_f32_16x16x32_bf16 v[42:45], v[158:161], v[184:187], v[42:45]
	v_mfma_f32_16x16x32_bf16 v[30:33], v[150:153], v[196:199], v[30:33]
	v_mfma_f32_16x16x32_bf16 v[26:29], v[158:161], v[196:199], v[26:29]
	v_mfma_f32_16x16x32_bf16 v[14:17], v[150:153], v[204:207], v[14:17]
	v_mfma_f32_16x16x32_bf16 v[10:13], v[158:161], v[204:207], v[10:13]
	v_mfma_f32_16x16x32_bf16 v[6:9], v[150:153], v[212:215], v[6:9]
	v_mfma_f32_16x16x32_bf16 v[2:5], v[158:161], v[212:215], v[2:5]
	s_setprio 0
	s_barrier
	s_add_i32 s64, 0, 0x18000
	s_add_i32 s65, 0, 0x1c000
	v_add_u32_e32 v142, s64, v167
	v_add_u32_e32 v158, s65, v167
	ds_read_b128 v[130:133], v142
	ds_read_b128 v[134:137], v142 offset:1024
	ds_read_b128 v[138:141], v142 offset:2048
	ds_read_b128 v[142:145], v142 offset:3072
	ds_read_b128 v[146:149], v158
	ds_read_b128 v[150:153], v158 offset:1024
	ds_read_b128 v[154:157], v158 offset:2048
	ds_read_b128 v[158:161], v158 offset:3072
	s_add_u32 s36, s36, 0x200000
	s_addc_u32 s37, s37, 0
	s_mov_b32 m0, s41
	v_lshl_add_u64 v[224:225], s[36:37], 0, v[168:169]
	ds_read_b128 v[162:165], v191 offset:32768
	ds_read_b128 v[184:187], v191 offset:33792
	ds_read_b128 v[192:195], v191 offset:34816
	ds_read_b128 v[196:199], v191 offset:35840
	ds_read_b128 v[200:203], v191 offset:36864
	ds_read_b128 v[204:207], v191 offset:37888
	ds_read_b128 v[208:211], v191 offset:38912
	ds_read_b128 v[212:215], v191 offset:39936
	global_load_lds_dwordx4 v[224:225], off
	v_lshl_add_u64 v[224:225], s[36:37], 0, v[172:173]
	s_mov_b32 m0, s42
	s_nop 0
	global_load_lds_dwordx4 v[224:225], off
	s_waitcnt vmcnt(8)
	s_waitcnt lgkmcnt(0)
	s_barrier
	s_setprio 1
	s_waitcnt lgkmcnt(0)
	v_mfma_f32_16x16x32_bf16 v[126:129], v[130:133], v[162:165], v[126:129]
	v_mfma_f32_16x16x32_bf16 v[122:125], v[138:141], v[162:165], v[122:125]
	v_mfma_f32_16x16x32_bf16 v[118:121], v[130:133], v[192:195], v[118:121]
	v_mfma_f32_16x16x32_bf16 v[106:109], v[138:141], v[192:195], v[106:109]
	v_mfma_f32_16x16x32_bf16 v[94:97], v[130:133], v[200:203], v[94:97]
	v_mfma_f32_16x16x32_bf16 v[90:93], v[138:141], v[200:203], v[90:93]
	v_mfma_f32_16x16x32_bf16 v[82:85], v[130:133], v[208:211], v[82:85]
	v_mfma_f32_16x16x32_bf16 v[74:77], v[138:141], v[208:211], v[74:77]
	v_mfma_f32_16x16x32_bf16 v[126:129], v[134:137], v[184:187], v[126:129]
	v_mfma_f32_16x16x32_bf16 v[122:125], v[142:145], v[184:187], v[122:125]
	v_mfma_f32_16x16x32_bf16 v[118:121], v[134:137], v[196:199], v[118:121]
	v_mfma_f32_16x16x32_bf16 v[106:109], v[142:145], v[196:199], v[106:109]
	v_mfma_f32_16x16x32_bf16 v[94:97], v[134:137], v[204:207], v[94:97]
	v_mfma_f32_16x16x32_bf16 v[90:93], v[142:145], v[204:207], v[90:93]
	v_mfma_f32_16x16x32_bf16 v[82:85], v[134:137], v[212:215], v[82:85]
	v_mfma_f32_16x16x32_bf16 v[74:77], v[142:145], v[212:215], v[74:77]
	s_setprio 0
	s_setprio 1
	v_mfma_f32_16x16x32_bf16 v[114:117], v[146:149], v[162:165], v[114:117]
	v_mfma_f32_16x16x32_bf16 v[110:113], v[154:157], v[162:165], v[110:113]
	v_mfma_f32_16x16x32_bf16 v[102:105], v[146:149], v[192:195], v[102:105]
	v_mfma_f32_16x16x32_bf16 v[98:101], v[154:157], v[192:195], v[98:101]
	v_mfma_f32_16x16x32_bf16 v[86:89], v[146:149], v[200:203], v[86:89]
	v_mfma_f32_16x16x32_bf16 v[78:81], v[154:157], v[200:203], v[78:81]
	v_mfma_f32_16x16x32_bf16 v[70:73], v[146:149], v[208:211], v[70:73]
	v_mfma_f32_16x16x32_bf16 v[66:69], v[154:157], v[208:211], v[66:69]
	v_mfma_f32_16x16x32_bf16 v[114:117], v[150:153], v[184:187], v[114:117]
	v_mfma_f32_16x16x32_bf16 v[110:113], v[158:161], v[184:187], v[110:113]
	v_mfma_f32_16x16x32_bf16 v[102:105], v[150:153], v[196:199], v[102:105]
	v_mfma_f32_16x16x32_bf16 v[98:101], v[158:161], v[196:199], v[98:101]
	v_mfma_f32_16x16x32_bf16 v[86:89], v[150:153], v[204:207], v[86:89]
	v_mfma_f32_16x16x32_bf16 v[78:81], v[158:161], v[204:207], v[78:81]
	v_mfma_f32_16x16x32_bf16 v[70:73], v[150:153], v[212:215], v[70:73]
	v_mfma_f32_16x16x32_bf16 v[66:69], v[158:161], v[212:215], v[66:69]
	s_setprio 0
	s_barrier
	s_add_i32 s36, s64, s38
	v_lshl_add_u64 v[216:217], v[216:217], 0, s[8:9]
	s_mov_b32 m0, s36
	ds_read_b128 v[162:165], v191 offset:49152
	ds_read_b128 v[184:187], v191 offset:50176
	ds_read_b128 v[192:195], v191 offset:51200
	ds_read_b128 v[196:199], v191 offset:52224
	ds_read_b128 v[200:203], v191 offset:53248
	ds_read_b128 v[204:207], v191 offset:54272
	ds_read_b128 v[208:211], v191 offset:55296
	ds_read_b128 v[212:215], v191 offset:56320
	global_load_lds_dwordx4 v[216:217], off
	s_add_i32 m0, s36, 0x2000
	s_add_u32 s34, s34, 0x200080
	v_lshl_add_u64 v[216:217], v[218:219], 0, s[8:9]
	s_addc_u32 s35, s35, 0
	s_add_i32 s36, s65, s38
	global_load_lds_dwordx4 v[216:217], off
	v_lshl_add_u64 v[216:217], s[34:35], 0, v[170:171]
	s_mov_b32 m0, s36
	s_nop 0
	global_load_lds_dwordx4 v[216:217], off
	v_lshl_add_u64 v[216:217], s[34:35], 0, v[174:175]
	s_add_i32 m0, s36, 0x2000
	s_nop 0
	global_load_lds_dwordx4 v[216:217], off
	v_lshl_add_u64 v[216:217], v[220:221], 0, s[8:9]
	s_mov_b32 m0, s49
	s_nop 0
	global_load_lds_dwordx4 v[216:217], off
	v_lshl_add_u64 v[216:217], v[222:223], 0, s[8:9]
	s_mov_b32 m0, s50
	s_nop 0
	global_load_lds_dwordx4 v[216:217], off
	s_waitcnt vmcnt(8)
	s_waitcnt lgkmcnt(0)
	s_barrier
	s_setprio 1
	s_waitcnt lgkmcnt(0)
	v_mfma_f32_16x16x32_bf16 v[62:65], v[130:133], v[162:165], v[62:65]
	v_mfma_f32_16x16x32_bf16 v[58:61], v[138:141], v[162:165], v[58:61]
	v_mfma_f32_16x16x32_bf16 v[54:57], v[130:133], v[192:195], v[54:57]
	v_mfma_f32_16x16x32_bf16 v[50:53], v[138:141], v[192:195], v[50:53]
	v_mfma_f32_16x16x32_bf16 v[38:41], v[130:133], v[200:203], v[38:41]
	v_mfma_f32_16x16x32_bf16 v[34:37], v[138:141], v[200:203], v[34:37]
	v_mfma_f32_16x16x32_bf16 v[22:25], v[130:133], v[208:211], v[22:25]
	v_mfma_f32_16x16x32_bf16 v[18:21], v[138:141], v[208:211], v[18:21]
	v_mfma_f32_16x16x32_bf16 v[62:65], v[134:137], v[184:187], v[62:65]
	v_mfma_f32_16x16x32_bf16 v[58:61], v[142:145], v[184:187], v[58:61]
	v_mfma_f32_16x16x32_bf16 v[54:57], v[134:137], v[196:199], v[54:57]
	v_mfma_f32_16x16x32_bf16 v[50:53], v[142:145], v[196:199], v[50:53]
	v_mfma_f32_16x16x32_bf16 v[38:41], v[134:137], v[204:207], v[38:41]
	v_mfma_f32_16x16x32_bf16 v[34:37], v[142:145], v[204:207], v[34:37]
	v_mfma_f32_16x16x32_bf16 v[22:25], v[134:137], v[212:215], v[22:25]
	v_mfma_f32_16x16x32_bf16 v[18:21], v[142:145], v[212:215], v[18:21]
	s_setprio 0
	s_setprio 1
	v_mfma_f32_16x16x32_bf16 v[46:49], v[146:149], v[162:165], v[46:49]
	v_mfma_f32_16x16x32_bf16 v[42:45], v[154:157], v[162:165], v[42:45]
	v_mfma_f32_16x16x32_bf16 v[30:33], v[146:149], v[192:195], v[30:33]
	v_mfma_f32_16x16x32_bf16 v[26:29], v[154:157], v[192:195], v[26:29]
	v_mfma_f32_16x16x32_bf16 v[14:17], v[146:149], v[200:203], v[14:17]
	v_mfma_f32_16x16x32_bf16 v[10:13], v[154:157], v[200:203], v[10:13]
	v_mfma_f32_16x16x32_bf16 v[6:9], v[146:149], v[208:211], v[6:9]
	v_mfma_f32_16x16x32_bf16 v[2:5], v[154:157], v[208:211], v[2:5]
	v_mfma_f32_16x16x32_bf16 v[46:49], v[150:153], v[184:187], v[46:49]
	v_mfma_f32_16x16x32_bf16 v[42:45], v[158:161], v[184:187], v[42:45]
	v_mfma_f32_16x16x32_bf16 v[30:33], v[150:153], v[196:199], v[30:33]
	v_mfma_f32_16x16x32_bf16 v[26:29], v[158:161], v[196:199], v[26:29]
	v_mfma_f32_16x16x32_bf16 v[14:17], v[150:153], v[204:207], v[14:17]
	v_mfma_f32_16x16x32_bf16 v[10:13], v[158:161], v[204:207], v[10:13]
	v_mfma_f32_16x16x32_bf16 v[6:9], v[150:153], v[212:215], v[6:9]
	v_mfma_f32_16x16x32_bf16 v[2:5], v[158:161], v[212:215], v[2:5]
	s_setprio 0
	s_barrier
	s_add_i32 s63, s63, 2
	s_add_u32 s30, s30, 0x100
	s_addc_u32 s31, s31, 0
	s_add_u32 s61, s61, 0x100
	s_addc_u32 s62, s62, 0
	s_cmpk_gt_u32 s63, 0x7d
	s_cbranch_scc0 .LBB0_1240
	s_and_b64 vcc, exec, s[10:11]
	s_cbranch_vccz .LBB0_1243
	s_barrier
